# stick-breaking cross-half exchange as an in-place v_permlane32_swap (3 instructions instead of 5 per exchange)
# speedup vs baseline: 1.0066x; 1.0066x over previous
; #define LAS __attribute__((address_space(3)))
; #define S_LOAD(key0) do { st0 = *(const u32x4*)(kg + (size_t)(key0) * 1024); st1 = *(const u32x4*)(kg + (size_t)((key0) + 64) * 1024); st2 = *(const u32x4*)(vg + (size_t)(key0) * 1024); st3 = *(const u32x4*)(vg + (size_t)((key0) + 64) * 1024); } while (0)
; __device__ __forceinline__ void sb_unit(const Frame& F, int b, int hd, int qi, int dry) {
;     ...
;         const bool meta = (it > jmax);
;         const int key0 = meta ? 0 : NMETA + 128 * (jmax - it);
;         if (it + 1 < nt) { const int nk = (it + 1 > jmax) ? 0 : NMETA + 128 * (jmax - it - 1); S_LOAD(nk); }
;         if (!dead && (meta || key0 < tqw + 31)) {
;             const LAS unsigned char* kb = lds + kra + (it & 1) * SK_BUF;
;             const LAS unsigned char* vb = lds + vra + (it & 1) * SV_BUF;
;     ...
;             float run = C;
;             if (!meta && key0 + 96 < tqw + 31) SB_HALF(96);
.LBB0_337:
	s_xor_b64 s[0:1], s[0:1], -1
	s_andn2_b64 vcc, exec, s[0:1]
	s_mov_b64 s[0:1], -1
	s_cbranch_vccnz .LBB0_350
	s_add_i32 s35, s33, 0xffffff10
	s_cmp_gt_u32 s36, s29
	s_cselect_b64 s[18:19], -1, 0
	s_and_b64 s[0:1], s[18:19], exec
	s_cselect_b32 s35, 0, s35
	s_cmp_lt_i32 s35, s30
	s_cselect_b64 s[0:1], -1, 0
	s_or_b64 s[0:1], s[18:19], s[0:1]
	s_andn2_b64 vcc, exec, s[0:1]
	s_mov_b64 s[0:1], 0
	s_cbranch_vccnz .LBB0_350
	s_and_b32 s0, s36, 1
	s_mul_i32 s36, s0, 0x4800
	s_mul_i32 s37, s0, 0x6000
	s_or_b32 s0, s35, 0x41
	s_cmp_ge_i32 s0, s26
	s_cselect_b64 s[0:1], -1, 0
	s_or_b64 s[0:1], s[18:19], s[0:1]
	s_and_b64 vcc, exec, s[0:1]
	v_add_u32_e32 v129, s36, v118
	v_or_b32_e32 v127, s35, v205
	v_add_u32_e32 v128, s37, v119
	s_cbranch_vccnz .LBB0_341
	s_add_i32 s61, s35, 128
	s_cmp_le_i32 s61, s26
	s_cbranch_scc1 .Lsbq_nomask_6
	ds_read_b128 v[32:35], v129 offset:13824
	ds_read_b128 v[214:217], v129 offset:13856
	ds_read_b128 v[210:213], v129 offset:13888
	ds_read_b128 v[130:133], v129 offset:13920
	ds_read_b64_tr_b16 v[92:93], v128 offset:55296
	ds_read_b64_tr_b16 v[94:95], v128 offset:56832
	ds_read_b64_tr_b16 v[90:91], v128 offset:56896
	ds_read_b64_tr_b16 v[88:89], v128 offset:55360
	ds_read_b64_tr_b16 v[84:85], v128 offset:58368
	ds_read_b64_tr_b16 v[86:87], v128 offset:59904
	ds_read_b64_tr_b16 v[82:83], v128 offset:59968
	ds_read_b64_tr_b16 v[80:81], v128 offset:58432
	v_exp_f32_e32 v135, v125
	v_sub_u32_e32 v134, v115, v127
	v_cmp_lt_i32_e32 vcc, 0, v134
	s_waitcnt lgkmcnt(11)
	v_mfma_f32_32x32x16_bf16 v[32:47], v[32:35], v[48:51], 0
	v_cmp_lt_i32_e64 s[0:1], 27, v134
	s_waitcnt lgkmcnt(10)
	v_mfma_f32_32x32x16_bf16 v[32:47], v[214:217], v[52:55], v[32:47]
	s_waitcnt lgkmcnt(9)
	v_mfma_f32_32x32x16_bf16 v[32:47], v[210:213], v[56:59], v[32:47]
	s_waitcnt lgkmcnt(8)
	v_mfma_f32_32x32x16_bf16 v[32:47], v[130:133], v[60:63], v[32:47]
	s_nop 11
	v_min_f32_e64 v32, -v32, s60
	v_min_f32_e64 v33, -v33, s60
	v_exp_f32_e32 v32, v32
	v_min_f32_e64 v34, -v34, s60
	v_exp_f32_e32 v33, v33
	v_exp_f32_e32 v34, v34
	v_min_f32_e64 v35, -v35, s60
	v_exp_f32_e32 v130, v35
	v_add_f32_e32 v35, 1.0, v32
	v_add_f32_e32 v131, 1.0, v33
	v_rcp_f32_e32 v35, v35
	v_add_f32_e32 v132, 1.0, v34
	v_rcp_f32_e32 v131, v131
	v_min_f32_e64 v36, -v36, s60
	v_rcp_f32_e32 v132, v132
	v_exp_f32_e32 v36, v36
	v_add_f32_e32 v133, 1.0, v130
	v_rcp_f32_e32 v136, v133
	v_mul_f32_e32 v32, v32, v35
	v_mul_f32_e32 v133, v135, v35
	v_mul_f32_e32 v33, v33, v131
	v_mul_f32_e32 v137, v135, v131
	v_cndmask_b32_e32 v35, 1.0, v32, vcc
	v_cndmask_b32_e32 v138, 0, v133, vcc
	v_cmp_lt_i32_e32 vcc, 1, v134
	v_mul_f32_e32 v34, v34, v132
	v_mul_f32_e32 v32, v135, v132
	v_cndmask_b32_e32 v131, 1.0, v33, vcc
	v_cndmask_b32_e32 v137, 0, v137, vcc
	v_cmp_lt_i32_e32 vcc, 2, v134
	v_min_f32_e64 v39, -v39, s60
	v_cndmask_b32_e32 v33, 1.0, v34, vcc
	v_add_f32_e32 v34, 1.0, v36
	v_rcp_f32_e32 v34, v34
	v_cndmask_b32_e32 v139, 0, v32, vcc
	v_mul_f32_e32 v32, v130, v136
	v_cmp_lt_i32_e32 vcc, 3, v134
	v_exp_f32_e32 v39, v39
	v_cndmask_b32_e32 v133, 1.0, v32, vcc
	v_mul_f32_e32 v32, v135, v136
	v_cndmask_b32_e32 v136, 0, v32, vcc
	v_mul_f32_e32 v32, v36, v34
	v_min_f32_e64 v36, -v37, s60
	v_exp_f32_e32 v36, v36
	v_cmp_lt_i32_e32 vcc, 8, v134
	v_mul_f32_e32 v34, v135, v34
	v_cndmask_b32_e32 v140, 0, v34, vcc
	v_add_f32_e32 v34, 1.0, v36
	v_rcp_f32_e32 v34, v34
	v_min_f32_e64 v37, -v38, s60
	v_exp_f32_e32 v37, v37
	v_cndmask_b32_e32 v32, 1.0, v32, vcc
	v_mul_f32_e32 v36, v36, v34
	v_cmp_lt_i32_e32 vcc, 9, v134
	v_mul_f32_e32 v34, v135, v34
	v_min_f32_e64 v42, -v42, s60
	v_cndmask_b32_e32 v38, 1.0, v36, vcc
	v_add_f32_e32 v36, 1.0, v37
	v_rcp_f32_e32 v36, v36
	v_cndmask_b32_e32 v141, 0, v34, vcc
	v_cmp_lt_i32_e32 vcc, 10, v134
	v_exp_f32_e32 v42, v42
	v_mul_f32_e32 v34, v37, v36
	v_add_f32_e32 v37, 1.0, v39
	v_rcp_f32_e32 v37, v37
	v_cndmask_b32_e32 v142, 1.0, v34, vcc
	v_mul_f32_e32 v34, v135, v36
	v_cndmask_b32_e32 v143, 0, v34, vcc
	v_mul_f32_e32 v34, v39, v37
	v_cmp_lt_i32_e32 vcc, 11, v134
	v_min_f32_e64 v36, -v40, s60
	v_exp_f32_e32 v36, v36
	v_cndmask_b32_e32 v39, 1.0, v34, vcc
	v_mul_f32_e32 v34, v135, v37
	v_min_f32_e64 v37, -v41, s60
	v_exp_f32_e32 v37, v37
	v_cndmask_b32_e32 v40, 0, v34, vcc
	v_add_f32_e32 v34, 1.0, v36
	v_rcp_f32_e32 v34, v34
	v_add_f32_e32 v41, 1.0, v37
	v_rcp_f32_e32 v41, v41
	v_cmp_lt_i32_e32 vcc, 16, v134
	v_mul_f32_e32 v36, v36, v34
	v_mul_f32_e32 v34, v135, v34
	v_cndmask_b32_e32 v144, 0, v34, vcc
	v_mul_f32_e32 v34, v37, v41
	v_add_f32_e32 v37, 1.0, v42
	v_rcp_f32_e32 v37, v37
	v_cndmask_b32_e32 v36, 1.0, v36, vcc
	v_cmp_lt_i32_e32 vcc, 17, v134
	v_min_f32_e64 v45, -v45, s60
	v_cndmask_b32_e32 v145, 1.0, v34, vcc
	v_mul_f32_e32 v34, v135, v41
	v_cndmask_b32_e32 v41, 0, v34, vcc
	v_mul_f32_e32 v34, v42, v37
	v_cmp_lt_i32_e32 vcc, 18, v134
	v_min_f32_e64 v42, -v43, s60
	v_exp_f32_e32 v42, v42
	v_cndmask_b32_e32 v43, 1.0, v34, vcc
	v_mul_f32_e32 v34, v135, v37
	v_min_f32_e64 v37, -v44, s60
	v_exp_f32_e32 v37, v37
	v_cndmask_b32_e32 v146, 0, v34, vcc
	v_add_f32_e32 v34, 1.0, v42
	v_rcp_f32_e32 v34, v34
	v_add_f32_e32 v44, 1.0, v37
	v_rcp_f32_e32 v44, v44
	v_exp_f32_e32 v45, v45
	v_min_f32_e64 v46, -v46, s60
	v_min_f32_e64 v47, -v47, s60
	v_exp_f32_e32 v46, v46
	v_exp_f32_e32 v47, v47
	v_mul_f32_e32 v42, v42, v34
	v_cmp_lt_i32_e32 vcc, 19, v134
	v_mul_f32_e32 v34, v135, v34
	v_add_f32_e32 v130, 1.0, v46
	v_cndmask_b32_e32 v147, 0, v34, vcc
	v_mul_f32_e32 v34, v37, v44
	v_add_f32_e32 v37, 1.0, v45
	v_rcp_f32_e32 v37, v37
	v_add_f32_e32 v132, 1.0, v47
	v_rcp_f32_e32 v130, v130
	v_rcp_f32_e32 v132, v132
	v_cndmask_b32_e32 v42, 1.0, v42, vcc
	v_cmp_lt_i32_e32 vcc, 24, v134
	v_mul_f32_e32 v44, v135, v44
	v_mul_f32_e32 v45, v45, v37
	v_cndmask_b32_e32 v34, 1.0, v34, vcc
	v_cndmask_b32_e32 v44, 0, v44, vcc
	v_cmp_lt_i32_e32 vcc, 25, v134
	v_mul_f32_e32 v37, v135, v37
	v_mul_f32_e32 v46, v46, v130
	v_cndmask_b32_e32 v45, 1.0, v45, vcc
	v_cndmask_b32_e32 v37, 0, v37, vcc
	v_cmp_lt_i32_e32 vcc, 26, v134
	v_mul_f32_e32 v47, v47, v132
	v_cndmask_b32_e64 v47, 1.0, v47, s[0:1]
	v_cndmask_b32_e32 v46, 1.0, v46, vcc
	v_mul_f32_e32 v34, v34, v45
	v_mul_f32_e32 v134, v46, v47
	v_mul_f32_e32 v134, v34, v134
	v_mov_b32_e32 v148, v134
	s_nop 1
	v_permlane32_swap_b32_e32 v134, v148
	v_mul_f32_e32 v34, v135, v130
	v_cndmask_b32_e32 v149, 0, v34, vcc
	v_mul_f32_e32 v34, v135, v132
	v_cndmask_b32_e64 v34, 0, v34, s[0:1]
	s_waitcnt lgkmcnt(0)
	v_cndmask_b32_e64 v130, 1.0, v148, s[2:3]
	v_mul_f32_e32 v135, v34, v130
	v_mul_f32_e32 v34, v36, v145
	v_mul_f32_e32 v36, v43, v42
	v_mul_f32_e32 v36, v34, v36
	v_mul_f32_e32 v32, v32, v38
	v_mul_f32_e32 v34, v142, v39
	v_mov_b32_e32 v150, v36
	s_nop 1
	v_permlane32_swap_b32_e32 v36, v150
	v_mul_f32_e32 v34, v32, v34
	v_mul_f32_e32 v47, v47, v130
	v_mov_b32_e32 v130, v34
	s_nop 1
	v_permlane32_swap_b32_e32 v34, v130
	v_mul_f32_e32 v46, v46, v47
	v_mul_f32_e32 v32, v134, v148
	s_waitcnt lgkmcnt(1)
	v_mul_f32_e32 v132, v36, v150
	v_mul_f32_e32 v45, v45, v46
	v_mul_f32_e32 v46, v37, v46
	s_waitcnt lgkmcnt(0)
	v_cndmask_b32_e64 v134, 1.0, v130, s[2:3]
	v_pk_mul_f32 v[36:37], v[32:33], v[132:133]
	v_pk_mul_f32 v[34:35], v[34:35], v[130:131]
	v_mul_f32_e32 v132, v36, v134
	v_mul_f32_e32 v134, v39, v132
	v_mul_f32_e32 v142, v142, v134
	v_mul_f32_e32 v148, v38, v142
	v_pk_mul_f32 v[38:39], v[34:35], v[36:37]
	v_mov_b32_e32 v130, v39
	s_nop 1
	v_permlane32_swap_b32_e32 v39, v130
	v_mul_f32_e32 v37, v40, v132
	v_mul_f32_e32 v40, v143, v134
	v_mul_f32_e32 v36, v141, v142
	v_mul_f32_e32 v132, v140, v148
	s_waitcnt lgkmcnt(0)
	v_cndmask_b32_e64 v34, 1.0, v130, s[2:3]
	v_mul_f32_e32 v34, v38, v34
	v_mul_f32_e32 v35, v133, v34
	v_mul_f32_e32 v33, v33, v35
	v_mul_f32_e32 v131, v131, v33
	v_mul_f32_e32 v133, v136, v34
	v_mul_f32_e32 v35, v139, v35
	v_mul_f32_e32 v33, v137, v33
	v_mul_f32_e32 v34, v138, v131
	v_cvt_pk_bf16_f32 v34, v34, v33
	v_cvt_pk_bf16_f32 v35, v35, v133
	v_cvt_pk_bf16_f32 v36, v132, v36
	v_cvt_pk_bf16_f32 v37, v40, v37
	v_cndmask_b32_e64 v33, 1.0, v150, s[2:3]
	v_mul_f32_e32 v32, v32, v33
	v_mfma_f32_32x32x16_bf16 v[16:31], v[92:95], v[34:37], v[16:31]
	v_mul_f32_e32 v33, v42, v32
	v_mul_f32_e32 v42, v43, v33
	v_mul_f32_e32 v43, v145, v42
	v_mul_f32_e32 v47, v149, v47
	v_mul_f32_e32 v40, v44, v45
	v_mul_f32_e32 v44, v147, v32
	v_mul_f32_e32 v33, v146, v33
	v_mfma_f32_32x32x16_bf16 v[0:15], v[88:91], v[34:37], v[0:15]
	v_mul_f32_e32 v32, v41, v42
	v_mul_f32_e32 v34, v144, v43
	v_cvt_pk_bf16_f32 v32, v34, v32
	v_cvt_pk_bf16_f32 v33, v33, v44
	v_cvt_pk_bf16_f32 v34, v40, v46
	v_cvt_pk_bf16_f32 v35, v47, v135
	v_mul_f32_e32 v36, v39, v130
	v_mul_f32_e32 v36, v38, v36
	v_mfma_f32_32x32x16_bf16 v[16:31], v[84:87], v[32:35], v[16:31]
	v_log_f32_e32 v36, v36
	s_nop 0
	v_add_f32_e32 v125, v125, v36
	v_mfma_f32_32x32x16_bf16 v[0:15], v[80:83], v[32:35], v[0:15]
	s_branch .LBB0_341
.Lsbq_nomask_6:
	ds_read_b128 v[32:35], v129 offset:13824
	ds_read_b128 v[214:217], v129 offset:13856
	ds_read_b128 v[210:213], v129 offset:13888
	ds_read_b128 v[130:133], v129 offset:13920
	ds_read_b64_tr_b16 v[92:93], v128 offset:55296
	ds_read_b64_tr_b16 v[94:95], v128 offset:56832
	ds_read_b64_tr_b16 v[90:91], v128 offset:56896
	ds_read_b64_tr_b16 v[88:89], v128 offset:55360
	ds_read_b64_tr_b16 v[84:85], v128 offset:58368
	ds_read_b64_tr_b16 v[86:87], v128 offset:59904
	ds_read_b64_tr_b16 v[82:83], v128 offset:59968
	ds_read_b64_tr_b16 v[80:81], v128 offset:58432
	v_exp_f32_e32 v135, v125
	s_waitcnt lgkmcnt(11)
	v_mfma_f32_32x32x16_bf16 v[32:47], v[32:35], v[48:51], 0
	s_waitcnt lgkmcnt(10)
	v_mfma_f32_32x32x16_bf16 v[32:47], v[214:217], v[52:55], v[32:47]
	s_waitcnt lgkmcnt(9)
	v_mfma_f32_32x32x16_bf16 v[32:47], v[210:213], v[56:59], v[32:47]
	s_waitcnt lgkmcnt(8)
	v_mfma_f32_32x32x16_bf16 v[32:47], v[130:133], v[60:63], v[32:47]
	s_nop 11
	v_min_f32_e64 v32, -v32, s60
	v_min_f32_e64 v33, -v33, s60
	v_exp_f32_e32 v32, v32
	v_min_f32_e64 v34, -v34, s60
	v_exp_f32_e32 v33, v33
	v_exp_f32_e32 v34, v34
	v_min_f32_e64 v35, -v35, s60
	v_exp_f32_e32 v130, v35
	v_add_f32_e32 v35, 1.0, v32
	v_add_f32_e32 v131, 1.0, v33
	v_rcp_f32_e32 v35, v35
	v_add_f32_e32 v132, 1.0, v34
	v_rcp_f32_e32 v131, v131
	v_min_f32_e64 v36, -v36, s60
	v_rcp_f32_e32 v132, v132
	v_exp_f32_e32 v36, v36
	v_add_f32_e32 v133, 1.0, v130
	v_rcp_f32_e32 v136, v133
	v_mul_f32_e32 v32, v32, v35
	v_mul_f32_e32 v138, v135, v35
	v_mul_f32_e32 v33, v33, v131
	v_mul_f32_e32 v137, v135, v131
	v_mov_b32_e32 v35, v32
	v_mul_f32_e32 v34, v34, v132
	v_mul_f32_e32 v139, v135, v132
	v_mov_b32_e32 v131, v33
	v_min_f32_e64 v39, -v39, s60
	v_mov_b32_e32 v33, v34
	v_add_f32_e32 v34, 1.0, v36
	v_rcp_f32_e32 v34, v34
	v_mul_f32_e32 v133, v130, v136
	v_exp_f32_e32 v39, v39
	v_mul_f32_e32 v136, v135, v136
	v_mul_f32_e32 v32, v36, v34
	v_min_f32_e64 v36, -v37, s60
	v_exp_f32_e32 v36, v36
	v_mul_f32_e32 v140, v135, v34
	v_add_f32_e32 v34, 1.0, v36
	v_rcp_f32_e32 v34, v34
	v_min_f32_e64 v37, -v38, s60
	v_exp_f32_e32 v37, v37
	v_mul_f32_e32 v38, v36, v34
	v_mul_f32_e32 v141, v135, v34
	v_min_f32_e64 v42, -v42, s60
	v_add_f32_e32 v36, 1.0, v37
	v_rcp_f32_e32 v36, v36
	v_exp_f32_e32 v42, v42
	v_mul_f32_e32 v142, v37, v36
	v_add_f32_e32 v37, 1.0, v39
	v_rcp_f32_e32 v37, v37
	v_mul_f32_e32 v143, v135, v36
	v_mul_f32_e32 v39, v39, v37
	v_min_f32_e64 v36, -v40, s60
	v_exp_f32_e32 v36, v36
	v_mul_f32_e32 v40, v135, v37
	v_min_f32_e64 v37, -v41, s60
	v_exp_f32_e32 v37, v37
	v_add_f32_e32 v34, 1.0, v36
	v_rcp_f32_e32 v34, v34
	v_add_f32_e32 v41, 1.0, v37
	v_rcp_f32_e32 v41, v41
	v_mul_f32_e32 v36, v36, v34
	v_mul_f32_e32 v144, v135, v34
	v_mul_f32_e32 v145, v37, v41
	v_add_f32_e32 v37, 1.0, v42
	v_rcp_f32_e32 v37, v37
	v_min_f32_e64 v45, -v45, s60
	v_mul_f32_e32 v41, v135, v41
	v_mul_f32_e32 v34, v42, v37
	v_min_f32_e64 v42, -v43, s60
	v_exp_f32_e32 v42, v42
	v_mov_b32_e32 v43, v34
	v_mul_f32_e32 v146, v135, v37
	v_min_f32_e64 v37, -v44, s60
	v_exp_f32_e32 v37, v37
	v_add_f32_e32 v34, 1.0, v42
	v_rcp_f32_e32 v34, v34
	v_add_f32_e32 v44, 1.0, v37
	v_rcp_f32_e32 v44, v44
	v_exp_f32_e32 v45, v45
	v_min_f32_e64 v46, -v46, s60
	v_min_f32_e64 v47, -v47, s60
	v_exp_f32_e32 v46, v46
	v_exp_f32_e32 v47, v47
	v_mul_f32_e32 v42, v42, v34
	v_mul_f32_e32 v147, v135, v34
	v_add_f32_e32 v130, 1.0, v46
	v_mul_f32_e32 v34, v37, v44
	v_add_f32_e32 v37, 1.0, v45
	v_rcp_f32_e32 v37, v37
	v_add_f32_e32 v132, 1.0, v47
	v_rcp_f32_e32 v130, v130
	v_rcp_f32_e32 v132, v132
	v_mul_f32_e32 v44, v135, v44
	v_mul_f32_e32 v45, v45, v37
	v_mul_f32_e32 v37, v135, v37
	v_mul_f32_e32 v46, v46, v130
	v_mul_f32_e32 v47, v47, v132
	v_mul_f32_e32 v34, v34, v45
	v_mul_f32_e32 v134, v46, v47
	v_mul_f32_e32 v134, v34, v134
	v_mov_b32_e32 v148, v134
	s_nop 1
	v_permlane32_swap_b32_e32 v134, v148
	v_mul_f32_e32 v149, v135, v130
	v_mul_f32_e32 v34, v135, v132
	s_waitcnt lgkmcnt(0)
; __device__ __forceinline__ void sb_unit(const Frame& F, int b, int hd, int qi, int dry) {
;     ...
;             float run = C;
;             if (!meta && key0 + 96 < tqw + 31) SB_HALF(96);
;             if (!meta && key0 + 64 < tqw + 31 && __any(run >= SB_DEAD)) SB_HALF(64);
	v_cndmask_b32_e64 v130, 1.0, v148, s[2:3]
	v_mul_f32_e32 v135, v34, v130
	v_mul_f32_e32 v34, v36, v145
	v_mul_f32_e32 v36, v43, v42
	v_mul_f32_e32 v36, v34, v36
	v_mul_f32_e32 v32, v32, v38
	v_mul_f32_e32 v34, v142, v39
	v_mov_b32_e32 v150, v36
	s_nop 1
	v_permlane32_swap_b32_e32 v36, v150
	v_mul_f32_e32 v34, v32, v34
	v_mul_f32_e32 v47, v47, v130
	v_mov_b32_e32 v130, v34
	s_nop 1
	v_permlane32_swap_b32_e32 v34, v130
	v_mul_f32_e32 v46, v46, v47
	v_mul_f32_e32 v32, v134, v148
	s_waitcnt lgkmcnt(1)
	v_mul_f32_e32 v132, v36, v150
	v_mul_f32_e32 v45, v45, v46
	v_mul_f32_e32 v46, v37, v46
	s_waitcnt lgkmcnt(0)
	v_cndmask_b32_e64 v134, 1.0, v130, s[2:3]
	v_pk_mul_f32 v[36:37], v[32:33], v[132:133]
	v_pk_mul_f32 v[34:35], v[34:35], v[130:131]
	v_mul_f32_e32 v132, v36, v134
	v_mul_f32_e32 v134, v39, v132
	v_mul_f32_e32 v142, v142, v134
	v_mul_f32_e32 v148, v38, v142
	v_pk_mul_f32 v[38:39], v[34:35], v[36:37]
	v_mov_b32_e32 v130, v39
	s_nop 1
	v_permlane32_swap_b32_e32 v39, v130
	v_mul_f32_e32 v37, v40, v132
	v_mul_f32_e32 v40, v143, v134
	v_mul_f32_e32 v36, v141, v142
	v_mul_f32_e32 v132, v140, v148
	s_waitcnt lgkmcnt(0)
	v_cndmask_b32_e64 v34, 1.0, v130, s[2:3]
	v_mul_f32_e32 v34, v38, v34
	v_mul_f32_e32 v35, v133, v34
	v_mul_f32_e32 v33, v33, v35
	v_mul_f32_e32 v131, v131, v33
	v_mul_f32_e32 v133, v136, v34
	v_mul_f32_e32 v35, v139, v35
	v_mul_f32_e32 v33, v137, v33
	v_mul_f32_e32 v34, v138, v131
	v_cvt_pk_bf16_f32 v34, v34, v33
	v_cvt_pk_bf16_f32 v35, v35, v133
	v_cvt_pk_bf16_f32 v36, v132, v36
	v_cvt_pk_bf16_f32 v37, v40, v37
	v_cndmask_b32_e64 v33, 1.0, v150, s[2:3]
	v_mul_f32_e32 v32, v32, v33
	v_mfma_f32_32x32x16_bf16 v[16:31], v[92:95], v[34:37], v[16:31]
	v_mul_f32_e32 v33, v42, v32
	v_mul_f32_e32 v42, v43, v33
	v_mul_f32_e32 v43, v145, v42
	v_mul_f32_e32 v47, v149, v47
	v_mul_f32_e32 v40, v44, v45
	v_mul_f32_e32 v44, v147, v32
	v_mul_f32_e32 v33, v146, v33
	v_mfma_f32_32x32x16_bf16 v[0:15], v[88:91], v[34:37], v[0:15]
	v_mul_f32_e32 v32, v41, v42
	v_mul_f32_e32 v34, v144, v43
	v_cvt_pk_bf16_f32 v32, v34, v32
	v_cvt_pk_bf16_f32 v33, v33, v44
	v_cvt_pk_bf16_f32 v34, v40, v46
	v_cvt_pk_bf16_f32 v35, v47, v135
	v_mul_f32_e32 v36, v39, v130
	v_mul_f32_e32 v36, v38, v36
	v_mfma_f32_32x32x16_bf16 v[16:31], v[84:87], v[32:35], v[16:31]
	v_log_f32_e32 v36, v36
	s_nop 0
	v_add_f32_e32 v125, v125, v36
	v_mfma_f32_32x32x16_bf16 v[0:15], v[80:83], v[32:35], v[0:15]
.LBB0_341:
	s_or_b32 s0, s35, 33
	s_cmp_ge_i32 s0, s26
	s_cselect_b64 s[0:1], -1, 0
	s_or_b64 s[0:1], s[18:19], s[0:1]
	s_and_b64 vcc, exec, s[0:1]
	s_cbranch_vccnz .LBB0_344
	v_cmp_le_f32_e32 vcc, s22, v125
	s_cbranch_vccz .LBB0_344
	s_add_i32 s61, s35, 96
	s_cmp_le_i32 s61, s26
	s_cbranch_scc1 .Lsbq_nomask_5
	ds_read_b128 v[32:35], v129 offset:9216
	ds_read_b128 v[214:217], v129 offset:9248
	ds_read_b128 v[210:213], v129 offset:9280
	ds_read_b128 v[130:133], v129 offset:9312
	ds_read_b64_tr_b16 v[92:93], v128 offset:49152
	ds_read_b64_tr_b16 v[94:95], v128 offset:50688
	ds_read_b64_tr_b16 v[90:91], v128 offset:50752
	ds_read_b64_tr_b16 v[88:89], v128 offset:49216
	ds_read_b64_tr_b16 v[84:85], v128 offset:52224
	ds_read_b64_tr_b16 v[86:87], v128 offset:53760
	ds_read_b64_tr_b16 v[82:83], v128 offset:53824
	ds_read_b64_tr_b16 v[80:81], v128 offset:52288
	v_exp_f32_e32 v135, v125
	v_sub_u32_e32 v134, v124, v127
	v_cmp_lt_i32_e32 vcc, 0, v134
	s_waitcnt lgkmcnt(11)
	v_mfma_f32_32x32x16_bf16 v[32:47], v[32:35], v[48:51], 0
	v_cmp_lt_i32_e64 s[0:1], 27, v134
	s_waitcnt lgkmcnt(10)
	v_mfma_f32_32x32x16_bf16 v[32:47], v[214:217], v[52:55], v[32:47]
	s_waitcnt lgkmcnt(9)
	v_mfma_f32_32x32x16_bf16 v[32:47], v[210:213], v[56:59], v[32:47]
	s_waitcnt lgkmcnt(8)
	v_mfma_f32_32x32x16_bf16 v[32:47], v[130:133], v[60:63], v[32:47]
	s_nop 11
	v_min_f32_e64 v32, -v32, s60
	v_min_f32_e64 v33, -v33, s60
	v_exp_f32_e32 v32, v32
	v_min_f32_e64 v34, -v34, s60
	v_exp_f32_e32 v33, v33
	v_exp_f32_e32 v34, v34
	v_min_f32_e64 v35, -v35, s60
	v_exp_f32_e32 v130, v35
	v_add_f32_e32 v35, 1.0, v32
	v_add_f32_e32 v131, 1.0, v33
	v_rcp_f32_e32 v35, v35
	v_add_f32_e32 v132, 1.0, v34
	v_rcp_f32_e32 v131, v131
	v_min_f32_e64 v36, -v36, s60
	v_rcp_f32_e32 v132, v132
	v_exp_f32_e32 v36, v36
	v_add_f32_e32 v133, 1.0, v130
	v_rcp_f32_e32 v136, v133
	v_mul_f32_e32 v32, v32, v35
	v_mul_f32_e32 v133, v135, v35
	v_mul_f32_e32 v33, v33, v131
	v_mul_f32_e32 v137, v135, v131
	v_cndmask_b32_e32 v35, 1.0, v32, vcc
	v_cndmask_b32_e32 v138, 0, v133, vcc
	v_cmp_lt_i32_e32 vcc, 1, v134
	v_mul_f32_e32 v34, v34, v132
	v_mul_f32_e32 v32, v135, v132
	v_cndmask_b32_e32 v131, 1.0, v33, vcc
	v_cndmask_b32_e32 v137, 0, v137, vcc
	v_cmp_lt_i32_e32 vcc, 2, v134
	v_min_f32_e64 v39, -v39, s60
	v_cndmask_b32_e32 v33, 1.0, v34, vcc
	v_add_f32_e32 v34, 1.0, v36
	v_rcp_f32_e32 v34, v34
	v_cndmask_b32_e32 v139, 0, v32, vcc
	v_mul_f32_e32 v32, v130, v136
	v_cmp_lt_i32_e32 vcc, 3, v134
	v_exp_f32_e32 v39, v39
	v_cndmask_b32_e32 v133, 1.0, v32, vcc
	v_mul_f32_e32 v32, v135, v136
	v_cndmask_b32_e32 v136, 0, v32, vcc
	v_mul_f32_e32 v32, v36, v34
	v_min_f32_e64 v36, -v37, s60
	v_exp_f32_e32 v36, v36
	v_cmp_lt_i32_e32 vcc, 8, v134
	v_mul_f32_e32 v34, v135, v34
	v_cndmask_b32_e32 v140, 0, v34, vcc
	v_add_f32_e32 v34, 1.0, v36
	v_rcp_f32_e32 v34, v34
	v_min_f32_e64 v37, -v38, s60
	v_exp_f32_e32 v37, v37
	v_cndmask_b32_e32 v32, 1.0, v32, vcc
	v_mul_f32_e32 v36, v36, v34
	v_cmp_lt_i32_e32 vcc, 9, v134
	v_mul_f32_e32 v34, v135, v34
	v_min_f32_e64 v42, -v42, s60
	v_cndmask_b32_e32 v38, 1.0, v36, vcc
	v_add_f32_e32 v36, 1.0, v37
	v_rcp_f32_e32 v36, v36
	v_cndmask_b32_e32 v141, 0, v34, vcc
	v_cmp_lt_i32_e32 vcc, 10, v134
	v_exp_f32_e32 v42, v42
	v_mul_f32_e32 v34, v37, v36
	v_add_f32_e32 v37, 1.0, v39
	v_rcp_f32_e32 v37, v37
	v_cndmask_b32_e32 v142, 1.0, v34, vcc
	v_mul_f32_e32 v34, v135, v36
	v_cndmask_b32_e32 v143, 0, v34, vcc
	v_mul_f32_e32 v34, v39, v37
	v_cmp_lt_i32_e32 vcc, 11, v134
	v_min_f32_e64 v36, -v40, s60
	v_exp_f32_e32 v36, v36
	v_cndmask_b32_e32 v39, 1.0, v34, vcc
	v_mul_f32_e32 v34, v135, v37
	v_min_f32_e64 v37, -v41, s60
	v_exp_f32_e32 v37, v37
	v_cndmask_b32_e32 v40, 0, v34, vcc
	v_add_f32_e32 v34, 1.0, v36
	v_rcp_f32_e32 v34, v34
	v_add_f32_e32 v41, 1.0, v37
	v_rcp_f32_e32 v41, v41
	v_cmp_lt_i32_e32 vcc, 16, v134
	v_mul_f32_e32 v36, v36, v34
	v_mul_f32_e32 v34, v135, v34
	v_cndmask_b32_e32 v144, 0, v34, vcc
	v_mul_f32_e32 v34, v37, v41
	v_add_f32_e32 v37, 1.0, v42
	v_rcp_f32_e32 v37, v37
	v_cndmask_b32_e32 v36, 1.0, v36, vcc
	v_cmp_lt_i32_e32 vcc, 17, v134
	v_min_f32_e64 v45, -v45, s60
	v_cndmask_b32_e32 v145, 1.0, v34, vcc
	v_mul_f32_e32 v34, v135, v41
	v_cndmask_b32_e32 v41, 0, v34, vcc
	v_mul_f32_e32 v34, v42, v37
	v_cmp_lt_i32_e32 vcc, 18, v134
	v_min_f32_e64 v42, -v43, s60
	v_exp_f32_e32 v42, v42
	v_cndmask_b32_e32 v43, 1.0, v34, vcc
	v_mul_f32_e32 v34, v135, v37
	v_min_f32_e64 v37, -v44, s60
	v_exp_f32_e32 v37, v37
	v_cndmask_b32_e32 v146, 0, v34, vcc
	v_add_f32_e32 v34, 1.0, v42
	v_rcp_f32_e32 v34, v34
	v_add_f32_e32 v44, 1.0, v37
	v_rcp_f32_e32 v44, v44
	v_exp_f32_e32 v45, v45
	v_min_f32_e64 v46, -v46, s60
	v_min_f32_e64 v47, -v47, s60
	v_exp_f32_e32 v46, v46
	v_exp_f32_e32 v47, v47
	v_mul_f32_e32 v42, v42, v34
	v_cmp_lt_i32_e32 vcc, 19, v134
	v_mul_f32_e32 v34, v135, v34
	v_add_f32_e32 v130, 1.0, v46
	v_cndmask_b32_e32 v147, 0, v34, vcc
	v_mul_f32_e32 v34, v37, v44
	v_add_f32_e32 v37, 1.0, v45
	v_rcp_f32_e32 v37, v37
	v_add_f32_e32 v132, 1.0, v47
	v_rcp_f32_e32 v130, v130
	v_rcp_f32_e32 v132, v132
	v_cndmask_b32_e32 v42, 1.0, v42, vcc
	v_cmp_lt_i32_e32 vcc, 24, v134
	v_mul_f32_e32 v44, v135, v44
	v_mul_f32_e32 v45, v45, v37
	v_cndmask_b32_e32 v34, 1.0, v34, vcc
	v_cndmask_b32_e32 v44, 0, v44, vcc
	v_cmp_lt_i32_e32 vcc, 25, v134
	v_mul_f32_e32 v37, v135, v37
	v_mul_f32_e32 v46, v46, v130
	v_cndmask_b32_e32 v45, 1.0, v45, vcc
	v_cndmask_b32_e32 v37, 0, v37, vcc
	v_cmp_lt_i32_e32 vcc, 26, v134
	v_mul_f32_e32 v47, v47, v132
	v_cndmask_b32_e64 v47, 1.0, v47, s[0:1]
	v_cndmask_b32_e32 v46, 1.0, v46, vcc
	v_mul_f32_e32 v34, v34, v45
	v_mul_f32_e32 v134, v46, v47
	v_mul_f32_e32 v134, v34, v134
	v_mov_b32_e32 v148, v134
	s_nop 1
	v_permlane32_swap_b32_e32 v134, v148
	v_mul_f32_e32 v34, v135, v130
	v_cndmask_b32_e32 v149, 0, v34, vcc
	v_mul_f32_e32 v34, v135, v132
	v_cndmask_b32_e64 v34, 0, v34, s[0:1]
	s_waitcnt lgkmcnt(0)
	v_cndmask_b32_e64 v130, 1.0, v148, s[2:3]
	v_mul_f32_e32 v135, v34, v130
	v_mul_f32_e32 v34, v36, v145
	v_mul_f32_e32 v36, v43, v42
	v_mul_f32_e32 v36, v34, v36
	v_mul_f32_e32 v32, v32, v38
	v_mul_f32_e32 v34, v142, v39
	v_mov_b32_e32 v150, v36
	s_nop 1
	v_permlane32_swap_b32_e32 v36, v150
	v_mul_f32_e32 v34, v32, v34
	v_mul_f32_e32 v47, v47, v130
	v_mov_b32_e32 v130, v34
	s_nop 1
	v_permlane32_swap_b32_e32 v34, v130
	v_mul_f32_e32 v46, v46, v47
	v_mul_f32_e32 v32, v134, v148
	s_waitcnt lgkmcnt(1)
	v_mul_f32_e32 v132, v36, v150
	v_mul_f32_e32 v45, v45, v46
	v_mul_f32_e32 v46, v37, v46
	s_waitcnt lgkmcnt(0)
	v_cndmask_b32_e64 v134, 1.0, v130, s[2:3]
	v_pk_mul_f32 v[36:37], v[32:33], v[132:133]
	v_pk_mul_f32 v[34:35], v[34:35], v[130:131]
	v_mul_f32_e32 v132, v36, v134
	v_mul_f32_e32 v134, v39, v132
	v_mul_f32_e32 v142, v142, v134
	v_mul_f32_e32 v148, v38, v142
	v_pk_mul_f32 v[38:39], v[34:35], v[36:37]
	v_mov_b32_e32 v130, v39
	s_nop 1
	v_permlane32_swap_b32_e32 v39, v130
	v_mul_f32_e32 v37, v40, v132
	v_mul_f32_e32 v40, v143, v134
	v_mul_f32_e32 v36, v141, v142
	v_mul_f32_e32 v132, v140, v148
	s_waitcnt lgkmcnt(0)
	v_cndmask_b32_e64 v34, 1.0, v130, s[2:3]
	v_mul_f32_e32 v34, v38, v34
	v_mul_f32_e32 v35, v133, v34
	v_mul_f32_e32 v33, v33, v35
	v_mul_f32_e32 v131, v131, v33
	v_mul_f32_e32 v133, v136, v34
	v_mul_f32_e32 v35, v139, v35
	v_mul_f32_e32 v33, v137, v33
	v_mul_f32_e32 v34, v138, v131
	v_cvt_pk_bf16_f32 v34, v34, v33
	v_cvt_pk_bf16_f32 v35, v35, v133
	v_cvt_pk_bf16_f32 v36, v132, v36
	v_cvt_pk_bf16_f32 v37, v40, v37
	v_cndmask_b32_e64 v33, 1.0, v150, s[2:3]
	v_mul_f32_e32 v32, v32, v33
	v_mfma_f32_32x32x16_bf16 v[16:31], v[92:95], v[34:37], v[16:31]
	v_mul_f32_e32 v33, v42, v32
	v_mul_f32_e32 v42, v43, v33
	v_mul_f32_e32 v43, v145, v42
	v_mul_f32_e32 v47, v149, v47
	v_mul_f32_e32 v40, v44, v45
	v_mul_f32_e32 v44, v147, v32
	v_mul_f32_e32 v33, v146, v33
	v_mfma_f32_32x32x16_bf16 v[0:15], v[88:91], v[34:37], v[0:15]
	v_mul_f32_e32 v32, v41, v42
	v_mul_f32_e32 v34, v144, v43
	v_cvt_pk_bf16_f32 v32, v34, v32
	v_cvt_pk_bf16_f32 v33, v33, v44
	v_cvt_pk_bf16_f32 v34, v40, v46
	v_cvt_pk_bf16_f32 v35, v47, v135
	v_mul_f32_e32 v36, v39, v130
	v_mul_f32_e32 v36, v38, v36
	v_mfma_f32_32x32x16_bf16 v[16:31], v[84:87], v[32:35], v[16:31]
	v_log_f32_e32 v36, v36
	s_nop 0
	v_add_f32_e32 v125, v125, v36
	v_mfma_f32_32x32x16_bf16 v[0:15], v[80:83], v[32:35], v[0:15]
	s_branch .LBB0_344
.Lsbq_nomask_5:
	ds_read_b128 v[32:35], v129 offset:9216
	ds_read_b128 v[214:217], v129 offset:9248
	ds_read_b128 v[210:213], v129 offset:9280
	ds_read_b128 v[130:133], v129 offset:9312
	ds_read_b64_tr_b16 v[92:93], v128 offset:49152
	ds_read_b64_tr_b16 v[94:95], v128 offset:50688
	ds_read_b64_tr_b16 v[90:91], v128 offset:50752
	ds_read_b64_tr_b16 v[88:89], v128 offset:49216
	ds_read_b64_tr_b16 v[84:85], v128 offset:52224
	ds_read_b64_tr_b16 v[86:87], v128 offset:53760
	ds_read_b64_tr_b16 v[82:83], v128 offset:53824
	ds_read_b64_tr_b16 v[80:81], v128 offset:52288
	v_exp_f32_e32 v135, v125
	s_waitcnt lgkmcnt(11)
	v_mfma_f32_32x32x16_bf16 v[32:47], v[32:35], v[48:51], 0
	s_waitcnt lgkmcnt(10)
	v_mfma_f32_32x32x16_bf16 v[32:47], v[214:217], v[52:55], v[32:47]
	s_waitcnt lgkmcnt(9)
	v_mfma_f32_32x32x16_bf16 v[32:47], v[210:213], v[56:59], v[32:47]
	s_waitcnt lgkmcnt(8)
	v_mfma_f32_32x32x16_bf16 v[32:47], v[130:133], v[60:63], v[32:47]
	s_nop 11
	v_min_f32_e64 v32, -v32, s60
	v_min_f32_e64 v33, -v33, s60
	v_exp_f32_e32 v32, v32
	v_min_f32_e64 v34, -v34, s60
	v_exp_f32_e32 v33, v33
	v_exp_f32_e32 v34, v34
	v_min_f32_e64 v35, -v35, s60
	v_exp_f32_e32 v130, v35
	v_add_f32_e32 v35, 1.0, v32
	v_add_f32_e32 v131, 1.0, v33
	v_rcp_f32_e32 v35, v35
	v_add_f32_e32 v132, 1.0, v34
	v_rcp_f32_e32 v131, v131
	v_min_f32_e64 v36, -v36, s60
	v_rcp_f32_e32 v132, v132
	v_exp_f32_e32 v36, v36
	v_add_f32_e32 v133, 1.0, v130
	v_rcp_f32_e32 v136, v133
	v_mul_f32_e32 v32, v32, v35
	v_mul_f32_e32 v138, v135, v35
	v_mul_f32_e32 v33, v33, v131
	v_mul_f32_e32 v137, v135, v131
	v_mov_b32_e32 v35, v32
	v_mul_f32_e32 v34, v34, v132
	v_mul_f32_e32 v139, v135, v132
	v_mov_b32_e32 v131, v33
	v_min_f32_e64 v39, -v39, s60
	v_mov_b32_e32 v33, v34
	v_add_f32_e32 v34, 1.0, v36
	v_rcp_f32_e32 v34, v34
	v_mul_f32_e32 v133, v130, v136
	v_exp_f32_e32 v39, v39
	v_mul_f32_e32 v136, v135, v136
	v_mul_f32_e32 v32, v36, v34
	v_min_f32_e64 v36, -v37, s60
	v_exp_f32_e32 v36, v36
	v_mul_f32_e32 v140, v135, v34
	v_add_f32_e32 v34, 1.0, v36
	v_rcp_f32_e32 v34, v34
	v_min_f32_e64 v37, -v38, s60
	v_exp_f32_e32 v37, v37
	v_mul_f32_e32 v38, v36, v34
	v_mul_f32_e32 v141, v135, v34
	v_min_f32_e64 v42, -v42, s60
	v_add_f32_e32 v36, 1.0, v37
	v_rcp_f32_e32 v36, v36
	v_exp_f32_e32 v42, v42
	v_mul_f32_e32 v142, v37, v36
	v_add_f32_e32 v37, 1.0, v39
	v_rcp_f32_e32 v37, v37
	v_mul_f32_e32 v143, v135, v36
	v_mul_f32_e32 v39, v39, v37
	v_min_f32_e64 v36, -v40, s60
	v_exp_f32_e32 v36, v36
	v_mul_f32_e32 v40, v135, v37
	v_min_f32_e64 v37, -v41, s60
	v_exp_f32_e32 v37, v37
	v_add_f32_e32 v34, 1.0, v36
	v_rcp_f32_e32 v34, v34
	v_add_f32_e32 v41, 1.0, v37
	v_rcp_f32_e32 v41, v41
	v_mul_f32_e32 v36, v36, v34
	v_mul_f32_e32 v144, v135, v34
	v_mul_f32_e32 v145, v37, v41
	v_add_f32_e32 v37, 1.0, v42
	v_rcp_f32_e32 v37, v37
	v_min_f32_e64 v45, -v45, s60
	v_mul_f32_e32 v41, v135, v41
	v_mul_f32_e32 v34, v42, v37
	v_min_f32_e64 v42, -v43, s60
	v_exp_f32_e32 v42, v42
	v_mov_b32_e32 v43, v34
	v_mul_f32_e32 v146, v135, v37
	v_min_f32_e64 v37, -v44, s60
	v_exp_f32_e32 v37, v37
	v_add_f32_e32 v34, 1.0, v42
	v_rcp_f32_e32 v34, v34
	v_add_f32_e32 v44, 1.0, v37
	v_rcp_f32_e32 v44, v44
	v_exp_f32_e32 v45, v45
	v_min_f32_e64 v46, -v46, s60
	v_min_f32_e64 v47, -v47, s60
	v_exp_f32_e32 v46, v46
	v_exp_f32_e32 v47, v47
	v_mul_f32_e32 v42, v42, v34
	v_mul_f32_e32 v147, v135, v34
	v_add_f32_e32 v130, 1.0, v46
	v_mul_f32_e32 v34, v37, v44
	v_add_f32_e32 v37, 1.0, v45
	v_rcp_f32_e32 v37, v37
	v_add_f32_e32 v132, 1.0, v47
	v_rcp_f32_e32 v130, v130
	v_rcp_f32_e32 v132, v132
	v_mul_f32_e32 v44, v135, v44
	v_mul_f32_e32 v45, v45, v37
	v_mul_f32_e32 v37, v135, v37
	v_mul_f32_e32 v46, v46, v130
	v_mul_f32_e32 v47, v47, v132
	v_mul_f32_e32 v34, v34, v45
	v_mul_f32_e32 v134, v46, v47
	v_mul_f32_e32 v134, v34, v134
	v_mov_b32_e32 v148, v134
	s_nop 1
	v_permlane32_swap_b32_e32 v134, v148
	v_mul_f32_e32 v149, v135, v130
	v_mul_f32_e32 v34, v135, v132
	s_waitcnt lgkmcnt(0)
	v_cndmask_b32_e64 v130, 1.0, v148, s[2:3]
	v_mul_f32_e32 v135, v34, v130
	v_mul_f32_e32 v34, v36, v145
	v_mul_f32_e32 v36, v43, v42
	v_mul_f32_e32 v36, v34, v36
	v_mul_f32_e32 v32, v32, v38
	v_mul_f32_e32 v34, v142, v39
	v_mov_b32_e32 v150, v36
	s_nop 1
	v_permlane32_swap_b32_e32 v36, v150
	v_mul_f32_e32 v34, v32, v34
	v_mul_f32_e32 v47, v47, v130
	v_mov_b32_e32 v130, v34
	s_nop 1
	v_permlane32_swap_b32_e32 v34, v130
	v_mul_f32_e32 v46, v46, v47
	v_mul_f32_e32 v32, v134, v148
	s_waitcnt lgkmcnt(1)
	v_mul_f32_e32 v132, v36, v150
	v_mul_f32_e32 v45, v45, v46
	v_mul_f32_e32 v46, v37, v46
	s_waitcnt lgkmcnt(0)
	v_cndmask_b32_e64 v134, 1.0, v130, s[2:3]
	v_pk_mul_f32 v[36:37], v[32:33], v[132:133]
	v_pk_mul_f32 v[34:35], v[34:35], v[130:131]
	v_mul_f32_e32 v132, v36, v134
	v_mul_f32_e32 v134, v39, v132
	v_mul_f32_e32 v142, v142, v134
	v_mul_f32_e32 v148, v38, v142
	v_pk_mul_f32 v[38:39], v[34:35], v[36:37]
	v_mov_b32_e32 v130, v39
	s_nop 1
	v_permlane32_swap_b32_e32 v39, v130
	v_mul_f32_e32 v37, v40, v132
	v_mul_f32_e32 v40, v143, v134
	v_mul_f32_e32 v36, v141, v142
	v_mul_f32_e32 v132, v140, v148
	s_waitcnt lgkmcnt(0)
	v_cndmask_b32_e64 v34, 1.0, v130, s[2:3]
	v_mul_f32_e32 v34, v38, v34
	v_mul_f32_e32 v35, v133, v34
	v_mul_f32_e32 v33, v33, v35
	v_mul_f32_e32 v131, v131, v33
	v_mul_f32_e32 v133, v136, v34
	v_mul_f32_e32 v35, v139, v35
	v_mul_f32_e32 v33, v137, v33
	v_mul_f32_e32 v34, v138, v131
	v_cvt_pk_bf16_f32 v34, v34, v33
	v_cvt_pk_bf16_f32 v35, v35, v133
	v_cvt_pk_bf16_f32 v36, v132, v36
	v_cvt_pk_bf16_f32 v37, v40, v37
	v_cndmask_b32_e64 v33, 1.0, v150, s[2:3]
	v_mul_f32_e32 v32, v32, v33
	v_mfma_f32_32x32x16_bf16 v[16:31], v[92:95], v[34:37], v[16:31]
	v_mul_f32_e32 v33, v42, v32
	v_mul_f32_e32 v42, v43, v33
	v_mul_f32_e32 v43, v145, v42
	v_mul_f32_e32 v47, v149, v47
	v_mul_f32_e32 v40, v44, v45
	v_mul_f32_e32 v44, v147, v32
	v_mul_f32_e32 v33, v146, v33
	v_mfma_f32_32x32x16_bf16 v[0:15], v[88:91], v[34:37], v[0:15]
	v_mul_f32_e32 v32, v41, v42
	v_mul_f32_e32 v34, v144, v43
	v_cvt_pk_bf16_f32 v32, v34, v32
	v_cvt_pk_bf16_f32 v33, v33, v44
	v_cvt_pk_bf16_f32 v34, v40, v46
	v_cvt_pk_bf16_f32 v35, v47, v135
	v_mul_f32_e32 v36, v39, v130
	v_mul_f32_e32 v36, v38, v36
	v_mfma_f32_32x32x16_bf16 v[16:31], v[84:87], v[32:35], v[16:31]
	v_log_f32_e32 v36, v36
	s_nop 0
	v_add_f32_e32 v125, v125, v36
	v_mfma_f32_32x32x16_bf16 v[0:15], v[80:83], v[32:35], v[0:15]
; __device__ __forceinline__ void sb_unit(const Frame& F, int b, int hd, int qi, int dry) {
;     ...
;             float run = C;
;             if (!meta && key0 + 96 < tqw + 31) SB_HALF(96);
;             if (!meta && key0 + 64 < tqw + 31 && __any(run >= SB_DEAD)) SB_HALF(64);
;             if (!meta && key0 + 32 < tqw + 31 && __any(run >= SB_DEAD)) SB_HALF(32);
.LBB0_344:
	s_or_b32 s0, s35, 1
	s_cmp_ge_i32 s0, s26
	s_cselect_b64 s[0:1], -1, 0
	s_or_b64 s[0:1], s[18:19], s[0:1]
	s_and_b64 vcc, exec, s[0:1]
	s_cbranch_vccnz .LBB0_347
	v_cmp_le_f32_e32 vcc, s22, v125
	s_cbranch_vccz .LBB0_347
	s_add_i32 s61, s35, 64
	s_cmp_le_i32 s61, s26
	s_cbranch_scc1 .Lsbq_nomask_4
	ds_read_b128 v[32:35], v129 offset:4608
	ds_read_b128 v[214:217], v129 offset:4640
	ds_read_b128 v[210:213], v129 offset:4672
	ds_read_b128 v[130:133], v129 offset:4704
	ds_read_b64_tr_b16 v[92:93], v128 offset:43008
	ds_read_b64_tr_b16 v[94:95], v128 offset:44544
	ds_read_b64_tr_b16 v[90:91], v128 offset:44608
	ds_read_b64_tr_b16 v[88:89], v128 offset:43072
	ds_read_b64_tr_b16 v[84:85], v128 offset:46080
	ds_read_b64_tr_b16 v[86:87], v128 offset:47616
	ds_read_b64_tr_b16 v[82:83], v128 offset:47680
	ds_read_b64_tr_b16 v[80:81], v128 offset:46144
	v_exp_f32_e32 v135, v125
	v_sub_u32_e32 v134, v126, v127
	v_cmp_lt_i32_e32 vcc, 0, v134
	s_waitcnt lgkmcnt(11)
	v_mfma_f32_32x32x16_bf16 v[32:47], v[32:35], v[48:51], 0
	v_cmp_lt_i32_e64 s[0:1], 27, v134
	s_waitcnt lgkmcnt(10)
	v_mfma_f32_32x32x16_bf16 v[32:47], v[214:217], v[52:55], v[32:47]
	s_waitcnt lgkmcnt(9)
	v_mfma_f32_32x32x16_bf16 v[32:47], v[210:213], v[56:59], v[32:47]
	s_waitcnt lgkmcnt(8)
	v_mfma_f32_32x32x16_bf16 v[32:47], v[130:133], v[60:63], v[32:47]
	s_nop 11
	v_min_f32_e64 v32, -v32, s60
	v_min_f32_e64 v33, -v33, s60
	v_exp_f32_e32 v32, v32
	v_min_f32_e64 v34, -v34, s60
	v_exp_f32_e32 v33, v33
	v_exp_f32_e32 v34, v34
	v_min_f32_e64 v35, -v35, s60
	v_exp_f32_e32 v130, v35
	v_add_f32_e32 v35, 1.0, v32
	v_add_f32_e32 v131, 1.0, v33
	v_rcp_f32_e32 v35, v35
	v_add_f32_e32 v132, 1.0, v34
	v_rcp_f32_e32 v131, v131
	v_min_f32_e64 v36, -v36, s60
	v_rcp_f32_e32 v132, v132
	v_exp_f32_e32 v36, v36
	v_add_f32_e32 v133, 1.0, v130
	v_rcp_f32_e32 v136, v133
	v_mul_f32_e32 v32, v32, v35
	v_mul_f32_e32 v133, v135, v35
	v_mul_f32_e32 v33, v33, v131
	v_mul_f32_e32 v137, v135, v131
	v_cndmask_b32_e32 v35, 1.0, v32, vcc
	v_cndmask_b32_e32 v138, 0, v133, vcc
	v_cmp_lt_i32_e32 vcc, 1, v134
	v_mul_f32_e32 v34, v34, v132
	v_mul_f32_e32 v32, v135, v132
	v_cndmask_b32_e32 v131, 1.0, v33, vcc
	v_cndmask_b32_e32 v137, 0, v137, vcc
	v_cmp_lt_i32_e32 vcc, 2, v134
	v_min_f32_e64 v39, -v39, s60
	v_cndmask_b32_e32 v33, 1.0, v34, vcc
	v_add_f32_e32 v34, 1.0, v36
	v_rcp_f32_e32 v34, v34
	v_cndmask_b32_e32 v139, 0, v32, vcc
	v_mul_f32_e32 v32, v130, v136
	v_cmp_lt_i32_e32 vcc, 3, v134
	v_exp_f32_e32 v39, v39
	v_cndmask_b32_e32 v133, 1.0, v32, vcc
	v_mul_f32_e32 v32, v135, v136
	v_cndmask_b32_e32 v136, 0, v32, vcc
	v_mul_f32_e32 v32, v36, v34
	v_min_f32_e64 v36, -v37, s60
	v_exp_f32_e32 v36, v36
	v_cmp_lt_i32_e32 vcc, 8, v134
	v_mul_f32_e32 v34, v135, v34
	v_cndmask_b32_e32 v140, 0, v34, vcc
	v_add_f32_e32 v34, 1.0, v36
	v_rcp_f32_e32 v34, v34
	v_min_f32_e64 v37, -v38, s60
	v_exp_f32_e32 v37, v37
	v_cndmask_b32_e32 v32, 1.0, v32, vcc
	v_mul_f32_e32 v36, v36, v34
	v_cmp_lt_i32_e32 vcc, 9, v134
	v_mul_f32_e32 v34, v135, v34
	v_min_f32_e64 v42, -v42, s60
	v_cndmask_b32_e32 v38, 1.0, v36, vcc
	v_add_f32_e32 v36, 1.0, v37
	v_rcp_f32_e32 v36, v36
	v_cndmask_b32_e32 v141, 0, v34, vcc
	v_cmp_lt_i32_e32 vcc, 10, v134
	v_exp_f32_e32 v42, v42
	v_mul_f32_e32 v34, v37, v36
	v_add_f32_e32 v37, 1.0, v39
	v_rcp_f32_e32 v37, v37
	v_cndmask_b32_e32 v142, 1.0, v34, vcc
	v_mul_f32_e32 v34, v135, v36
	v_cndmask_b32_e32 v143, 0, v34, vcc
	v_mul_f32_e32 v34, v39, v37
	v_cmp_lt_i32_e32 vcc, 11, v134
	v_min_f32_e64 v36, -v40, s60
	v_exp_f32_e32 v36, v36
	v_cndmask_b32_e32 v39, 1.0, v34, vcc
	v_mul_f32_e32 v34, v135, v37
	v_min_f32_e64 v37, -v41, s60
	v_exp_f32_e32 v37, v37
	v_cndmask_b32_e32 v40, 0, v34, vcc
	v_add_f32_e32 v34, 1.0, v36
	v_rcp_f32_e32 v34, v34
	v_add_f32_e32 v41, 1.0, v37
	v_rcp_f32_e32 v41, v41
	v_cmp_lt_i32_e32 vcc, 16, v134
	v_mul_f32_e32 v36, v36, v34
	v_mul_f32_e32 v34, v135, v34
	v_cndmask_b32_e32 v144, 0, v34, vcc
	v_mul_f32_e32 v34, v37, v41
	v_add_f32_e32 v37, 1.0, v42
	v_rcp_f32_e32 v37, v37
	v_cndmask_b32_e32 v36, 1.0, v36, vcc
	v_cmp_lt_i32_e32 vcc, 17, v134
	v_min_f32_e64 v45, -v45, s60
	v_cndmask_b32_e32 v145, 1.0, v34, vcc
	v_mul_f32_e32 v34, v135, v41
	v_cndmask_b32_e32 v41, 0, v34, vcc
	v_mul_f32_e32 v34, v42, v37
	v_cmp_lt_i32_e32 vcc, 18, v134
	v_min_f32_e64 v42, -v43, s60
	v_exp_f32_e32 v42, v42
	v_cndmask_b32_e32 v43, 1.0, v34, vcc
	v_mul_f32_e32 v34, v135, v37
	v_min_f32_e64 v37, -v44, s60
	v_exp_f32_e32 v37, v37
	v_cndmask_b32_e32 v146, 0, v34, vcc
	v_add_f32_e32 v34, 1.0, v42
	v_rcp_f32_e32 v34, v34
	v_add_f32_e32 v44, 1.0, v37
	v_rcp_f32_e32 v44, v44
	v_exp_f32_e32 v45, v45
	v_min_f32_e64 v46, -v46, s60
	v_min_f32_e64 v47, -v47, s60
	v_exp_f32_e32 v46, v46
	v_exp_f32_e32 v47, v47
	v_mul_f32_e32 v42, v42, v34
	v_cmp_lt_i32_e32 vcc, 19, v134
	v_mul_f32_e32 v34, v135, v34
	v_add_f32_e32 v130, 1.0, v46
	v_cndmask_b32_e32 v147, 0, v34, vcc
	v_mul_f32_e32 v34, v37, v44
	v_add_f32_e32 v37, 1.0, v45
	v_rcp_f32_e32 v37, v37
	v_add_f32_e32 v132, 1.0, v47
	v_rcp_f32_e32 v130, v130
	v_rcp_f32_e32 v132, v132
	v_cndmask_b32_e32 v42, 1.0, v42, vcc
	v_cmp_lt_i32_e32 vcc, 24, v134
	v_mul_f32_e32 v44, v135, v44
	v_mul_f32_e32 v45, v45, v37
	v_cndmask_b32_e32 v34, 1.0, v34, vcc
	v_cndmask_b32_e32 v44, 0, v44, vcc
	v_cmp_lt_i32_e32 vcc, 25, v134
	v_mul_f32_e32 v37, v135, v37
	v_mul_f32_e32 v46, v46, v130
	v_cndmask_b32_e32 v45, 1.0, v45, vcc
	v_cndmask_b32_e32 v37, 0, v37, vcc
	v_cmp_lt_i32_e32 vcc, 26, v134
	v_mul_f32_e32 v47, v47, v132
	v_cndmask_b32_e64 v47, 1.0, v47, s[0:1]
	v_cndmask_b32_e32 v46, 1.0, v46, vcc
	v_mul_f32_e32 v34, v34, v45
	v_mul_f32_e32 v134, v46, v47
	v_mul_f32_e32 v134, v34, v134
	v_mov_b32_e32 v148, v134
	s_nop 1
	v_permlane32_swap_b32_e32 v134, v148
	v_mul_f32_e32 v34, v135, v130
	v_cndmask_b32_e32 v149, 0, v34, vcc
	v_mul_f32_e32 v34, v135, v132
	v_cndmask_b32_e64 v34, 0, v34, s[0:1]
	s_waitcnt lgkmcnt(0)
	v_cndmask_b32_e64 v130, 1.0, v148, s[2:3]
	v_mul_f32_e32 v135, v34, v130
	v_mul_f32_e32 v34, v36, v145
	v_mul_f32_e32 v36, v43, v42
	v_mul_f32_e32 v36, v34, v36
	v_mul_f32_e32 v32, v32, v38
	v_mul_f32_e32 v34, v142, v39
	v_mov_b32_e32 v150, v36
	s_nop 1
	v_permlane32_swap_b32_e32 v36, v150
	v_mul_f32_e32 v34, v32, v34
	v_mul_f32_e32 v47, v47, v130
	v_mov_b32_e32 v130, v34
	s_nop 1
	v_permlane32_swap_b32_e32 v34, v130
	v_mul_f32_e32 v46, v46, v47
	v_mul_f32_e32 v32, v134, v148
	s_waitcnt lgkmcnt(1)
	v_mul_f32_e32 v132, v36, v150
	v_mul_f32_e32 v45, v45, v46
	v_mul_f32_e32 v46, v37, v46
	s_waitcnt lgkmcnt(0)
	v_cndmask_b32_e64 v134, 1.0, v130, s[2:3]
	v_pk_mul_f32 v[36:37], v[32:33], v[132:133]
	v_pk_mul_f32 v[34:35], v[34:35], v[130:131]
	v_mul_f32_e32 v132, v36, v134
	v_mul_f32_e32 v134, v39, v132
	v_mul_f32_e32 v142, v142, v134
	v_mul_f32_e32 v148, v38, v142
	v_pk_mul_f32 v[38:39], v[34:35], v[36:37]
	v_mov_b32_e32 v130, v39
	s_nop 1
	v_permlane32_swap_b32_e32 v39, v130
	v_mul_f32_e32 v37, v40, v132
	v_mul_f32_e32 v40, v143, v134
	v_mul_f32_e32 v36, v141, v142
	v_mul_f32_e32 v132, v140, v148
	s_waitcnt lgkmcnt(0)
	v_cndmask_b32_e64 v34, 1.0, v130, s[2:3]
	v_mul_f32_e32 v34, v38, v34
	v_mul_f32_e32 v35, v133, v34
	v_mul_f32_e32 v33, v33, v35
	v_mul_f32_e32 v131, v131, v33
	v_mul_f32_e32 v133, v136, v34
	v_mul_f32_e32 v35, v139, v35
	v_mul_f32_e32 v33, v137, v33
	v_mul_f32_e32 v34, v138, v131
	v_cvt_pk_bf16_f32 v34, v34, v33
	v_cvt_pk_bf16_f32 v35, v35, v133
	v_cvt_pk_bf16_f32 v36, v132, v36
	v_cvt_pk_bf16_f32 v37, v40, v37
	v_cndmask_b32_e64 v33, 1.0, v150, s[2:3]
	v_mul_f32_e32 v32, v32, v33
	v_mfma_f32_32x32x16_bf16 v[16:31], v[92:95], v[34:37], v[16:31]
	v_mul_f32_e32 v33, v42, v32
	v_mul_f32_e32 v42, v43, v33
	v_mul_f32_e32 v43, v145, v42
	v_mul_f32_e32 v47, v149, v47
	v_mul_f32_e32 v40, v44, v45
	v_mul_f32_e32 v44, v147, v32
	v_mul_f32_e32 v33, v146, v33
	v_mfma_f32_32x32x16_bf16 v[0:15], v[88:91], v[34:37], v[0:15]
	v_mul_f32_e32 v32, v41, v42
	v_mul_f32_e32 v34, v144, v43
	v_cvt_pk_bf16_f32 v32, v34, v32
	v_cvt_pk_bf16_f32 v33, v33, v44
	v_cvt_pk_bf16_f32 v34, v40, v46
	v_cvt_pk_bf16_f32 v35, v47, v135
	v_mul_f32_e32 v36, v39, v130
	v_mul_f32_e32 v36, v38, v36
	v_mfma_f32_32x32x16_bf16 v[16:31], v[84:87], v[32:35], v[16:31]
	v_log_f32_e32 v36, v36
	s_nop 0
	v_add_f32_e32 v125, v125, v36
	v_mfma_f32_32x32x16_bf16 v[0:15], v[80:83], v[32:35], v[0:15]
	s_branch .LBB0_347
.Lsbq_nomask_4:
	ds_read_b128 v[32:35], v129 offset:4608
	ds_read_b128 v[214:217], v129 offset:4640
	ds_read_b128 v[210:213], v129 offset:4672
	ds_read_b128 v[130:133], v129 offset:4704
	ds_read_b64_tr_b16 v[92:93], v128 offset:43008
	ds_read_b64_tr_b16 v[94:95], v128 offset:44544
	ds_read_b64_tr_b16 v[90:91], v128 offset:44608
	ds_read_b64_tr_b16 v[88:89], v128 offset:43072
	ds_read_b64_tr_b16 v[84:85], v128 offset:46080
	ds_read_b64_tr_b16 v[86:87], v128 offset:47616
	ds_read_b64_tr_b16 v[82:83], v128 offset:47680
	ds_read_b64_tr_b16 v[80:81], v128 offset:46144
	v_exp_f32_e32 v135, v125
	s_waitcnt lgkmcnt(11)
	v_mfma_f32_32x32x16_bf16 v[32:47], v[32:35], v[48:51], 0
	s_waitcnt lgkmcnt(10)
	v_mfma_f32_32x32x16_bf16 v[32:47], v[214:217], v[52:55], v[32:47]
	s_waitcnt lgkmcnt(9)
	v_mfma_f32_32x32x16_bf16 v[32:47], v[210:213], v[56:59], v[32:47]
	s_waitcnt lgkmcnt(8)
	v_mfma_f32_32x32x16_bf16 v[32:47], v[130:133], v[60:63], v[32:47]
	s_nop 11
	v_min_f32_e64 v32, -v32, s60
	v_min_f32_e64 v33, -v33, s60
	v_exp_f32_e32 v32, v32
	v_min_f32_e64 v34, -v34, s60
	v_exp_f32_e32 v33, v33
	v_exp_f32_e32 v34, v34
	v_min_f32_e64 v35, -v35, s60
	v_exp_f32_e32 v130, v35
	v_add_f32_e32 v35, 1.0, v32
	v_add_f32_e32 v131, 1.0, v33
	v_rcp_f32_e32 v35, v35
	v_add_f32_e32 v132, 1.0, v34
	v_rcp_f32_e32 v131, v131
	v_min_f32_e64 v36, -v36, s60
	v_rcp_f32_e32 v132, v132
	v_exp_f32_e32 v36, v36
	v_add_f32_e32 v133, 1.0, v130
	v_rcp_f32_e32 v136, v133
	v_mul_f32_e32 v32, v32, v35
	v_mul_f32_e32 v138, v135, v35
	v_mul_f32_e32 v33, v33, v131
	v_mul_f32_e32 v137, v135, v131
	v_mov_b32_e32 v35, v32
	v_mul_f32_e32 v34, v34, v132
	v_mul_f32_e32 v139, v135, v132
	v_mov_b32_e32 v131, v33
	v_min_f32_e64 v39, -v39, s60
	v_mov_b32_e32 v33, v34
	v_add_f32_e32 v34, 1.0, v36
	v_rcp_f32_e32 v34, v34
	v_mul_f32_e32 v133, v130, v136
	v_exp_f32_e32 v39, v39
	v_mul_f32_e32 v136, v135, v136
	v_mul_f32_e32 v32, v36, v34
	v_min_f32_e64 v36, -v37, s60
	v_exp_f32_e32 v36, v36
	v_mul_f32_e32 v140, v135, v34
	v_add_f32_e32 v34, 1.0, v36
	v_rcp_f32_e32 v34, v34
	v_min_f32_e64 v37, -v38, s60
	v_exp_f32_e32 v37, v37
	v_mul_f32_e32 v38, v36, v34
	v_mul_f32_e32 v141, v135, v34
	v_min_f32_e64 v42, -v42, s60
	v_add_f32_e32 v36, 1.0, v37
	v_rcp_f32_e32 v36, v36
	v_exp_f32_e32 v42, v42
	v_mul_f32_e32 v142, v37, v36
	v_add_f32_e32 v37, 1.0, v39
	v_rcp_f32_e32 v37, v37
	v_mul_f32_e32 v143, v135, v36
	v_mul_f32_e32 v39, v39, v37
	v_min_f32_e64 v36, -v40, s60
	v_exp_f32_e32 v36, v36
	v_mul_f32_e32 v40, v135, v37
	v_min_f32_e64 v37, -v41, s60
	v_exp_f32_e32 v37, v37
	v_add_f32_e32 v34, 1.0, v36
	v_rcp_f32_e32 v34, v34
	v_add_f32_e32 v41, 1.0, v37
	v_rcp_f32_e32 v41, v41
	v_mul_f32_e32 v36, v36, v34
	v_mul_f32_e32 v144, v135, v34
	v_mul_f32_e32 v145, v37, v41
	v_add_f32_e32 v37, 1.0, v42
	v_rcp_f32_e32 v37, v37
	v_min_f32_e64 v45, -v45, s60
	v_mul_f32_e32 v41, v135, v41
	v_mul_f32_e32 v34, v42, v37
	v_min_f32_e64 v42, -v43, s60
	v_exp_f32_e32 v42, v42
	v_mov_b32_e32 v43, v34
	v_mul_f32_e32 v146, v135, v37
	v_min_f32_e64 v37, -v44, s60
	v_exp_f32_e32 v37, v37
	v_add_f32_e32 v34, 1.0, v42
	v_rcp_f32_e32 v34, v34
	v_add_f32_e32 v44, 1.0, v37
	v_rcp_f32_e32 v44, v44
	v_exp_f32_e32 v45, v45
	v_min_f32_e64 v46, -v46, s60
	v_min_f32_e64 v47, -v47, s60
	v_exp_f32_e32 v46, v46
	v_exp_f32_e32 v47, v47
	v_mul_f32_e32 v42, v42, v34
	v_mul_f32_e32 v147, v135, v34
	v_add_f32_e32 v130, 1.0, v46
	v_mul_f32_e32 v34, v37, v44
	v_add_f32_e32 v37, 1.0, v45
	v_rcp_f32_e32 v37, v37
	v_add_f32_e32 v132, 1.0, v47
	v_rcp_f32_e32 v130, v130
	v_rcp_f32_e32 v132, v132
	v_mul_f32_e32 v44, v135, v44
	v_mul_f32_e32 v45, v45, v37
	v_mul_f32_e32 v37, v135, v37
	v_mul_f32_e32 v46, v46, v130
	v_mul_f32_e32 v47, v47, v132
	v_mul_f32_e32 v34, v34, v45
	v_mul_f32_e32 v134, v46, v47
	v_mul_f32_e32 v134, v34, v134
	v_mov_b32_e32 v148, v134
	s_nop 1
	v_permlane32_swap_b32_e32 v134, v148
	v_mul_f32_e32 v149, v135, v130
	v_mul_f32_e32 v34, v135, v132
	s_waitcnt lgkmcnt(0)
	v_cndmask_b32_e64 v130, 1.0, v148, s[2:3]
	v_mul_f32_e32 v135, v34, v130
	v_mul_f32_e32 v34, v36, v145
	v_mul_f32_e32 v36, v43, v42
	v_mul_f32_e32 v36, v34, v36
	v_mul_f32_e32 v32, v32, v38
	v_mul_f32_e32 v34, v142, v39
	v_mov_b32_e32 v150, v36
	s_nop 1
	v_permlane32_swap_b32_e32 v36, v150
	v_mul_f32_e32 v34, v32, v34
	v_mul_f32_e32 v47, v47, v130
	v_mov_b32_e32 v130, v34
	s_nop 1
	v_permlane32_swap_b32_e32 v34, v130
	v_mul_f32_e32 v46, v46, v47
	v_mul_f32_e32 v32, v134, v148
	s_waitcnt lgkmcnt(1)
	v_mul_f32_e32 v132, v36, v150
	v_mul_f32_e32 v45, v45, v46
	v_mul_f32_e32 v46, v37, v46
	s_waitcnt lgkmcnt(0)
	v_cndmask_b32_e64 v134, 1.0, v130, s[2:3]
	v_pk_mul_f32 v[36:37], v[32:33], v[132:133]
	v_pk_mul_f32 v[34:35], v[34:35], v[130:131]
	v_mul_f32_e32 v132, v36, v134
	v_mul_f32_e32 v134, v39, v132
	v_mul_f32_e32 v142, v142, v134
	v_mul_f32_e32 v148, v38, v142
	v_pk_mul_f32 v[38:39], v[34:35], v[36:37]
	v_mov_b32_e32 v130, v39
	s_nop 1
	v_permlane32_swap_b32_e32 v39, v130
	v_mul_f32_e32 v37, v40, v132
	v_mul_f32_e32 v40, v143, v134
	v_mul_f32_e32 v36, v141, v142
	v_mul_f32_e32 v132, v140, v148
	s_waitcnt lgkmcnt(0)
	v_cndmask_b32_e64 v34, 1.0, v130, s[2:3]
	v_mul_f32_e32 v34, v38, v34
	v_mul_f32_e32 v35, v133, v34
	v_mul_f32_e32 v33, v33, v35
	v_mul_f32_e32 v131, v131, v33
	v_mul_f32_e32 v133, v136, v34
	v_mul_f32_e32 v35, v139, v35
	v_mul_f32_e32 v33, v137, v33
	v_mul_f32_e32 v34, v138, v131
	v_cvt_pk_bf16_f32 v34, v34, v33
	v_cvt_pk_bf16_f32 v35, v35, v133
	v_cvt_pk_bf16_f32 v36, v132, v36
	v_cvt_pk_bf16_f32 v37, v40, v37
	v_cndmask_b32_e64 v33, 1.0, v150, s[2:3]
	v_mul_f32_e32 v32, v32, v33
	v_mfma_f32_32x32x16_bf16 v[16:31], v[92:95], v[34:37], v[16:31]
	v_mul_f32_e32 v33, v42, v32
	v_mul_f32_e32 v42, v43, v33
	v_mul_f32_e32 v43, v145, v42
	v_mul_f32_e32 v47, v149, v47
	v_mul_f32_e32 v40, v44, v45
	v_mul_f32_e32 v44, v147, v32
	v_mul_f32_e32 v33, v146, v33
	v_mfma_f32_32x32x16_bf16 v[0:15], v[88:91], v[34:37], v[0:15]
	v_mul_f32_e32 v32, v41, v42
	v_mul_f32_e32 v34, v144, v43
	v_cvt_pk_bf16_f32 v32, v34, v32
	v_cvt_pk_bf16_f32 v33, v33, v44
	v_cvt_pk_bf16_f32 v34, v40, v46
	v_cvt_pk_bf16_f32 v35, v47, v135
	v_mul_f32_e32 v36, v39, v130
	v_mul_f32_e32 v36, v38, v36
	v_mfma_f32_32x32x16_bf16 v[16:31], v[84:87], v[32:35], v[16:31]
	v_log_f32_e32 v36, v36
	s_nop 0
	v_add_f32_e32 v125, v125, v36
	v_mfma_f32_32x32x16_bf16 v[0:15], v[80:83], v[32:35], v[0:15]

.Lsbq0_masked_2:
	ds_read_b128 v[32:35], v129
	ds_read_b128 v[214:217], v129 offset:32
	ds_read_b128 v[210:213], v129 offset:64
	ds_read_b128 v[130:133], v129 offset:96
	ds_read_b64_tr_b16 v[92:93], v128 offset:36864
	ds_read_b64_tr_b16 v[94:95], v128 offset:38400
	ds_read_b64_tr_b16 v[90:91], v128 offset:38464
	ds_read_b64_tr_b16 v[88:89], v128 offset:36928
	ds_read_b64_tr_b16 v[84:85], v128 offset:39936
	ds_read_b64_tr_b16 v[86:87], v128 offset:41472
	ds_read_b64_tr_b16 v[82:83], v128 offset:41536
	ds_read_b64_tr_b16 v[80:81], v128 offset:40000
	v_cndmask_b32_e64 v129, v114, 16, s[18:19]
	v_sub_u32_e32 v127, v129, v127
	v_cmp_lt_i32_e32 vcc, 0, v127
	v_cmp_lt_i32_e64 s[0:1], 27, v127
	v_exp_f32_e32 v128, v125
	s_waitcnt lgkmcnt(11)
	v_mfma_f32_32x32x16_bf16 v[32:47], v[32:35], v[48:51], 0
	s_waitcnt lgkmcnt(10)
	v_mfma_f32_32x32x16_bf16 v[32:47], v[214:217], v[52:55], v[32:47]
	s_waitcnt lgkmcnt(9)
	v_mfma_f32_32x32x16_bf16 v[32:47], v[210:213], v[56:59], v[32:47]
	s_waitcnt lgkmcnt(8)
	v_mfma_f32_32x32x16_bf16 v[32:47], v[130:133], v[60:63], v[32:47]
	s_nop 11
	v_min_f32_e64 v32, -v32, s60
	v_min_f32_e64 v33, -v33, s60
	v_exp_f32_e32 v32, v32
	v_min_f32_e64 v34, -v34, s60
	v_exp_f32_e32 v33, v33
	v_exp_f32_e32 v34, v34
	v_min_f32_e64 v35, -v35, s60
	v_exp_f32_e32 v130, v35
	v_add_f32_e32 v35, 1.0, v32
	v_add_f32_e32 v129, 1.0, v33
	v_rcp_f32_e32 v35, v35
	v_add_f32_e32 v131, 1.0, v34
	v_rcp_f32_e32 v129, v129
	v_rcp_f32_e32 v131, v131
	v_add_f32_e32 v132, 1.0, v130
	v_rcp_f32_e32 v132, v132
	v_mul_f32_e32 v32, v32, v35
	v_mul_f32_e32 v133, v128, v35
	v_min_f32_e64 v36, -v36, s60
	v_mul_f32_e32 v33, v33, v129
	v_mul_f32_e32 v134, v128, v129
	v_cndmask_b32_e32 v35, 1.0, v32, vcc
	v_cndmask_b32_e32 v133, 0, v133, vcc
	v_cmp_lt_i32_e32 vcc, 1, v127
	v_mul_f32_e32 v34, v34, v131
	v_exp_f32_e32 v32, v36
	v_cndmask_b32_e32 v129, 1.0, v33, vcc
	v_cndmask_b32_e32 v134, 0, v134, vcc
	v_cmp_lt_i32_e32 vcc, 2, v127
	v_add_f32_e32 v36, 1.0, v32
	v_rcp_f32_e32 v36, v36
	v_cndmask_b32_e32 v33, 1.0, v34, vcc
	v_mul_f32_e32 v34, v128, v131
	v_cndmask_b32_e32 v135, 0, v34, vcc
	v_mul_f32_e32 v34, v130, v132
	v_cmp_lt_i32_e32 vcc, 3, v127
	v_mul_f32_e32 v32, v32, v36
	v_mul_f32_e32 v36, v128, v36
	v_cndmask_b32_e32 v131, 1.0, v34, vcc
	v_mul_f32_e32 v34, v128, v132
	v_cndmask_b32_e32 v132, 0, v34, vcc
	v_min_f32_e64 v34, -v37, s60
	v_exp_f32_e32 v34, v34
	v_cmp_lt_i32_e32 vcc, 8, v127
	v_min_f32_e64 v37, -v38, s60
	v_cndmask_b32_e32 v136, 0, v36, vcc
	v_add_f32_e32 v36, 1.0, v34
	v_rcp_f32_e32 v36, v36
	v_exp_f32_e32 v37, v37
	v_cndmask_b32_e32 v32, 1.0, v32, vcc
	v_cmp_lt_i32_e32 vcc, 9, v127
	v_mul_f32_e32 v34, v34, v36
	v_cndmask_b32_e32 v38, 1.0, v34, vcc
	v_add_f32_e32 v34, 1.0, v37
	v_min_f32_e64 v39, -v39, s60
	v_rcp_f32_e32 v34, v34
	v_exp_f32_e32 v39, v39
	v_mul_f32_e32 v36, v128, v36
	v_cndmask_b32_e32 v137, 0, v36, vcc
	v_mul_f32_e32 v36, v37, v34
	v_add_f32_e32 v37, 1.0, v39
	v_rcp_f32_e32 v37, v37
	v_cmp_lt_i32_e32 vcc, 10, v127
	v_mul_f32_e32 v34, v128, v34
	v_cndmask_b32_e32 v138, 1.0, v36, vcc
	v_cndmask_b32_e32 v139, 0, v34, vcc
	v_mul_f32_e32 v34, v39, v37
	v_cmp_lt_i32_e32 vcc, 11, v127
	v_min_f32_e64 v36, -v40, s60
	v_exp_f32_e32 v36, v36
	v_cndmask_b32_e32 v39, 1.0, v34, vcc
	v_mul_f32_e32 v34, v128, v37
	v_min_f32_e64 v37, -v41, s60
	v_exp_f32_e32 v37, v37
	v_cndmask_b32_e32 v40, 0, v34, vcc
	v_add_f32_e32 v34, 1.0, v36
	v_rcp_f32_e32 v34, v34
	v_add_f32_e32 v41, 1.0, v37
	v_min_f32_e64 v42, -v42, s60
	v_rcp_f32_e32 v41, v41
	v_exp_f32_e32 v42, v42
	v_mul_f32_e32 v36, v36, v34
	v_cmp_lt_i32_e32 vcc, 16, v127
	v_mul_f32_e32 v34, v128, v34
	v_cndmask_b32_e32 v140, 0, v34, vcc
	v_mul_f32_e32 v34, v37, v41
	v_add_f32_e32 v37, 1.0, v42
	v_rcp_f32_e32 v37, v37
	v_cndmask_b32_e32 v36, 1.0, v36, vcc
	v_cmp_lt_i32_e32 vcc, 17, v127
	v_min_f32_e64 v45, -v45, s60
	v_cndmask_b32_e32 v141, 1.0, v34, vcc
	v_mul_f32_e32 v34, v128, v41
	v_cndmask_b32_e32 v41, 0, v34, vcc
	v_mul_f32_e32 v34, v42, v37
	v_cmp_lt_i32_e32 vcc, 18, v127
	v_min_f32_e64 v42, -v43, s60
	v_exp_f32_e32 v42, v42
	v_cndmask_b32_e32 v43, 1.0, v34, vcc
	v_mul_f32_e32 v34, v128, v37
	v_min_f32_e64 v37, -v44, s60
	v_exp_f32_e32 v37, v37
	v_cndmask_b32_e32 v142, 0, v34, vcc
	v_add_f32_e32 v34, 1.0, v42
	v_rcp_f32_e32 v34, v34
	v_add_f32_e32 v44, 1.0, v37
	v_rcp_f32_e32 v44, v44
	v_exp_f32_e32 v45, v45
	v_min_f32_e64 v46, -v46, s60
	v_min_f32_e64 v47, -v47, s60
	v_exp_f32_e32 v46, v46
	v_exp_f32_e32 v47, v47
	v_mul_f32_e32 v42, v42, v34
	v_cmp_lt_i32_e32 vcc, 19, v127
	v_mul_f32_e32 v34, v128, v34
	v_add_f32_e32 v130, 1.0, v46
	v_cndmask_b32_e32 v143, 0, v34, vcc
	v_mul_f32_e32 v34, v37, v44
	v_add_f32_e32 v37, 1.0, v45
	v_rcp_f32_e32 v37, v37
	v_add_f32_e32 v144, 1.0, v47
	v_rcp_f32_e32 v130, v130
	v_rcp_f32_e32 v144, v144
	v_cndmask_b32_e32 v42, 1.0, v42, vcc
	v_cmp_lt_i32_e32 vcc, 24, v127
	v_mul_f32_e32 v44, v128, v44
	v_mul_f32_e32 v45, v45, v37
	v_cndmask_b32_e32 v34, 1.0, v34, vcc
	v_cndmask_b32_e32 v44, 0, v44, vcc
	v_cmp_lt_i32_e32 vcc, 25, v127
	v_mul_f32_e32 v37, v128, v37
	v_mul_f32_e32 v46, v46, v130
	v_cndmask_b32_e32 v45, 1.0, v45, vcc
	v_cndmask_b32_e32 v37, 0, v37, vcc
	v_cmp_lt_i32_e32 vcc, 26, v127
	v_mul_f32_e32 v47, v47, v144
	v_cndmask_b32_e64 v47, 1.0, v47, s[0:1]
	v_cndmask_b32_e32 v46, 1.0, v46, vcc
	v_mul_f32_e32 v34, v34, v45
	v_mul_f32_e32 v127, v46, v47
	v_mul_f32_e32 v127, v34, v127
	v_mov_b32_e32 v145, v127
	s_nop 1
	v_permlane32_swap_b32_e32 v127, v145
	v_mul_f32_e32 v34, v128, v130
	v_cndmask_b32_e32 v130, 0, v34, vcc
	v_mul_f32_e32 v34, v128, v144
	v_cndmask_b32_e64 v34, 0, v34, s[0:1]
	s_waitcnt lgkmcnt(0)
	v_cndmask_b32_e64 v128, 1.0, v145, s[2:3]
	v_mul_f32_e32 v144, v34, v128
	v_mul_f32_e32 v34, v36, v141
	v_mul_f32_e32 v36, v43, v42
	v_mul_f32_e32 v36, v34, v36
	v_mul_f32_e32 v32, v32, v38
	v_mul_f32_e32 v34, v138, v39
	v_mov_b32_e32 v146, v36
	s_nop 1
	v_permlane32_swap_b32_e32 v36, v146
	v_mul_f32_e32 v34, v32, v34
	v_mul_f32_e32 v47, v47, v128
	v_mov_b32_e32 v128, v34
	s_nop 1
	v_permlane32_swap_b32_e32 v34, v128
	v_mul_f32_e32 v46, v46, v47
	v_mul_f32_e32 v47, v130, v47
	v_mul_f32_e32 v32, v127, v145
	s_waitcnt lgkmcnt(1)
	v_mul_f32_e32 v130, v36, v146
	v_mul_f32_e32 v45, v45, v46
	v_mul_f32_e32 v46, v37, v46
	s_waitcnt lgkmcnt(0)
	v_cndmask_b32_e64 v127, 1.0, v128, s[2:3]
	v_pk_mul_f32 v[36:37], v[32:33], v[130:131]
	v_pk_mul_f32 v[34:35], v[34:35], v[128:129]
	v_mul_f32_e32 v127, v36, v127
	v_mul_f32_e32 v130, v39, v127
	v_mul_f32_e32 v138, v138, v130
	v_mul_f32_e32 v145, v38, v138
	v_pk_mul_f32 v[38:39], v[34:35], v[36:37]
	v_mov_b32_e32 v128, v39
	s_nop 1
	v_permlane32_swap_b32_e32 v39, v128
	v_mul_f32_e32 v37, v40, v127
	v_mul_f32_e32 v40, v139, v130
	v_mul_f32_e32 v36, v137, v138
	v_mul_f32_e32 v127, v136, v145
	s_waitcnt lgkmcnt(0)
	v_cndmask_b32_e64 v34, 1.0, v128, s[2:3]
	v_mul_f32_e32 v34, v38, v34
	v_mul_f32_e32 v35, v131, v34
	v_mul_f32_e32 v33, v33, v35
	v_mul_f32_e32 v129, v129, v33
	v_mul_f32_e32 v130, v132, v34
	v_mul_f32_e32 v35, v135, v35
	v_mul_f32_e32 v33, v134, v33
	v_mul_f32_e32 v34, v133, v129
	v_cvt_pk_bf16_f32 v34, v34, v33
	v_cvt_pk_bf16_f32 v35, v35, v130
	v_cvt_pk_bf16_f32 v36, v127, v36
	v_cvt_pk_bf16_f32 v37, v40, v37
	v_cndmask_b32_e64 v33, 1.0, v146, s[2:3]
	v_mul_f32_e32 v32, v32, v33
	v_mfma_f32_32x32x16_bf16 v[16:31], v[92:95], v[34:37], v[16:31]
	v_mul_f32_e32 v33, v42, v32
	v_mul_f32_e32 v42, v43, v33
	v_mul_f32_e32 v43, v141, v42
	v_mul_f32_e32 v40, v44, v45
	v_mul_f32_e32 v44, v143, v32
	v_mul_f32_e32 v33, v142, v33
	v_mul_f32_e32 v32, v41, v42
	v_mfma_f32_32x32x16_bf16 v[0:15], v[88:91], v[34:37], v[0:15]
	v_mul_f32_e32 v34, v140, v43
	v_cvt_pk_bf16_f32 v32, v34, v32
	v_cvt_pk_bf16_f32 v33, v33, v44
	v_cvt_pk_bf16_f32 v34, v40, v46
	v_cvt_pk_bf16_f32 v35, v47, v144
	v_mul_f32_e32 v36, v39, v128
	v_mul_f32_e32 v36, v38, v36
	v_mfma_f32_32x32x16_bf16 v[16:31], v[84:87], v[32:35], v[16:31]
	v_log_f32_e32 v36, v36
	s_nop 0
	v_add_f32_e32 v125, v125, v36
	v_mfma_f32_32x32x16_bf16 v[0:15], v[80:83], v[32:35], v[0:15]
	s_branch .LBB0_349
.Lsbq0_nomask_2:
	ds_read_b128 v[32:35], v129
	ds_read_b128 v[214:217], v129 offset:32
	ds_read_b128 v[210:213], v129 offset:64
	ds_read_b128 v[130:133], v129 offset:96
	ds_read_b64_tr_b16 v[92:93], v128 offset:36864
	ds_read_b64_tr_b16 v[94:95], v128 offset:38400
	ds_read_b64_tr_b16 v[90:91], v128 offset:38464
	ds_read_b64_tr_b16 v[88:89], v128 offset:36928
	ds_read_b64_tr_b16 v[84:85], v128 offset:39936
	ds_read_b64_tr_b16 v[86:87], v128 offset:41472
	ds_read_b64_tr_b16 v[82:83], v128 offset:41536
	ds_read_b64_tr_b16 v[80:81], v128 offset:40000
	v_exp_f32_e32 v128, v125
	s_waitcnt lgkmcnt(11)
	v_mfma_f32_32x32x16_bf16 v[32:47], v[32:35], v[48:51], 0
	s_waitcnt lgkmcnt(10)
	v_mfma_f32_32x32x16_bf16 v[32:47], v[214:217], v[52:55], v[32:47]
	s_waitcnt lgkmcnt(9)
	v_mfma_f32_32x32x16_bf16 v[32:47], v[210:213], v[56:59], v[32:47]
	s_waitcnt lgkmcnt(8)
	v_mfma_f32_32x32x16_bf16 v[32:47], v[130:133], v[60:63], v[32:47]
	s_nop 11
	v_min_f32_e64 v32, -v32, s60
	v_min_f32_e64 v33, -v33, s60
	v_exp_f32_e32 v32, v32
	v_min_f32_e64 v34, -v34, s60
	v_exp_f32_e32 v33, v33
	v_exp_f32_e32 v34, v34
	v_min_f32_e64 v35, -v35, s60
	v_exp_f32_e32 v130, v35
	v_add_f32_e32 v35, 1.0, v32
	v_add_f32_e32 v129, 1.0, v33
	v_rcp_f32_e32 v35, v35
	v_add_f32_e32 v131, 1.0, v34
	v_rcp_f32_e32 v129, v129
	v_rcp_f32_e32 v131, v131
	v_add_f32_e32 v132, 1.0, v130
	v_rcp_f32_e32 v132, v132
	v_mul_f32_e32 v32, v32, v35
	v_mul_f32_e32 v133, v128, v35
	v_min_f32_e64 v36, -v36, s60
	v_mul_f32_e32 v33, v33, v129
	v_mul_f32_e32 v134, v128, v129
	v_mov_b32_e32 v35, v32
	v_mul_f32_e32 v34, v34, v131
	v_exp_f32_e32 v32, v36
	v_mov_b32_e32 v129, v33
	v_add_f32_e32 v36, 1.0, v32
	v_rcp_f32_e32 v36, v36
	v_mov_b32_e32 v33, v34
	v_mul_f32_e32 v135, v128, v131
	v_mul_f32_e32 v131, v130, v132
	v_mul_f32_e32 v32, v32, v36
	v_mul_f32_e32 v136, v128, v36
	v_mul_f32_e32 v132, v128, v132
	v_min_f32_e64 v34, -v37, s60
	v_exp_f32_e32 v34, v34
	v_min_f32_e64 v37, -v38, s60
	v_add_f32_e32 v36, 1.0, v34
	v_rcp_f32_e32 v36, v36
	v_exp_f32_e32 v37, v37
	v_mul_f32_e32 v38, v34, v36
	v_add_f32_e32 v34, 1.0, v37
	v_min_f32_e64 v39, -v39, s60
	v_rcp_f32_e32 v34, v34
	v_exp_f32_e32 v39, v39
	v_mul_f32_e32 v137, v128, v36
	v_mul_f32_e32 v138, v37, v34
	v_add_f32_e32 v37, 1.0, v39
	v_rcp_f32_e32 v37, v37
	v_mul_f32_e32 v139, v128, v34
	v_mul_f32_e32 v39, v39, v37
	v_min_f32_e64 v36, -v40, s60
	v_exp_f32_e32 v36, v36
	v_mul_f32_e32 v40, v128, v37
	v_min_f32_e64 v37, -v41, s60
	v_exp_f32_e32 v37, v37
	v_add_f32_e32 v34, 1.0, v36
	v_rcp_f32_e32 v34, v34
	v_add_f32_e32 v41, 1.0, v37
	v_min_f32_e64 v42, -v42, s60
	v_rcp_f32_e32 v41, v41
	v_exp_f32_e32 v42, v42
	v_mul_f32_e32 v36, v36, v34
	v_mul_f32_e32 v140, v128, v34
	v_mul_f32_e32 v141, v37, v41
	v_add_f32_e32 v37, 1.0, v42
	v_rcp_f32_e32 v37, v37
	v_min_f32_e64 v45, -v45, s60
	v_mul_f32_e32 v41, v128, v41
	v_mul_f32_e32 v34, v42, v37
	v_min_f32_e64 v42, -v43, s60
	v_exp_f32_e32 v42, v42
	v_mov_b32_e32 v43, v34
	v_mul_f32_e32 v142, v128, v37
	v_min_f32_e64 v37, -v44, s60
	v_exp_f32_e32 v37, v37
	v_add_f32_e32 v34, 1.0, v42
	v_rcp_f32_e32 v34, v34
	v_add_f32_e32 v44, 1.0, v37
	v_rcp_f32_e32 v44, v44
	v_exp_f32_e32 v45, v45
	v_min_f32_e64 v46, -v46, s60
	v_min_f32_e64 v47, -v47, s60
	v_exp_f32_e32 v46, v46
	v_exp_f32_e32 v47, v47
	v_mul_f32_e32 v42, v42, v34
	v_mul_f32_e32 v143, v128, v34
	v_add_f32_e32 v130, 1.0, v46
	v_mul_f32_e32 v34, v37, v44
	v_add_f32_e32 v37, 1.0, v45
	v_rcp_f32_e32 v37, v37
	v_add_f32_e32 v144, 1.0, v47
	v_rcp_f32_e32 v130, v130
	v_rcp_f32_e32 v144, v144
	v_mul_f32_e32 v44, v128, v44
	v_mul_f32_e32 v45, v45, v37
	v_mul_f32_e32 v37, v128, v37
	v_mul_f32_e32 v46, v46, v130
	v_mul_f32_e32 v47, v47, v144
	v_mul_f32_e32 v34, v34, v45
	v_mul_f32_e32 v127, v46, v47
	v_mul_f32_e32 v127, v34, v127
	v_mov_b32_e32 v145, v127
	s_nop 1
	v_permlane32_swap_b32_e32 v127, v145
	v_mul_f32_e32 v130, v128, v130
	v_mul_f32_e32 v34, v128, v144
	s_waitcnt lgkmcnt(0)
	v_cndmask_b32_e64 v128, 1.0, v145, s[2:3]
	v_mul_f32_e32 v144, v34, v128
	v_mul_f32_e32 v34, v36, v141
	v_mul_f32_e32 v36, v43, v42
	v_mul_f32_e32 v36, v34, v36
	v_mul_f32_e32 v32, v32, v38
	v_mul_f32_e32 v34, v138, v39
	v_mov_b32_e32 v146, v36
	s_nop 1
	v_permlane32_swap_b32_e32 v36, v146
	v_mul_f32_e32 v34, v32, v34
	v_mul_f32_e32 v47, v47, v128
	v_mov_b32_e32 v128, v34
	s_nop 1
	v_permlane32_swap_b32_e32 v34, v128
	v_mul_f32_e32 v46, v46, v47
	v_mul_f32_e32 v47, v130, v47
	v_mul_f32_e32 v32, v127, v145
	s_waitcnt lgkmcnt(1)
	v_mul_f32_e32 v130, v36, v146
	v_mul_f32_e32 v45, v45, v46
	v_mul_f32_e32 v46, v37, v46
	s_waitcnt lgkmcnt(0)
	v_cndmask_b32_e64 v127, 1.0, v128, s[2:3]
	v_pk_mul_f32 v[36:37], v[32:33], v[130:131]
	v_pk_mul_f32 v[34:35], v[34:35], v[128:129]
	v_mul_f32_e32 v127, v36, v127
	v_mul_f32_e32 v130, v39, v127
	v_mul_f32_e32 v138, v138, v130
	v_mul_f32_e32 v145, v38, v138
	v_pk_mul_f32 v[38:39], v[34:35], v[36:37]
	v_mov_b32_e32 v128, v39
	s_nop 1
	v_permlane32_swap_b32_e32 v39, v128
	v_mul_f32_e32 v37, v40, v127
	v_mul_f32_e32 v40, v139, v130
	v_mul_f32_e32 v36, v137, v138
	v_mul_f32_e32 v127, v136, v145
	s_waitcnt lgkmcnt(0)
	v_cndmask_b32_e64 v34, 1.0, v128, s[2:3]
	v_mul_f32_e32 v34, v38, v34
	v_mul_f32_e32 v35, v131, v34
	v_mul_f32_e32 v33, v33, v35
	v_mul_f32_e32 v129, v129, v33
	v_mul_f32_e32 v130, v132, v34
	v_mul_f32_e32 v35, v135, v35
	v_mul_f32_e32 v33, v134, v33
	v_mul_f32_e32 v34, v133, v129
	v_cvt_pk_bf16_f32 v34, v34, v33
	v_cvt_pk_bf16_f32 v35, v35, v130
	v_cvt_pk_bf16_f32 v36, v127, v36
	v_cvt_pk_bf16_f32 v37, v40, v37
	v_cndmask_b32_e64 v33, 1.0, v146, s[2:3]
	v_mul_f32_e32 v32, v32, v33
	v_mfma_f32_32x32x16_bf16 v[16:31], v[92:95], v[34:37], v[16:31]
	v_mul_f32_e32 v33, v42, v32
	v_mul_f32_e32 v42, v43, v33
	v_mul_f32_e32 v43, v141, v42
	v_mul_f32_e32 v40, v44, v45
	v_mul_f32_e32 v44, v143, v32
	v_mul_f32_e32 v33, v142, v33
	v_mul_f32_e32 v32, v41, v42
	v_mfma_f32_32x32x16_bf16 v[0:15], v[88:91], v[34:37], v[0:15]
	v_mul_f32_e32 v34, v140, v43
	v_cvt_pk_bf16_f32 v32, v34, v32
	v_cvt_pk_bf16_f32 v33, v33, v44
	v_cvt_pk_bf16_f32 v34, v40, v46
	v_cvt_pk_bf16_f32 v35, v47, v144
	v_mul_f32_e32 v36, v39, v128
	v_mul_f32_e32 v36, v38, v36
	v_mfma_f32_32x32x16_bf16 v[16:31], v[84:87], v[32:35], v[16:31]
	v_log_f32_e32 v36, v36
	s_nop 0
	v_add_f32_e32 v125, v125, v36
	v_mfma_f32_32x32x16_bf16 v[0:15], v[80:83], v[32:35], v[0:15]

; #define LAS __attribute__((address_space(3)))
; #define S_LOAD(key0) do { st0 = *(const u32x4*)(kg + (size_t)(key0) * 1024); st1 = *(const u32x4*)(kg + (size_t)((key0) + 64) * 1024); st2 = *(const u32x4*)(vg + (size_t)(key0) * 1024); st3 = *(const u32x4*)(vg + (size_t)((key0) + 64) * 1024); } while (0)
; __device__ __forceinline__ void sb_unit(const Frame& F, int b, int hd, int qi, int dry) {
;     ...
;         const bool meta = (it > jmax);
;         const int key0 = meta ? 0 : NMETA + 128 * (jmax - it);
;         if (it + 1 < nt) { const int nk = (it + 1 > jmax) ? 0 : NMETA + 128 * (jmax - it - 1); S_LOAD(nk); }
;         if (!dead && (meta || key0 < tqw + 31)) {
;             const LAS unsigned char* kb = lds + kra + (it & 1) * SK_BUF;
;             const LAS unsigned char* vb = lds + vra + (it & 1) * SV_BUF;
;     ...
;             float run = C;
;             if (!meta && key0 + 96 < tqw + 31) SB_HALF(96);
.LBB0_360:
	s_xor_b64 s[0:1], s[0:1], -1
	s_andn2_b64 vcc, exec, s[0:1]
	s_mov_b64 s[0:1], -1
	s_cbranch_vccnz .LBB0_373
	s_add_i32 s34, s31, 0xffffff10
	s_cmp_gt_u32 s35, s27
	s_cselect_b64 s[18:19], -1, 0
	s_and_b64 s[0:1], s[18:19], exec
	s_cselect_b32 s34, 0, s34
	s_cmp_lt_i32 s34, s29
	s_cselect_b64 s[0:1], -1, 0
	s_or_b64 s[0:1], s[18:19], s[0:1]
	s_andn2_b64 vcc, exec, s[0:1]
	s_mov_b64 s[0:1], 0
	s_cbranch_vccnz .LBB0_373
	s_and_b32 s0, s35, 1
	s_mul_i32 s35, s0, 0x4800
	s_mul_i32 s36, s0, 0x6000
	s_or_b32 s0, s34, 0x41
	s_cmp_ge_i32 s0, s25
	s_cselect_b64 s[0:1], -1, 0
	s_or_b64 s[0:1], s[18:19], s[0:1]
	s_and_b64 vcc, exec, s[0:1]
	v_add_u32_e32 v129, s35, v118
	v_or_b32_e32 v127, s34, v205
	v_add_u32_e32 v128, s36, v119
	s_cbranch_vccnz .LBB0_364
	s_add_i32 s61, s34, 128
	s_cmp_le_i32 s61, s25
	s_cbranch_scc1 .Lsbq_nomask_3
	ds_read_b128 v[32:35], v129 offset:13824
	ds_read_b128 v[214:217], v129 offset:13856
	ds_read_b128 v[210:213], v129 offset:13888
	ds_read_b128 v[130:133], v129 offset:13920
	ds_read_b64_tr_b16 v[92:93], v128 offset:55296
	ds_read_b64_tr_b16 v[94:95], v128 offset:56832
	ds_read_b64_tr_b16 v[90:91], v128 offset:56896
	ds_read_b64_tr_b16 v[88:89], v128 offset:55360
	ds_read_b64_tr_b16 v[84:85], v128 offset:58368
	ds_read_b64_tr_b16 v[86:87], v128 offset:59904
	ds_read_b64_tr_b16 v[82:83], v128 offset:59968
	ds_read_b64_tr_b16 v[80:81], v128 offset:58432
	v_exp_f32_e32 v135, v126
	v_sub_u32_e32 v134, v115, v127
	v_cmp_lt_i32_e32 vcc, 0, v134
	s_waitcnt lgkmcnt(11)
	v_mfma_f32_32x32x16_bf16 v[32:47], v[32:35], v[48:51], 0
	v_cmp_lt_i32_e64 s[0:1], 27, v134
	s_waitcnt lgkmcnt(10)
	v_mfma_f32_32x32x16_bf16 v[32:47], v[214:217], v[52:55], v[32:47]
	s_waitcnt lgkmcnt(9)
	v_mfma_f32_32x32x16_bf16 v[32:47], v[210:213], v[56:59], v[32:47]
	s_waitcnt lgkmcnt(8)
	v_mfma_f32_32x32x16_bf16 v[32:47], v[130:133], v[60:63], v[32:47]
	s_nop 11
	v_min_f32_e64 v32, -v32, s60
	v_min_f32_e64 v33, -v33, s60
	v_exp_f32_e32 v32, v32
	v_min_f32_e64 v34, -v34, s60
	v_exp_f32_e32 v33, v33
	v_exp_f32_e32 v34, v34
	v_min_f32_e64 v35, -v35, s60
	v_exp_f32_e32 v130, v35
	v_add_f32_e32 v35, 1.0, v32
	v_add_f32_e32 v131, 1.0, v33
	v_rcp_f32_e32 v35, v35
	v_add_f32_e32 v132, 1.0, v34
	v_rcp_f32_e32 v131, v131
	v_min_f32_e64 v36, -v36, s60
	v_rcp_f32_e32 v132, v132
	v_exp_f32_e32 v36, v36
	v_add_f32_e32 v133, 1.0, v130
	v_rcp_f32_e32 v136, v133
	v_mul_f32_e32 v32, v32, v35
	v_mul_f32_e32 v133, v135, v35
	v_mul_f32_e32 v33, v33, v131
	v_mul_f32_e32 v137, v135, v131
	v_cndmask_b32_e32 v35, 1.0, v32, vcc
	v_cndmask_b32_e32 v138, 0, v133, vcc
	v_cmp_lt_i32_e32 vcc, 1, v134
	v_mul_f32_e32 v34, v34, v132
	v_mul_f32_e32 v32, v135, v132
	v_cndmask_b32_e32 v131, 1.0, v33, vcc
	v_cndmask_b32_e32 v137, 0, v137, vcc
	v_cmp_lt_i32_e32 vcc, 2, v134
	v_min_f32_e64 v39, -v39, s60
	v_cndmask_b32_e32 v33, 1.0, v34, vcc
	v_add_f32_e32 v34, 1.0, v36
	v_rcp_f32_e32 v34, v34
	v_cndmask_b32_e32 v139, 0, v32, vcc
	v_mul_f32_e32 v32, v130, v136
	v_cmp_lt_i32_e32 vcc, 3, v134
	v_exp_f32_e32 v39, v39
	v_cndmask_b32_e32 v133, 1.0, v32, vcc
	v_mul_f32_e32 v32, v135, v136
	v_cndmask_b32_e32 v136, 0, v32, vcc
	v_mul_f32_e32 v32, v36, v34
	v_min_f32_e64 v36, -v37, s60
	v_exp_f32_e32 v36, v36
	v_cmp_lt_i32_e32 vcc, 8, v134
	v_mul_f32_e32 v34, v135, v34
	v_cndmask_b32_e32 v140, 0, v34, vcc
	v_add_f32_e32 v34, 1.0, v36
	v_rcp_f32_e32 v34, v34
	v_min_f32_e64 v37, -v38, s60
	v_exp_f32_e32 v37, v37
	v_cndmask_b32_e32 v32, 1.0, v32, vcc
	v_mul_f32_e32 v36, v36, v34
	v_cmp_lt_i32_e32 vcc, 9, v134
	v_mul_f32_e32 v34, v135, v34
	v_min_f32_e64 v42, -v42, s60
	v_cndmask_b32_e32 v38, 1.0, v36, vcc
	v_add_f32_e32 v36, 1.0, v37
	v_rcp_f32_e32 v36, v36
	v_cndmask_b32_e32 v141, 0, v34, vcc
	v_cmp_lt_i32_e32 vcc, 10, v134
	v_exp_f32_e32 v42, v42
	v_mul_f32_e32 v34, v37, v36
	v_add_f32_e32 v37, 1.0, v39
	v_rcp_f32_e32 v37, v37
	v_cndmask_b32_e32 v142, 1.0, v34, vcc
	v_mul_f32_e32 v34, v135, v36
	v_cndmask_b32_e32 v143, 0, v34, vcc
	v_mul_f32_e32 v34, v39, v37
	v_cmp_lt_i32_e32 vcc, 11, v134
	v_min_f32_e64 v36, -v40, s60
	v_exp_f32_e32 v36, v36
	v_cndmask_b32_e32 v39, 1.0, v34, vcc
	v_mul_f32_e32 v34, v135, v37
	v_min_f32_e64 v37, -v41, s60
	v_exp_f32_e32 v37, v37
	v_cndmask_b32_e32 v40, 0, v34, vcc
	v_add_f32_e32 v34, 1.0, v36
	v_rcp_f32_e32 v34, v34
	v_add_f32_e32 v41, 1.0, v37
	v_rcp_f32_e32 v41, v41
	v_cmp_lt_i32_e32 vcc, 16, v134
	v_mul_f32_e32 v36, v36, v34
	v_mul_f32_e32 v34, v135, v34
	v_cndmask_b32_e32 v144, 0, v34, vcc
	v_mul_f32_e32 v34, v37, v41
	v_add_f32_e32 v37, 1.0, v42
	v_rcp_f32_e32 v37, v37
	v_cndmask_b32_e32 v36, 1.0, v36, vcc
	v_cmp_lt_i32_e32 vcc, 17, v134
	v_min_f32_e64 v45, -v45, s60
	v_cndmask_b32_e32 v145, 1.0, v34, vcc
	v_mul_f32_e32 v34, v135, v41
	v_cndmask_b32_e32 v41, 0, v34, vcc
	v_mul_f32_e32 v34, v42, v37
	v_cmp_lt_i32_e32 vcc, 18, v134
	v_min_f32_e64 v42, -v43, s60
	v_exp_f32_e32 v42, v42
	v_cndmask_b32_e32 v43, 1.0, v34, vcc
	v_mul_f32_e32 v34, v135, v37
	v_min_f32_e64 v37, -v44, s60
	v_exp_f32_e32 v37, v37
	v_cndmask_b32_e32 v146, 0, v34, vcc
	v_add_f32_e32 v34, 1.0, v42
	v_rcp_f32_e32 v34, v34
	v_add_f32_e32 v44, 1.0, v37
	v_rcp_f32_e32 v44, v44
	v_exp_f32_e32 v45, v45
	v_min_f32_e64 v46, -v46, s60
	v_min_f32_e64 v47, -v47, s60
	v_exp_f32_e32 v46, v46
	v_exp_f32_e32 v47, v47
	v_mul_f32_e32 v42, v42, v34
	v_cmp_lt_i32_e32 vcc, 19, v134
	v_mul_f32_e32 v34, v135, v34
	v_add_f32_e32 v130, 1.0, v46
	v_cndmask_b32_e32 v147, 0, v34, vcc
	v_mul_f32_e32 v34, v37, v44
	v_add_f32_e32 v37, 1.0, v45
	v_rcp_f32_e32 v37, v37
	v_add_f32_e32 v132, 1.0, v47
	v_rcp_f32_e32 v130, v130
	v_rcp_f32_e32 v132, v132
	v_cndmask_b32_e32 v42, 1.0, v42, vcc
	v_cmp_lt_i32_e32 vcc, 24, v134
	v_mul_f32_e32 v44, v135, v44
	v_mul_f32_e32 v45, v45, v37
	v_cndmask_b32_e32 v34, 1.0, v34, vcc
	v_cndmask_b32_e32 v44, 0, v44, vcc
	v_cmp_lt_i32_e32 vcc, 25, v134
	v_mul_f32_e32 v37, v135, v37
	v_mul_f32_e32 v46, v46, v130
	v_cndmask_b32_e32 v45, 1.0, v45, vcc
	v_cndmask_b32_e32 v37, 0, v37, vcc
	v_cmp_lt_i32_e32 vcc, 26, v134
	v_mul_f32_e32 v47, v47, v132
	v_cndmask_b32_e64 v47, 1.0, v47, s[0:1]
	v_cndmask_b32_e32 v46, 1.0, v46, vcc
	v_mul_f32_e32 v34, v34, v45
	v_mul_f32_e32 v134, v46, v47
	v_mul_f32_e32 v134, v34, v134
	v_mov_b32_e32 v148, v134
	s_nop 1
	v_permlane32_swap_b32_e32 v134, v148
	v_mul_f32_e32 v34, v135, v130
	v_cndmask_b32_e32 v149, 0, v34, vcc
	v_mul_f32_e32 v34, v135, v132
	v_cndmask_b32_e64 v34, 0, v34, s[0:1]
	s_waitcnt lgkmcnt(0)
	v_cndmask_b32_e64 v130, 1.0, v148, s[2:3]
	v_mul_f32_e32 v135, v34, v130
	v_mul_f32_e32 v34, v36, v145
	v_mul_f32_e32 v36, v43, v42
	v_mul_f32_e32 v36, v34, v36
	v_mul_f32_e32 v32, v32, v38
	v_mul_f32_e32 v34, v142, v39
	v_mov_b32_e32 v150, v36
	s_nop 1
	v_permlane32_swap_b32_e32 v36, v150
	v_mul_f32_e32 v34, v32, v34
	v_mul_f32_e32 v47, v47, v130
	v_mov_b32_e32 v130, v34
	s_nop 1
	v_permlane32_swap_b32_e32 v34, v130
	v_mul_f32_e32 v46, v46, v47
	v_mul_f32_e32 v32, v134, v148
	s_waitcnt lgkmcnt(1)
	v_mul_f32_e32 v132, v36, v150
	v_mul_f32_e32 v45, v45, v46
	v_mul_f32_e32 v46, v37, v46
	s_waitcnt lgkmcnt(0)
	v_cndmask_b32_e64 v134, 1.0, v130, s[2:3]
	v_pk_mul_f32 v[36:37], v[32:33], v[132:133]
	v_pk_mul_f32 v[34:35], v[34:35], v[130:131]
	v_mul_f32_e32 v132, v36, v134
	v_mul_f32_e32 v134, v39, v132
	v_mul_f32_e32 v142, v142, v134
	v_mul_f32_e32 v148, v38, v142
	v_pk_mul_f32 v[38:39], v[34:35], v[36:37]
	v_mov_b32_e32 v130, v39
	s_nop 1
	v_permlane32_swap_b32_e32 v39, v130
	v_mul_f32_e32 v37, v40, v132
	v_mul_f32_e32 v40, v143, v134
	v_mul_f32_e32 v36, v141, v142
	v_mul_f32_e32 v132, v140, v148
	s_waitcnt lgkmcnt(0)
	v_cndmask_b32_e64 v34, 1.0, v130, s[2:3]
	v_mul_f32_e32 v34, v38, v34
	v_mul_f32_e32 v35, v133, v34
	v_mul_f32_e32 v33, v33, v35
	v_mul_f32_e32 v131, v131, v33
	v_mul_f32_e32 v133, v136, v34
	v_mul_f32_e32 v35, v139, v35
	v_mul_f32_e32 v33, v137, v33
	v_mul_f32_e32 v34, v138, v131
	v_cvt_pk_bf16_f32 v34, v34, v33
	v_cvt_pk_bf16_f32 v35, v35, v133
	v_cvt_pk_bf16_f32 v36, v132, v36
	v_cvt_pk_bf16_f32 v37, v40, v37
	v_cndmask_b32_e64 v33, 1.0, v150, s[2:3]
	v_mul_f32_e32 v32, v32, v33
	v_mfma_f32_32x32x16_bf16 v[0:15], v[92:95], v[34:37], v[0:15]
	v_mul_f32_e32 v33, v42, v32
	v_mul_f32_e32 v42, v43, v33
	v_mul_f32_e32 v43, v145, v42
	v_mul_f32_e32 v47, v149, v47
	v_mul_f32_e32 v40, v44, v45
	v_mul_f32_e32 v44, v147, v32
	v_mul_f32_e32 v33, v146, v33
	v_mfma_f32_32x32x16_bf16 v[16:31], v[88:91], v[34:37], v[16:31]
	v_mul_f32_e32 v32, v41, v42
	v_mul_f32_e32 v34, v144, v43
	v_cvt_pk_bf16_f32 v32, v34, v32
	v_cvt_pk_bf16_f32 v33, v33, v44
	v_cvt_pk_bf16_f32 v34, v40, v46
	v_cvt_pk_bf16_f32 v35, v47, v135
	v_mul_f32_e32 v36, v39, v130
	v_mul_f32_e32 v36, v38, v36
	v_mfma_f32_32x32x16_bf16 v[0:15], v[84:87], v[32:35], v[0:15]
	v_log_f32_e32 v36, v36
	s_nop 0
	v_add_f32_e32 v126, v126, v36
	v_mfma_f32_32x32x16_bf16 v[16:31], v[80:83], v[32:35], v[16:31]
	s_branch .LBB0_364
.Lsbq_nomask_3:
	ds_read_b128 v[32:35], v129 offset:13824
	ds_read_b128 v[214:217], v129 offset:13856
	ds_read_b128 v[210:213], v129 offset:13888
	ds_read_b128 v[130:133], v129 offset:13920
	ds_read_b64_tr_b16 v[92:93], v128 offset:55296
	ds_read_b64_tr_b16 v[94:95], v128 offset:56832
	ds_read_b64_tr_b16 v[90:91], v128 offset:56896
	ds_read_b64_tr_b16 v[88:89], v128 offset:55360
	ds_read_b64_tr_b16 v[84:85], v128 offset:58368
	ds_read_b64_tr_b16 v[86:87], v128 offset:59904
	ds_read_b64_tr_b16 v[82:83], v128 offset:59968
	ds_read_b64_tr_b16 v[80:81], v128 offset:58432
	v_exp_f32_e32 v135, v126
	s_waitcnt lgkmcnt(11)
	v_mfma_f32_32x32x16_bf16 v[32:47], v[32:35], v[48:51], 0
	s_waitcnt lgkmcnt(10)
	v_mfma_f32_32x32x16_bf16 v[32:47], v[214:217], v[52:55], v[32:47]
	s_waitcnt lgkmcnt(9)
	v_mfma_f32_32x32x16_bf16 v[32:47], v[210:213], v[56:59], v[32:47]
	s_waitcnt lgkmcnt(8)
	v_mfma_f32_32x32x16_bf16 v[32:47], v[130:133], v[60:63], v[32:47]
	s_nop 11
	v_min_f32_e64 v32, -v32, s60
	v_min_f32_e64 v33, -v33, s60
	v_exp_f32_e32 v32, v32
	v_min_f32_e64 v34, -v34, s60
	v_exp_f32_e32 v33, v33
	v_exp_f32_e32 v34, v34
	v_min_f32_e64 v35, -v35, s60
	v_exp_f32_e32 v130, v35
	v_add_f32_e32 v35, 1.0, v32
	v_add_f32_e32 v131, 1.0, v33
	v_rcp_f32_e32 v35, v35
	v_add_f32_e32 v132, 1.0, v34
	v_rcp_f32_e32 v131, v131
	v_min_f32_e64 v36, -v36, s60
	v_rcp_f32_e32 v132, v132
	v_exp_f32_e32 v36, v36
	v_add_f32_e32 v133, 1.0, v130
	v_rcp_f32_e32 v136, v133
	v_mul_f32_e32 v32, v32, v35
	v_mul_f32_e32 v138, v135, v35
	v_mul_f32_e32 v33, v33, v131
	v_mul_f32_e32 v137, v135, v131
	v_mov_b32_e32 v35, v32
	v_mul_f32_e32 v34, v34, v132
	v_mul_f32_e32 v139, v135, v132
	v_mov_b32_e32 v131, v33
	v_min_f32_e64 v39, -v39, s60
	v_mov_b32_e32 v33, v34
	v_add_f32_e32 v34, 1.0, v36
	v_rcp_f32_e32 v34, v34
	v_mul_f32_e32 v133, v130, v136
	v_exp_f32_e32 v39, v39
	v_mul_f32_e32 v136, v135, v136
	v_mul_f32_e32 v32, v36, v34
	v_min_f32_e64 v36, -v37, s60
	v_exp_f32_e32 v36, v36
	v_mul_f32_e32 v140, v135, v34
	v_add_f32_e32 v34, 1.0, v36
	v_rcp_f32_e32 v34, v34
	v_min_f32_e64 v37, -v38, s60
	v_exp_f32_e32 v37, v37
	v_mul_f32_e32 v38, v36, v34
	v_mul_f32_e32 v141, v135, v34
	v_min_f32_e64 v42, -v42, s60
	v_add_f32_e32 v36, 1.0, v37
	v_rcp_f32_e32 v36, v36
	v_exp_f32_e32 v42, v42
	v_mul_f32_e32 v142, v37, v36
	v_add_f32_e32 v37, 1.0, v39
	v_rcp_f32_e32 v37, v37
	v_mul_f32_e32 v143, v135, v36
	v_mul_f32_e32 v39, v39, v37
	v_min_f32_e64 v36, -v40, s60
	v_exp_f32_e32 v36, v36
	v_mul_f32_e32 v40, v135, v37
	v_min_f32_e64 v37, -v41, s60
	v_exp_f32_e32 v37, v37
	v_add_f32_e32 v34, 1.0, v36
	v_rcp_f32_e32 v34, v34
	v_add_f32_e32 v41, 1.0, v37
	v_rcp_f32_e32 v41, v41
	v_mul_f32_e32 v36, v36, v34
	v_mul_f32_e32 v144, v135, v34
	v_mul_f32_e32 v145, v37, v41
	v_add_f32_e32 v37, 1.0, v42
	v_rcp_f32_e32 v37, v37
	v_min_f32_e64 v45, -v45, s60
	v_mul_f32_e32 v41, v135, v41
	v_mul_f32_e32 v34, v42, v37
	v_min_f32_e64 v42, -v43, s60
	v_exp_f32_e32 v42, v42
	v_mov_b32_e32 v43, v34
	v_mul_f32_e32 v146, v135, v37
	v_min_f32_e64 v37, -v44, s60
	v_exp_f32_e32 v37, v37
	v_add_f32_e32 v34, 1.0, v42
	v_rcp_f32_e32 v34, v34
	v_add_f32_e32 v44, 1.0, v37
	v_rcp_f32_e32 v44, v44
	v_exp_f32_e32 v45, v45
	v_min_f32_e64 v46, -v46, s60
	v_min_f32_e64 v47, -v47, s60
	v_exp_f32_e32 v46, v46
	v_exp_f32_e32 v47, v47
	v_mul_f32_e32 v42, v42, v34
	v_mul_f32_e32 v147, v135, v34
	v_add_f32_e32 v130, 1.0, v46
	v_mul_f32_e32 v34, v37, v44
	v_add_f32_e32 v37, 1.0, v45
	v_rcp_f32_e32 v37, v37
	v_add_f32_e32 v132, 1.0, v47
	v_rcp_f32_e32 v130, v130
	v_rcp_f32_e32 v132, v132
	v_mul_f32_e32 v44, v135, v44
	v_mul_f32_e32 v45, v45, v37
	v_mul_f32_e32 v37, v135, v37
	v_mul_f32_e32 v46, v46, v130
	v_mul_f32_e32 v47, v47, v132
	v_mul_f32_e32 v34, v34, v45
	v_mul_f32_e32 v134, v46, v47
	v_mul_f32_e32 v134, v34, v134
	v_mov_b32_e32 v148, v134
	s_nop 1
	v_permlane32_swap_b32_e32 v134, v148
	v_mul_f32_e32 v149, v135, v130
	v_mul_f32_e32 v34, v135, v132
	s_waitcnt lgkmcnt(0)
; __device__ __forceinline__ void sb_unit(const Frame& F, int b, int hd, int qi, int dry) {
;     ...
;             float run = C;
;             if (!meta && key0 + 96 < tqw + 31) SB_HALF(96);
;             if (!meta && key0 + 64 < tqw + 31 && __any(run >= SB_DEAD)) SB_HALF(64);
	v_cndmask_b32_e64 v130, 1.0, v148, s[2:3]
	v_mul_f32_e32 v135, v34, v130
	v_mul_f32_e32 v34, v36, v145
	v_mul_f32_e32 v36, v43, v42
	v_mul_f32_e32 v36, v34, v36
	v_mul_f32_e32 v32, v32, v38
	v_mul_f32_e32 v34, v142, v39
	v_mov_b32_e32 v150, v36
	s_nop 1
	v_permlane32_swap_b32_e32 v36, v150
	v_mul_f32_e32 v34, v32, v34
	v_mul_f32_e32 v47, v47, v130
	v_mov_b32_e32 v130, v34
	s_nop 1
	v_permlane32_swap_b32_e32 v34, v130
	v_mul_f32_e32 v46, v46, v47
	v_mul_f32_e32 v32, v134, v148
	s_waitcnt lgkmcnt(1)
	v_mul_f32_e32 v132, v36, v150
	v_mul_f32_e32 v45, v45, v46
	v_mul_f32_e32 v46, v37, v46
	s_waitcnt lgkmcnt(0)
	v_cndmask_b32_e64 v134, 1.0, v130, s[2:3]
	v_pk_mul_f32 v[36:37], v[32:33], v[132:133]
	v_pk_mul_f32 v[34:35], v[34:35], v[130:131]
	v_mul_f32_e32 v132, v36, v134
	v_mul_f32_e32 v134, v39, v132
	v_mul_f32_e32 v142, v142, v134
	v_mul_f32_e32 v148, v38, v142
	v_pk_mul_f32 v[38:39], v[34:35], v[36:37]
	v_mov_b32_e32 v130, v39
	s_nop 1
	v_permlane32_swap_b32_e32 v39, v130
	v_mul_f32_e32 v37, v40, v132
	v_mul_f32_e32 v40, v143, v134
	v_mul_f32_e32 v36, v141, v142
	v_mul_f32_e32 v132, v140, v148
	s_waitcnt lgkmcnt(0)
	v_cndmask_b32_e64 v34, 1.0, v130, s[2:3]
	v_mul_f32_e32 v34, v38, v34
	v_mul_f32_e32 v35, v133, v34
	v_mul_f32_e32 v33, v33, v35
	v_mul_f32_e32 v131, v131, v33
	v_mul_f32_e32 v133, v136, v34
	v_mul_f32_e32 v35, v139, v35
	v_mul_f32_e32 v33, v137, v33
	v_mul_f32_e32 v34, v138, v131
	v_cvt_pk_bf16_f32 v34, v34, v33
	v_cvt_pk_bf16_f32 v35, v35, v133
	v_cvt_pk_bf16_f32 v36, v132, v36
	v_cvt_pk_bf16_f32 v37, v40, v37
	v_cndmask_b32_e64 v33, 1.0, v150, s[2:3]
	v_mul_f32_e32 v32, v32, v33
	v_mfma_f32_32x32x16_bf16 v[0:15], v[92:95], v[34:37], v[0:15]
	v_mul_f32_e32 v33, v42, v32
	v_mul_f32_e32 v42, v43, v33
	v_mul_f32_e32 v43, v145, v42
	v_mul_f32_e32 v47, v149, v47
	v_mul_f32_e32 v40, v44, v45
	v_mul_f32_e32 v44, v147, v32
	v_mul_f32_e32 v33, v146, v33
	v_mfma_f32_32x32x16_bf16 v[16:31], v[88:91], v[34:37], v[16:31]
	v_mul_f32_e32 v32, v41, v42
	v_mul_f32_e32 v34, v144, v43
	v_cvt_pk_bf16_f32 v32, v34, v32
	v_cvt_pk_bf16_f32 v33, v33, v44
	v_cvt_pk_bf16_f32 v34, v40, v46
	v_cvt_pk_bf16_f32 v35, v47, v135
	v_mul_f32_e32 v36, v39, v130
	v_mul_f32_e32 v36, v38, v36
	v_mfma_f32_32x32x16_bf16 v[0:15], v[84:87], v[32:35], v[0:15]
	v_log_f32_e32 v36, v36
	s_nop 0
	v_add_f32_e32 v126, v126, v36
	v_mfma_f32_32x32x16_bf16 v[16:31], v[80:83], v[32:35], v[16:31]
.LBB0_364:
	s_or_b32 s0, s34, 33
	s_cmp_ge_i32 s0, s25
	s_cselect_b64 s[0:1], -1, 0
	s_or_b64 s[0:1], s[18:19], s[0:1]
	s_and_b64 vcc, exec, s[0:1]
	s_cbranch_vccnz .LBB0_367
	v_cmp_le_f32_e32 vcc, s22, v126
	s_cbranch_vccz .LBB0_367
	s_add_i32 s61, s34, 96
	s_cmp_le_i32 s61, s25
	s_cbranch_scc1 .Lsbq_nomask_2
	ds_read_b128 v[32:35], v129 offset:9216
	ds_read_b128 v[214:217], v129 offset:9248
	ds_read_b128 v[210:213], v129 offset:9280
	ds_read_b128 v[130:133], v129 offset:9312
	ds_read_b64_tr_b16 v[92:93], v128 offset:49152
	ds_read_b64_tr_b16 v[94:95], v128 offset:50688
	ds_read_b64_tr_b16 v[90:91], v128 offset:50752
	ds_read_b64_tr_b16 v[88:89], v128 offset:49216
	ds_read_b64_tr_b16 v[84:85], v128 offset:52224
	ds_read_b64_tr_b16 v[86:87], v128 offset:53760
	ds_read_b64_tr_b16 v[82:83], v128 offset:53824
	ds_read_b64_tr_b16 v[80:81], v128 offset:52288
	v_exp_f32_e32 v135, v126
	v_sub_u32_e32 v134, v124, v127
	v_cmp_lt_i32_e32 vcc, 0, v134
	s_waitcnt lgkmcnt(11)
	v_mfma_f32_32x32x16_bf16 v[32:47], v[32:35], v[48:51], 0
	v_cmp_lt_i32_e64 s[0:1], 27, v134
	s_waitcnt lgkmcnt(10)
	v_mfma_f32_32x32x16_bf16 v[32:47], v[214:217], v[52:55], v[32:47]
	s_waitcnt lgkmcnt(9)
	v_mfma_f32_32x32x16_bf16 v[32:47], v[210:213], v[56:59], v[32:47]
	s_waitcnt lgkmcnt(8)
	v_mfma_f32_32x32x16_bf16 v[32:47], v[130:133], v[60:63], v[32:47]
	s_nop 11
	v_min_f32_e64 v32, -v32, s60
	v_min_f32_e64 v33, -v33, s60
	v_exp_f32_e32 v32, v32
	v_min_f32_e64 v34, -v34, s60
	v_exp_f32_e32 v33, v33
	v_exp_f32_e32 v34, v34
	v_min_f32_e64 v35, -v35, s60
	v_exp_f32_e32 v130, v35
	v_add_f32_e32 v35, 1.0, v32
	v_add_f32_e32 v131, 1.0, v33
	v_rcp_f32_e32 v35, v35
	v_add_f32_e32 v132, 1.0, v34
	v_rcp_f32_e32 v131, v131
	v_min_f32_e64 v36, -v36, s60
	v_rcp_f32_e32 v132, v132
	v_exp_f32_e32 v36, v36
	v_add_f32_e32 v133, 1.0, v130
	v_rcp_f32_e32 v136, v133
	v_mul_f32_e32 v32, v32, v35
	v_mul_f32_e32 v133, v135, v35
	v_mul_f32_e32 v33, v33, v131
	v_mul_f32_e32 v137, v135, v131
	v_cndmask_b32_e32 v35, 1.0, v32, vcc
	v_cndmask_b32_e32 v138, 0, v133, vcc
	v_cmp_lt_i32_e32 vcc, 1, v134
	v_mul_f32_e32 v34, v34, v132
	v_mul_f32_e32 v32, v135, v132
	v_cndmask_b32_e32 v131, 1.0, v33, vcc
	v_cndmask_b32_e32 v137, 0, v137, vcc
	v_cmp_lt_i32_e32 vcc, 2, v134
	v_min_f32_e64 v39, -v39, s60
	v_cndmask_b32_e32 v33, 1.0, v34, vcc
	v_add_f32_e32 v34, 1.0, v36
	v_rcp_f32_e32 v34, v34
	v_cndmask_b32_e32 v139, 0, v32, vcc
	v_mul_f32_e32 v32, v130, v136
	v_cmp_lt_i32_e32 vcc, 3, v134
	v_exp_f32_e32 v39, v39
	v_cndmask_b32_e32 v133, 1.0, v32, vcc
	v_mul_f32_e32 v32, v135, v136
	v_cndmask_b32_e32 v136, 0, v32, vcc
	v_mul_f32_e32 v32, v36, v34
	v_min_f32_e64 v36, -v37, s60
	v_exp_f32_e32 v36, v36
	v_cmp_lt_i32_e32 vcc, 8, v134
	v_mul_f32_e32 v34, v135, v34
	v_cndmask_b32_e32 v140, 0, v34, vcc
	v_add_f32_e32 v34, 1.0, v36
	v_rcp_f32_e32 v34, v34
	v_min_f32_e64 v37, -v38, s60
	v_exp_f32_e32 v37, v37
	v_cndmask_b32_e32 v32, 1.0, v32, vcc
	v_mul_f32_e32 v36, v36, v34
	v_cmp_lt_i32_e32 vcc, 9, v134
	v_mul_f32_e32 v34, v135, v34
	v_min_f32_e64 v42, -v42, s60
	v_cndmask_b32_e32 v38, 1.0, v36, vcc
	v_add_f32_e32 v36, 1.0, v37
	v_rcp_f32_e32 v36, v36
	v_cndmask_b32_e32 v141, 0, v34, vcc
	v_cmp_lt_i32_e32 vcc, 10, v134
	v_exp_f32_e32 v42, v42
	v_mul_f32_e32 v34, v37, v36
	v_add_f32_e32 v37, 1.0, v39
	v_rcp_f32_e32 v37, v37
	v_cndmask_b32_e32 v142, 1.0, v34, vcc
	v_mul_f32_e32 v34, v135, v36
	v_cndmask_b32_e32 v143, 0, v34, vcc
	v_mul_f32_e32 v34, v39, v37
	v_cmp_lt_i32_e32 vcc, 11, v134
	v_min_f32_e64 v36, -v40, s60
	v_exp_f32_e32 v36, v36
	v_cndmask_b32_e32 v39, 1.0, v34, vcc
	v_mul_f32_e32 v34, v135, v37
	v_min_f32_e64 v37, -v41, s60
	v_exp_f32_e32 v37, v37
	v_cndmask_b32_e32 v40, 0, v34, vcc
	v_add_f32_e32 v34, 1.0, v36
	v_rcp_f32_e32 v34, v34
	v_add_f32_e32 v41, 1.0, v37
	v_rcp_f32_e32 v41, v41
	v_cmp_lt_i32_e32 vcc, 16, v134
	v_mul_f32_e32 v36, v36, v34
	v_mul_f32_e32 v34, v135, v34
	v_cndmask_b32_e32 v144, 0, v34, vcc
	v_mul_f32_e32 v34, v37, v41
	v_add_f32_e32 v37, 1.0, v42
	v_rcp_f32_e32 v37, v37
	v_cndmask_b32_e32 v36, 1.0, v36, vcc
	v_cmp_lt_i32_e32 vcc, 17, v134
	v_min_f32_e64 v45, -v45, s60
	v_cndmask_b32_e32 v145, 1.0, v34, vcc
	v_mul_f32_e32 v34, v135, v41
	v_cndmask_b32_e32 v41, 0, v34, vcc
	v_mul_f32_e32 v34, v42, v37
	v_cmp_lt_i32_e32 vcc, 18, v134
	v_min_f32_e64 v42, -v43, s60
	v_exp_f32_e32 v42, v42
	v_cndmask_b32_e32 v43, 1.0, v34, vcc
	v_mul_f32_e32 v34, v135, v37
	v_min_f32_e64 v37, -v44, s60
	v_exp_f32_e32 v37, v37
	v_cndmask_b32_e32 v146, 0, v34, vcc
	v_add_f32_e32 v34, 1.0, v42
	v_rcp_f32_e32 v34, v34
	v_add_f32_e32 v44, 1.0, v37
	v_rcp_f32_e32 v44, v44
	v_exp_f32_e32 v45, v45
	v_min_f32_e64 v46, -v46, s60
	v_min_f32_e64 v47, -v47, s60
	v_exp_f32_e32 v46, v46
	v_exp_f32_e32 v47, v47
	v_mul_f32_e32 v42, v42, v34
	v_cmp_lt_i32_e32 vcc, 19, v134
	v_mul_f32_e32 v34, v135, v34
	v_add_f32_e32 v130, 1.0, v46
	v_cndmask_b32_e32 v147, 0, v34, vcc
	v_mul_f32_e32 v34, v37, v44
	v_add_f32_e32 v37, 1.0, v45
	v_rcp_f32_e32 v37, v37
	v_add_f32_e32 v132, 1.0, v47
	v_rcp_f32_e32 v130, v130
	v_rcp_f32_e32 v132, v132
	v_cndmask_b32_e32 v42, 1.0, v42, vcc
	v_cmp_lt_i32_e32 vcc, 24, v134
	v_mul_f32_e32 v44, v135, v44
	v_mul_f32_e32 v45, v45, v37
	v_cndmask_b32_e32 v34, 1.0, v34, vcc
	v_cndmask_b32_e32 v44, 0, v44, vcc
	v_cmp_lt_i32_e32 vcc, 25, v134
	v_mul_f32_e32 v37, v135, v37
	v_mul_f32_e32 v46, v46, v130
	v_cndmask_b32_e32 v45, 1.0, v45, vcc
	v_cndmask_b32_e32 v37, 0, v37, vcc
	v_cmp_lt_i32_e32 vcc, 26, v134
	v_mul_f32_e32 v47, v47, v132
	v_cndmask_b32_e64 v47, 1.0, v47, s[0:1]
	v_cndmask_b32_e32 v46, 1.0, v46, vcc
	v_mul_f32_e32 v34, v34, v45
	v_mul_f32_e32 v134, v46, v47
	v_mul_f32_e32 v134, v34, v134
	v_mov_b32_e32 v148, v134
	s_nop 1
	v_permlane32_swap_b32_e32 v134, v148
	v_mul_f32_e32 v34, v135, v130
	v_cndmask_b32_e32 v149, 0, v34, vcc
	v_mul_f32_e32 v34, v135, v132
	v_cndmask_b32_e64 v34, 0, v34, s[0:1]
	s_waitcnt lgkmcnt(0)
	v_cndmask_b32_e64 v130, 1.0, v148, s[2:3]
	v_mul_f32_e32 v135, v34, v130
	v_mul_f32_e32 v34, v36, v145
	v_mul_f32_e32 v36, v43, v42
	v_mul_f32_e32 v36, v34, v36
	v_mul_f32_e32 v32, v32, v38
	v_mul_f32_e32 v34, v142, v39
	v_mov_b32_e32 v150, v36
	s_nop 1
	v_permlane32_swap_b32_e32 v36, v150
	v_mul_f32_e32 v34, v32, v34
	v_mul_f32_e32 v47, v47, v130
	v_mov_b32_e32 v130, v34
	s_nop 1
	v_permlane32_swap_b32_e32 v34, v130
	v_mul_f32_e32 v46, v46, v47
	v_mul_f32_e32 v32, v134, v148
	s_waitcnt lgkmcnt(1)
	v_mul_f32_e32 v132, v36, v150
	v_mul_f32_e32 v45, v45, v46
	v_mul_f32_e32 v46, v37, v46
	s_waitcnt lgkmcnt(0)
	v_cndmask_b32_e64 v134, 1.0, v130, s[2:3]
	v_pk_mul_f32 v[36:37], v[32:33], v[132:133]
	v_pk_mul_f32 v[34:35], v[34:35], v[130:131]
	v_mul_f32_e32 v132, v36, v134
	v_mul_f32_e32 v134, v39, v132
	v_mul_f32_e32 v142, v142, v134
	v_mul_f32_e32 v148, v38, v142
	v_pk_mul_f32 v[38:39], v[34:35], v[36:37]
	v_mov_b32_e32 v130, v39
	s_nop 1
	v_permlane32_swap_b32_e32 v39, v130
	v_mul_f32_e32 v37, v40, v132
	v_mul_f32_e32 v40, v143, v134
	v_mul_f32_e32 v36, v141, v142
	v_mul_f32_e32 v132, v140, v148
	s_waitcnt lgkmcnt(0)
	v_cndmask_b32_e64 v34, 1.0, v130, s[2:3]
	v_mul_f32_e32 v34, v38, v34
	v_mul_f32_e32 v35, v133, v34
	v_mul_f32_e32 v33, v33, v35
	v_mul_f32_e32 v131, v131, v33
	v_mul_f32_e32 v133, v136, v34
	v_mul_f32_e32 v35, v139, v35
	v_mul_f32_e32 v33, v137, v33
	v_mul_f32_e32 v34, v138, v131
	v_cvt_pk_bf16_f32 v34, v34, v33
	v_cvt_pk_bf16_f32 v35, v35, v133
	v_cvt_pk_bf16_f32 v36, v132, v36
	v_cvt_pk_bf16_f32 v37, v40, v37
	v_cndmask_b32_e64 v33, 1.0, v150, s[2:3]
	v_mul_f32_e32 v32, v32, v33
	v_mfma_f32_32x32x16_bf16 v[0:15], v[92:95], v[34:37], v[0:15]
	v_mul_f32_e32 v33, v42, v32
	v_mul_f32_e32 v42, v43, v33
	v_mul_f32_e32 v43, v145, v42
	v_mul_f32_e32 v47, v149, v47
	v_mul_f32_e32 v40, v44, v45
	v_mul_f32_e32 v44, v147, v32
	v_mul_f32_e32 v33, v146, v33
	v_mfma_f32_32x32x16_bf16 v[16:31], v[88:91], v[34:37], v[16:31]
	v_mul_f32_e32 v32, v41, v42
	v_mul_f32_e32 v34, v144, v43
	v_cvt_pk_bf16_f32 v32, v34, v32
	v_cvt_pk_bf16_f32 v33, v33, v44
	v_cvt_pk_bf16_f32 v34, v40, v46
	v_cvt_pk_bf16_f32 v35, v47, v135
	v_mul_f32_e32 v36, v39, v130
	v_mul_f32_e32 v36, v38, v36
	v_mfma_f32_32x32x16_bf16 v[0:15], v[84:87], v[32:35], v[0:15]
	v_log_f32_e32 v36, v36
	s_nop 0
	v_add_f32_e32 v126, v126, v36
	v_mfma_f32_32x32x16_bf16 v[16:31], v[80:83], v[32:35], v[16:31]
	s_branch .LBB0_367
.Lsbq_nomask_2:
	ds_read_b128 v[32:35], v129 offset:9216
	ds_read_b128 v[214:217], v129 offset:9248
	ds_read_b128 v[210:213], v129 offset:9280
	ds_read_b128 v[130:133], v129 offset:9312
	ds_read_b64_tr_b16 v[92:93], v128 offset:49152
	ds_read_b64_tr_b16 v[94:95], v128 offset:50688
	ds_read_b64_tr_b16 v[90:91], v128 offset:50752
	ds_read_b64_tr_b16 v[88:89], v128 offset:49216
	ds_read_b64_tr_b16 v[84:85], v128 offset:52224
	ds_read_b64_tr_b16 v[86:87], v128 offset:53760
	ds_read_b64_tr_b16 v[82:83], v128 offset:53824
	ds_read_b64_tr_b16 v[80:81], v128 offset:52288
	v_exp_f32_e32 v135, v126
	s_waitcnt lgkmcnt(11)
	v_mfma_f32_32x32x16_bf16 v[32:47], v[32:35], v[48:51], 0
	s_waitcnt lgkmcnt(10)
	v_mfma_f32_32x32x16_bf16 v[32:47], v[214:217], v[52:55], v[32:47]
	s_waitcnt lgkmcnt(9)
	v_mfma_f32_32x32x16_bf16 v[32:47], v[210:213], v[56:59], v[32:47]
	s_waitcnt lgkmcnt(8)
	v_mfma_f32_32x32x16_bf16 v[32:47], v[130:133], v[60:63], v[32:47]
	s_nop 11
	v_min_f32_e64 v32, -v32, s60
	v_min_f32_e64 v33, -v33, s60
	v_exp_f32_e32 v32, v32
	v_min_f32_e64 v34, -v34, s60
	v_exp_f32_e32 v33, v33
	v_exp_f32_e32 v34, v34
	v_min_f32_e64 v35, -v35, s60
	v_exp_f32_e32 v130, v35
	v_add_f32_e32 v35, 1.0, v32
	v_add_f32_e32 v131, 1.0, v33
	v_rcp_f32_e32 v35, v35
	v_add_f32_e32 v132, 1.0, v34
	v_rcp_f32_e32 v131, v131
	v_min_f32_e64 v36, -v36, s60
	v_rcp_f32_e32 v132, v132
	v_exp_f32_e32 v36, v36
	v_add_f32_e32 v133, 1.0, v130
	v_rcp_f32_e32 v136, v133
	v_mul_f32_e32 v32, v32, v35
	v_mul_f32_e32 v138, v135, v35
	v_mul_f32_e32 v33, v33, v131
	v_mul_f32_e32 v137, v135, v131
	v_mov_b32_e32 v35, v32
	v_mul_f32_e32 v34, v34, v132
	v_mul_f32_e32 v139, v135, v132
	v_mov_b32_e32 v131, v33
	v_min_f32_e64 v39, -v39, s60
	v_mov_b32_e32 v33, v34
	v_add_f32_e32 v34, 1.0, v36
	v_rcp_f32_e32 v34, v34
	v_mul_f32_e32 v133, v130, v136
	v_exp_f32_e32 v39, v39
	v_mul_f32_e32 v136, v135, v136
	v_mul_f32_e32 v32, v36, v34
	v_min_f32_e64 v36, -v37, s60
	v_exp_f32_e32 v36, v36
	v_mul_f32_e32 v140, v135, v34
	v_add_f32_e32 v34, 1.0, v36
	v_rcp_f32_e32 v34, v34
	v_min_f32_e64 v37, -v38, s60
	v_exp_f32_e32 v37, v37
	v_mul_f32_e32 v38, v36, v34
	v_mul_f32_e32 v141, v135, v34
	v_min_f32_e64 v42, -v42, s60
	v_add_f32_e32 v36, 1.0, v37
	v_rcp_f32_e32 v36, v36
	v_exp_f32_e32 v42, v42
	v_mul_f32_e32 v142, v37, v36
	v_add_f32_e32 v37, 1.0, v39
	v_rcp_f32_e32 v37, v37
	v_mul_f32_e32 v143, v135, v36
	v_mul_f32_e32 v39, v39, v37
	v_min_f32_e64 v36, -v40, s60
	v_exp_f32_e32 v36, v36
	v_mul_f32_e32 v40, v135, v37
	v_min_f32_e64 v37, -v41, s60
	v_exp_f32_e32 v37, v37
	v_add_f32_e32 v34, 1.0, v36
	v_rcp_f32_e32 v34, v34
	v_add_f32_e32 v41, 1.0, v37
	v_rcp_f32_e32 v41, v41
	v_mul_f32_e32 v36, v36, v34
	v_mul_f32_e32 v144, v135, v34
	v_mul_f32_e32 v145, v37, v41
	v_add_f32_e32 v37, 1.0, v42
	v_rcp_f32_e32 v37, v37
	v_min_f32_e64 v45, -v45, s60
	v_mul_f32_e32 v41, v135, v41
	v_mul_f32_e32 v34, v42, v37
	v_min_f32_e64 v42, -v43, s60
	v_exp_f32_e32 v42, v42
	v_mov_b32_e32 v43, v34
	v_mul_f32_e32 v146, v135, v37
	v_min_f32_e64 v37, -v44, s60
	v_exp_f32_e32 v37, v37
	v_add_f32_e32 v34, 1.0, v42
	v_rcp_f32_e32 v34, v34
	v_add_f32_e32 v44, 1.0, v37
	v_rcp_f32_e32 v44, v44
	v_exp_f32_e32 v45, v45
	v_min_f32_e64 v46, -v46, s60
	v_min_f32_e64 v47, -v47, s60
	v_exp_f32_e32 v46, v46
	v_exp_f32_e32 v47, v47
	v_mul_f32_e32 v42, v42, v34
	v_mul_f32_e32 v147, v135, v34
	v_add_f32_e32 v130, 1.0, v46
	v_mul_f32_e32 v34, v37, v44
	v_add_f32_e32 v37, 1.0, v45
	v_rcp_f32_e32 v37, v37
	v_add_f32_e32 v132, 1.0, v47
	v_rcp_f32_e32 v130, v130
	v_rcp_f32_e32 v132, v132
	v_mul_f32_e32 v44, v135, v44
	v_mul_f32_e32 v45, v45, v37
	v_mul_f32_e32 v37, v135, v37
	v_mul_f32_e32 v46, v46, v130
	v_mul_f32_e32 v47, v47, v132
	v_mul_f32_e32 v34, v34, v45
	v_mul_f32_e32 v134, v46, v47
	v_mul_f32_e32 v134, v34, v134
	v_mov_b32_e32 v148, v134
	s_nop 1
	v_permlane32_swap_b32_e32 v134, v148
	v_mul_f32_e32 v149, v135, v130
	v_mul_f32_e32 v34, v135, v132
	s_waitcnt lgkmcnt(0)
	v_cndmask_b32_e64 v130, 1.0, v148, s[2:3]
	v_mul_f32_e32 v135, v34, v130
	v_mul_f32_e32 v34, v36, v145
	v_mul_f32_e32 v36, v43, v42
	v_mul_f32_e32 v36, v34, v36
	v_mul_f32_e32 v32, v32, v38
	v_mul_f32_e32 v34, v142, v39
	v_mov_b32_e32 v150, v36
	s_nop 1
	v_permlane32_swap_b32_e32 v36, v150
	v_mul_f32_e32 v34, v32, v34
	v_mul_f32_e32 v47, v47, v130
	v_mov_b32_e32 v130, v34
	s_nop 1
	v_permlane32_swap_b32_e32 v34, v130
	v_mul_f32_e32 v46, v46, v47
	v_mul_f32_e32 v32, v134, v148
	s_waitcnt lgkmcnt(1)
	v_mul_f32_e32 v132, v36, v150
	v_mul_f32_e32 v45, v45, v46
	v_mul_f32_e32 v46, v37, v46
	s_waitcnt lgkmcnt(0)
	v_cndmask_b32_e64 v134, 1.0, v130, s[2:3]
	v_pk_mul_f32 v[36:37], v[32:33], v[132:133]
	v_pk_mul_f32 v[34:35], v[34:35], v[130:131]
	v_mul_f32_e32 v132, v36, v134
	v_mul_f32_e32 v134, v39, v132
	v_mul_f32_e32 v142, v142, v134
	v_mul_f32_e32 v148, v38, v142
	v_pk_mul_f32 v[38:39], v[34:35], v[36:37]
	v_mov_b32_e32 v130, v39
	s_nop 1
	v_permlane32_swap_b32_e32 v39, v130
	v_mul_f32_e32 v37, v40, v132
	v_mul_f32_e32 v40, v143, v134
	v_mul_f32_e32 v36, v141, v142
	v_mul_f32_e32 v132, v140, v148
	s_waitcnt lgkmcnt(0)
	v_cndmask_b32_e64 v34, 1.0, v130, s[2:3]
	v_mul_f32_e32 v34, v38, v34
	v_mul_f32_e32 v35, v133, v34
	v_mul_f32_e32 v33, v33, v35
	v_mul_f32_e32 v131, v131, v33
	v_mul_f32_e32 v133, v136, v34
	v_mul_f32_e32 v35, v139, v35
	v_mul_f32_e32 v33, v137, v33
	v_mul_f32_e32 v34, v138, v131
	v_cvt_pk_bf16_f32 v34, v34, v33
	v_cvt_pk_bf16_f32 v35, v35, v133
	v_cvt_pk_bf16_f32 v36, v132, v36
	v_cvt_pk_bf16_f32 v37, v40, v37
	v_cndmask_b32_e64 v33, 1.0, v150, s[2:3]
	v_mul_f32_e32 v32, v32, v33
	v_mfma_f32_32x32x16_bf16 v[0:15], v[92:95], v[34:37], v[0:15]
	v_mul_f32_e32 v33, v42, v32
	v_mul_f32_e32 v42, v43, v33
	v_mul_f32_e32 v43, v145, v42
	v_mul_f32_e32 v47, v149, v47
	v_mul_f32_e32 v40, v44, v45
	v_mul_f32_e32 v44, v147, v32
	v_mul_f32_e32 v33, v146, v33
	v_mfma_f32_32x32x16_bf16 v[16:31], v[88:91], v[34:37], v[16:31]
	v_mul_f32_e32 v32, v41, v42
	v_mul_f32_e32 v34, v144, v43
	v_cvt_pk_bf16_f32 v32, v34, v32
	v_cvt_pk_bf16_f32 v33, v33, v44
	v_cvt_pk_bf16_f32 v34, v40, v46
	v_cvt_pk_bf16_f32 v35, v47, v135
	v_mul_f32_e32 v36, v39, v130
	v_mul_f32_e32 v36, v38, v36
	v_mfma_f32_32x32x16_bf16 v[0:15], v[84:87], v[32:35], v[0:15]
	v_log_f32_e32 v36, v36
	s_nop 0
	v_add_f32_e32 v126, v126, v36
	v_mfma_f32_32x32x16_bf16 v[16:31], v[80:83], v[32:35], v[16:31]
; __device__ __forceinline__ void sb_unit(const Frame& F, int b, int hd, int qi, int dry) {
;     ...
;             float run = C;
;             if (!meta && key0 + 96 < tqw + 31) SB_HALF(96);
;             if (!meta && key0 + 64 < tqw + 31 && __any(run >= SB_DEAD)) SB_HALF(64);
;             if (!meta && key0 + 32 < tqw + 31 && __any(run >= SB_DEAD)) SB_HALF(32);
.LBB0_367:
	s_or_b32 s0, s34, 1
	s_cmp_ge_i32 s0, s25
	s_cselect_b64 s[0:1], -1, 0
	s_or_b64 s[0:1], s[18:19], s[0:1]
	s_and_b64 vcc, exec, s[0:1]
	s_cbranch_vccnz .LBB0_370
	v_cmp_le_f32_e32 vcc, s22, v126
	s_cbranch_vccz .LBB0_370
	s_add_i32 s61, s34, 64
	s_cmp_le_i32 s61, s25
	s_cbranch_scc1 .Lsbq_nomask_1
	ds_read_b128 v[32:35], v129 offset:4608
	ds_read_b128 v[214:217], v129 offset:4640
	ds_read_b128 v[210:213], v129 offset:4672
	ds_read_b128 v[130:133], v129 offset:4704
	ds_read_b64_tr_b16 v[92:93], v128 offset:43008
	ds_read_b64_tr_b16 v[94:95], v128 offset:44544
	ds_read_b64_tr_b16 v[90:91], v128 offset:44608
	ds_read_b64_tr_b16 v[88:89], v128 offset:43072
	ds_read_b64_tr_b16 v[84:85], v128 offset:46080
	ds_read_b64_tr_b16 v[86:87], v128 offset:47616
	ds_read_b64_tr_b16 v[82:83], v128 offset:47680
	ds_read_b64_tr_b16 v[80:81], v128 offset:46144
	v_exp_f32_e32 v135, v126
	v_sub_u32_e32 v134, v125, v127
	v_cmp_lt_i32_e32 vcc, 0, v134
	s_waitcnt lgkmcnt(11)
	v_mfma_f32_32x32x16_bf16 v[32:47], v[32:35], v[48:51], 0
	v_cmp_lt_i32_e64 s[0:1], 27, v134
	s_waitcnt lgkmcnt(10)
	v_mfma_f32_32x32x16_bf16 v[32:47], v[214:217], v[52:55], v[32:47]
	s_waitcnt lgkmcnt(9)
	v_mfma_f32_32x32x16_bf16 v[32:47], v[210:213], v[56:59], v[32:47]
	s_waitcnt lgkmcnt(8)
	v_mfma_f32_32x32x16_bf16 v[32:47], v[130:133], v[60:63], v[32:47]
	s_nop 11
	v_min_f32_e64 v32, -v32, s60
	v_min_f32_e64 v33, -v33, s60
	v_exp_f32_e32 v32, v32
	v_min_f32_e64 v34, -v34, s60
	v_exp_f32_e32 v33, v33
	v_exp_f32_e32 v34, v34
	v_min_f32_e64 v35, -v35, s60
	v_exp_f32_e32 v130, v35
	v_add_f32_e32 v35, 1.0, v32
	v_add_f32_e32 v131, 1.0, v33
	v_rcp_f32_e32 v35, v35
	v_add_f32_e32 v132, 1.0, v34
	v_rcp_f32_e32 v131, v131
	v_min_f32_e64 v36, -v36, s60
	v_rcp_f32_e32 v132, v132
	v_exp_f32_e32 v36, v36
	v_add_f32_e32 v133, 1.0, v130
	v_rcp_f32_e32 v136, v133
	v_mul_f32_e32 v32, v32, v35
	v_mul_f32_e32 v133, v135, v35
	v_mul_f32_e32 v33, v33, v131
	v_mul_f32_e32 v137, v135, v131
	v_cndmask_b32_e32 v35, 1.0, v32, vcc
	v_cndmask_b32_e32 v138, 0, v133, vcc
	v_cmp_lt_i32_e32 vcc, 1, v134
	v_mul_f32_e32 v34, v34, v132
	v_mul_f32_e32 v32, v135, v132
	v_cndmask_b32_e32 v131, 1.0, v33, vcc
	v_cndmask_b32_e32 v137, 0, v137, vcc
	v_cmp_lt_i32_e32 vcc, 2, v134
	v_min_f32_e64 v39, -v39, s60
	v_cndmask_b32_e32 v33, 1.0, v34, vcc
	v_add_f32_e32 v34, 1.0, v36
	v_rcp_f32_e32 v34, v34
	v_cndmask_b32_e32 v139, 0, v32, vcc
	v_mul_f32_e32 v32, v130, v136
	v_cmp_lt_i32_e32 vcc, 3, v134
	v_exp_f32_e32 v39, v39
	v_cndmask_b32_e32 v133, 1.0, v32, vcc
	v_mul_f32_e32 v32, v135, v136
	v_cndmask_b32_e32 v136, 0, v32, vcc
	v_mul_f32_e32 v32, v36, v34
	v_min_f32_e64 v36, -v37, s60
	v_exp_f32_e32 v36, v36
	v_cmp_lt_i32_e32 vcc, 8, v134
	v_mul_f32_e32 v34, v135, v34
	v_cndmask_b32_e32 v140, 0, v34, vcc
	v_add_f32_e32 v34, 1.0, v36
	v_rcp_f32_e32 v34, v34
	v_min_f32_e64 v37, -v38, s60
	v_exp_f32_e32 v37, v37
	v_cndmask_b32_e32 v32, 1.0, v32, vcc
	v_mul_f32_e32 v36, v36, v34
	v_cmp_lt_i32_e32 vcc, 9, v134
	v_mul_f32_e32 v34, v135, v34
	v_min_f32_e64 v42, -v42, s60
	v_cndmask_b32_e32 v38, 1.0, v36, vcc
	v_add_f32_e32 v36, 1.0, v37
	v_rcp_f32_e32 v36, v36
	v_cndmask_b32_e32 v141, 0, v34, vcc
	v_cmp_lt_i32_e32 vcc, 10, v134
	v_exp_f32_e32 v42, v42
	v_mul_f32_e32 v34, v37, v36
	v_add_f32_e32 v37, 1.0, v39
	v_rcp_f32_e32 v37, v37
	v_cndmask_b32_e32 v142, 1.0, v34, vcc
	v_mul_f32_e32 v34, v135, v36
	v_cndmask_b32_e32 v143, 0, v34, vcc
	v_mul_f32_e32 v34, v39, v37
	v_cmp_lt_i32_e32 vcc, 11, v134
	v_min_f32_e64 v36, -v40, s60
	v_exp_f32_e32 v36, v36
	v_cndmask_b32_e32 v39, 1.0, v34, vcc
	v_mul_f32_e32 v34, v135, v37
	v_min_f32_e64 v37, -v41, s60
	v_exp_f32_e32 v37, v37
	v_cndmask_b32_e32 v40, 0, v34, vcc
	v_add_f32_e32 v34, 1.0, v36
	v_rcp_f32_e32 v34, v34
	v_add_f32_e32 v41, 1.0, v37
	v_rcp_f32_e32 v41, v41
	v_cmp_lt_i32_e32 vcc, 16, v134
	v_mul_f32_e32 v36, v36, v34
	v_mul_f32_e32 v34, v135, v34
	v_cndmask_b32_e32 v144, 0, v34, vcc
	v_mul_f32_e32 v34, v37, v41
	v_add_f32_e32 v37, 1.0, v42
	v_rcp_f32_e32 v37, v37
	v_cndmask_b32_e32 v36, 1.0, v36, vcc
	v_cmp_lt_i32_e32 vcc, 17, v134
	v_min_f32_e64 v45, -v45, s60
	v_cndmask_b32_e32 v145, 1.0, v34, vcc
	v_mul_f32_e32 v34, v135, v41
	v_cndmask_b32_e32 v41, 0, v34, vcc
	v_mul_f32_e32 v34, v42, v37
	v_cmp_lt_i32_e32 vcc, 18, v134
	v_min_f32_e64 v42, -v43, s60
	v_exp_f32_e32 v42, v42
	v_cndmask_b32_e32 v43, 1.0, v34, vcc
	v_mul_f32_e32 v34, v135, v37
	v_min_f32_e64 v37, -v44, s60
	v_exp_f32_e32 v37, v37
	v_cndmask_b32_e32 v146, 0, v34, vcc
	v_add_f32_e32 v34, 1.0, v42
	v_rcp_f32_e32 v34, v34
	v_add_f32_e32 v44, 1.0, v37
	v_rcp_f32_e32 v44, v44
	v_exp_f32_e32 v45, v45
	v_min_f32_e64 v46, -v46, s60
	v_min_f32_e64 v47, -v47, s60
	v_exp_f32_e32 v46, v46
	v_exp_f32_e32 v47, v47
	v_mul_f32_e32 v42, v42, v34
	v_cmp_lt_i32_e32 vcc, 19, v134
	v_mul_f32_e32 v34, v135, v34
	v_add_f32_e32 v130, 1.0, v46
	v_cndmask_b32_e32 v147, 0, v34, vcc
	v_mul_f32_e32 v34, v37, v44
	v_add_f32_e32 v37, 1.0, v45
	v_rcp_f32_e32 v37, v37
	v_add_f32_e32 v132, 1.0, v47
	v_rcp_f32_e32 v130, v130
	v_rcp_f32_e32 v132, v132
	v_cndmask_b32_e32 v42, 1.0, v42, vcc
	v_cmp_lt_i32_e32 vcc, 24, v134
	v_mul_f32_e32 v44, v135, v44
	v_mul_f32_e32 v45, v45, v37
	v_cndmask_b32_e32 v34, 1.0, v34, vcc
	v_cndmask_b32_e32 v44, 0, v44, vcc
	v_cmp_lt_i32_e32 vcc, 25, v134
	v_mul_f32_e32 v37, v135, v37
	v_mul_f32_e32 v46, v46, v130
	v_cndmask_b32_e32 v45, 1.0, v45, vcc
	v_cndmask_b32_e32 v37, 0, v37, vcc
	v_cmp_lt_i32_e32 vcc, 26, v134
	v_mul_f32_e32 v47, v47, v132
	v_cndmask_b32_e64 v47, 1.0, v47, s[0:1]
	v_cndmask_b32_e32 v46, 1.0, v46, vcc
	v_mul_f32_e32 v34, v34, v45
	v_mul_f32_e32 v134, v46, v47
	v_mul_f32_e32 v134, v34, v134
	v_mov_b32_e32 v148, v134
	s_nop 1
	v_permlane32_swap_b32_e32 v134, v148
	v_mul_f32_e32 v34, v135, v130
	v_cndmask_b32_e32 v149, 0, v34, vcc
	v_mul_f32_e32 v34, v135, v132
	v_cndmask_b32_e64 v34, 0, v34, s[0:1]
	s_waitcnt lgkmcnt(0)
	v_cndmask_b32_e64 v130, 1.0, v148, s[2:3]
	v_mul_f32_e32 v135, v34, v130
	v_mul_f32_e32 v34, v36, v145
	v_mul_f32_e32 v36, v43, v42
	v_mul_f32_e32 v36, v34, v36
	v_mul_f32_e32 v32, v32, v38
	v_mul_f32_e32 v34, v142, v39
	v_mov_b32_e32 v150, v36
	s_nop 1
	v_permlane32_swap_b32_e32 v36, v150
	v_mul_f32_e32 v34, v32, v34
	v_mul_f32_e32 v47, v47, v130
	v_mov_b32_e32 v130, v34
	s_nop 1
	v_permlane32_swap_b32_e32 v34, v130
	v_mul_f32_e32 v46, v46, v47
	v_mul_f32_e32 v32, v134, v148
	s_waitcnt lgkmcnt(1)
	v_mul_f32_e32 v132, v36, v150
	v_mul_f32_e32 v45, v45, v46
	v_mul_f32_e32 v46, v37, v46
	s_waitcnt lgkmcnt(0)
	v_cndmask_b32_e64 v134, 1.0, v130, s[2:3]
	v_pk_mul_f32 v[36:37], v[32:33], v[132:133]
	v_pk_mul_f32 v[34:35], v[34:35], v[130:131]
	v_mul_f32_e32 v132, v36, v134
	v_mul_f32_e32 v134, v39, v132
	v_mul_f32_e32 v142, v142, v134
	v_mul_f32_e32 v148, v38, v142
	v_pk_mul_f32 v[38:39], v[34:35], v[36:37]
	v_mov_b32_e32 v130, v39
	s_nop 1
	v_permlane32_swap_b32_e32 v39, v130
	v_mul_f32_e32 v37, v40, v132
	v_mul_f32_e32 v40, v143, v134
	v_mul_f32_e32 v36, v141, v142
	v_mul_f32_e32 v132, v140, v148
	s_waitcnt lgkmcnt(0)
	v_cndmask_b32_e64 v34, 1.0, v130, s[2:3]
	v_mul_f32_e32 v34, v38, v34
	v_mul_f32_e32 v35, v133, v34
	v_mul_f32_e32 v33, v33, v35
	v_mul_f32_e32 v131, v131, v33
	v_mul_f32_e32 v133, v136, v34
	v_mul_f32_e32 v35, v139, v35
	v_mul_f32_e32 v33, v137, v33
	v_mul_f32_e32 v34, v138, v131
	v_cvt_pk_bf16_f32 v34, v34, v33
	v_cvt_pk_bf16_f32 v35, v35, v133
	v_cvt_pk_bf16_f32 v36, v132, v36
	v_cvt_pk_bf16_f32 v37, v40, v37
	v_cndmask_b32_e64 v33, 1.0, v150, s[2:3]
	v_mul_f32_e32 v32, v32, v33
	v_mfma_f32_32x32x16_bf16 v[0:15], v[92:95], v[34:37], v[0:15]
	v_mul_f32_e32 v33, v42, v32
	v_mul_f32_e32 v42, v43, v33
	v_mul_f32_e32 v43, v145, v42
	v_mul_f32_e32 v47, v149, v47
	v_mul_f32_e32 v40, v44, v45
	v_mul_f32_e32 v44, v147, v32
	v_mul_f32_e32 v33, v146, v33
	v_mfma_f32_32x32x16_bf16 v[16:31], v[88:91], v[34:37], v[16:31]
	v_mul_f32_e32 v32, v41, v42
	v_mul_f32_e32 v34, v144, v43
	v_cvt_pk_bf16_f32 v32, v34, v32
	v_cvt_pk_bf16_f32 v33, v33, v44
	v_cvt_pk_bf16_f32 v34, v40, v46
	v_cvt_pk_bf16_f32 v35, v47, v135
	v_mul_f32_e32 v36, v39, v130
	v_mul_f32_e32 v36, v38, v36
	v_mfma_f32_32x32x16_bf16 v[0:15], v[84:87], v[32:35], v[0:15]
	v_log_f32_e32 v36, v36
	s_nop 0
	v_add_f32_e32 v126, v126, v36
	v_mfma_f32_32x32x16_bf16 v[16:31], v[80:83], v[32:35], v[16:31]
	s_branch .LBB0_370
.Lsbq_nomask_1:
	ds_read_b128 v[32:35], v129 offset:4608
	ds_read_b128 v[214:217], v129 offset:4640
	ds_read_b128 v[210:213], v129 offset:4672
	ds_read_b128 v[130:133], v129 offset:4704
	ds_read_b64_tr_b16 v[92:93], v128 offset:43008
	ds_read_b64_tr_b16 v[94:95], v128 offset:44544
	ds_read_b64_tr_b16 v[90:91], v128 offset:44608
	ds_read_b64_tr_b16 v[88:89], v128 offset:43072
	ds_read_b64_tr_b16 v[84:85], v128 offset:46080
	ds_read_b64_tr_b16 v[86:87], v128 offset:47616
	ds_read_b64_tr_b16 v[82:83], v128 offset:47680
	ds_read_b64_tr_b16 v[80:81], v128 offset:46144
	v_exp_f32_e32 v135, v126
	s_waitcnt lgkmcnt(11)
	v_mfma_f32_32x32x16_bf16 v[32:47], v[32:35], v[48:51], 0
	s_waitcnt lgkmcnt(10)
	v_mfma_f32_32x32x16_bf16 v[32:47], v[214:217], v[52:55], v[32:47]
	s_waitcnt lgkmcnt(9)
	v_mfma_f32_32x32x16_bf16 v[32:47], v[210:213], v[56:59], v[32:47]
	s_waitcnt lgkmcnt(8)
	v_mfma_f32_32x32x16_bf16 v[32:47], v[130:133], v[60:63], v[32:47]
	s_nop 11
	v_min_f32_e64 v32, -v32, s60
	v_min_f32_e64 v33, -v33, s60
	v_exp_f32_e32 v32, v32
	v_min_f32_e64 v34, -v34, s60
	v_exp_f32_e32 v33, v33
	v_exp_f32_e32 v34, v34
	v_min_f32_e64 v35, -v35, s60
	v_exp_f32_e32 v130, v35
	v_add_f32_e32 v35, 1.0, v32
	v_add_f32_e32 v131, 1.0, v33
	v_rcp_f32_e32 v35, v35
	v_add_f32_e32 v132, 1.0, v34
	v_rcp_f32_e32 v131, v131
	v_min_f32_e64 v36, -v36, s60
	v_rcp_f32_e32 v132, v132
	v_exp_f32_e32 v36, v36
	v_add_f32_e32 v133, 1.0, v130
	v_rcp_f32_e32 v136, v133
	v_mul_f32_e32 v32, v32, v35
	v_mul_f32_e32 v138, v135, v35
	v_mul_f32_e32 v33, v33, v131
	v_mul_f32_e32 v137, v135, v131
	v_mov_b32_e32 v35, v32
	v_mul_f32_e32 v34, v34, v132
	v_mul_f32_e32 v139, v135, v132
	v_mov_b32_e32 v131, v33
	v_min_f32_e64 v39, -v39, s60
	v_mov_b32_e32 v33, v34
	v_add_f32_e32 v34, 1.0, v36
	v_rcp_f32_e32 v34, v34
	v_mul_f32_e32 v133, v130, v136
	v_exp_f32_e32 v39, v39
	v_mul_f32_e32 v136, v135, v136
	v_mul_f32_e32 v32, v36, v34
	v_min_f32_e64 v36, -v37, s60
	v_exp_f32_e32 v36, v36
	v_mul_f32_e32 v140, v135, v34
	v_add_f32_e32 v34, 1.0, v36
	v_rcp_f32_e32 v34, v34
	v_min_f32_e64 v37, -v38, s60
	v_exp_f32_e32 v37, v37
	v_mul_f32_e32 v38, v36, v34
	v_mul_f32_e32 v141, v135, v34
	v_min_f32_e64 v42, -v42, s60
	v_add_f32_e32 v36, 1.0, v37
	v_rcp_f32_e32 v36, v36
	v_exp_f32_e32 v42, v42
	v_mul_f32_e32 v142, v37, v36
	v_add_f32_e32 v37, 1.0, v39
	v_rcp_f32_e32 v37, v37
	v_mul_f32_e32 v143, v135, v36
	v_mul_f32_e32 v39, v39, v37
	v_min_f32_e64 v36, -v40, s60
	v_exp_f32_e32 v36, v36
	v_mul_f32_e32 v40, v135, v37
	v_min_f32_e64 v37, -v41, s60
	v_exp_f32_e32 v37, v37
	v_add_f32_e32 v34, 1.0, v36
	v_rcp_f32_e32 v34, v34
	v_add_f32_e32 v41, 1.0, v37
	v_rcp_f32_e32 v41, v41
	v_mul_f32_e32 v36, v36, v34
	v_mul_f32_e32 v144, v135, v34
	v_mul_f32_e32 v145, v37, v41
	v_add_f32_e32 v37, 1.0, v42
	v_rcp_f32_e32 v37, v37
	v_min_f32_e64 v45, -v45, s60
	v_mul_f32_e32 v41, v135, v41
	v_mul_f32_e32 v34, v42, v37
	v_min_f32_e64 v42, -v43, s60
	v_exp_f32_e32 v42, v42
	v_mov_b32_e32 v43, v34
	v_mul_f32_e32 v146, v135, v37
	v_min_f32_e64 v37, -v44, s60
	v_exp_f32_e32 v37, v37
	v_add_f32_e32 v34, 1.0, v42
	v_rcp_f32_e32 v34, v34
	v_add_f32_e32 v44, 1.0, v37
	v_rcp_f32_e32 v44, v44
	v_exp_f32_e32 v45, v45
	v_min_f32_e64 v46, -v46, s60
	v_min_f32_e64 v47, -v47, s60
	v_exp_f32_e32 v46, v46
	v_exp_f32_e32 v47, v47
	v_mul_f32_e32 v42, v42, v34
	v_mul_f32_e32 v147, v135, v34
	v_add_f32_e32 v130, 1.0, v46
	v_mul_f32_e32 v34, v37, v44
	v_add_f32_e32 v37, 1.0, v45
	v_rcp_f32_e32 v37, v37
	v_add_f32_e32 v132, 1.0, v47
	v_rcp_f32_e32 v130, v130
	v_rcp_f32_e32 v132, v132
	v_mul_f32_e32 v44, v135, v44
	v_mul_f32_e32 v45, v45, v37
	v_mul_f32_e32 v37, v135, v37
	v_mul_f32_e32 v46, v46, v130
	v_mul_f32_e32 v47, v47, v132
	v_mul_f32_e32 v34, v34, v45
	v_mul_f32_e32 v134, v46, v47
	v_mul_f32_e32 v134, v34, v134
	v_mov_b32_e32 v148, v134
	s_nop 1
	v_permlane32_swap_b32_e32 v134, v148
	v_mul_f32_e32 v149, v135, v130
	v_mul_f32_e32 v34, v135, v132
	s_waitcnt lgkmcnt(0)
	v_cndmask_b32_e64 v130, 1.0, v148, s[2:3]
	v_mul_f32_e32 v135, v34, v130
	v_mul_f32_e32 v34, v36, v145
	v_mul_f32_e32 v36, v43, v42
	v_mul_f32_e32 v36, v34, v36
	v_mul_f32_e32 v32, v32, v38
	v_mul_f32_e32 v34, v142, v39
	v_mov_b32_e32 v150, v36
	s_nop 1
	v_permlane32_swap_b32_e32 v36, v150
	v_mul_f32_e32 v34, v32, v34
	v_mul_f32_e32 v47, v47, v130
	v_mov_b32_e32 v130, v34
	s_nop 1
	v_permlane32_swap_b32_e32 v34, v130
	v_mul_f32_e32 v46, v46, v47
	v_mul_f32_e32 v32, v134, v148
	s_waitcnt lgkmcnt(1)
	v_mul_f32_e32 v132, v36, v150
	v_mul_f32_e32 v45, v45, v46
	v_mul_f32_e32 v46, v37, v46
	s_waitcnt lgkmcnt(0)
	v_cndmask_b32_e64 v134, 1.0, v130, s[2:3]
	v_pk_mul_f32 v[36:37], v[32:33], v[132:133]
	v_pk_mul_f32 v[34:35], v[34:35], v[130:131]
	v_mul_f32_e32 v132, v36, v134
	v_mul_f32_e32 v134, v39, v132
	v_mul_f32_e32 v142, v142, v134
	v_mul_f32_e32 v148, v38, v142
	v_pk_mul_f32 v[38:39], v[34:35], v[36:37]
	v_mov_b32_e32 v130, v39
	s_nop 1
	v_permlane32_swap_b32_e32 v39, v130
	v_mul_f32_e32 v37, v40, v132
	v_mul_f32_e32 v40, v143, v134
	v_mul_f32_e32 v36, v141, v142
	v_mul_f32_e32 v132, v140, v148
	s_waitcnt lgkmcnt(0)
	v_cndmask_b32_e64 v34, 1.0, v130, s[2:3]
	v_mul_f32_e32 v34, v38, v34
	v_mul_f32_e32 v35, v133, v34
	v_mul_f32_e32 v33, v33, v35
	v_mul_f32_e32 v131, v131, v33
	v_mul_f32_e32 v133, v136, v34
	v_mul_f32_e32 v35, v139, v35
	v_mul_f32_e32 v33, v137, v33
	v_mul_f32_e32 v34, v138, v131
	v_cvt_pk_bf16_f32 v34, v34, v33
	v_cvt_pk_bf16_f32 v35, v35, v133
	v_cvt_pk_bf16_f32 v36, v132, v36
	v_cvt_pk_bf16_f32 v37, v40, v37
	v_cndmask_b32_e64 v33, 1.0, v150, s[2:3]
	v_mul_f32_e32 v32, v32, v33
	v_mfma_f32_32x32x16_bf16 v[0:15], v[92:95], v[34:37], v[0:15]
	v_mul_f32_e32 v33, v42, v32
	v_mul_f32_e32 v42, v43, v33
	v_mul_f32_e32 v43, v145, v42
	v_mul_f32_e32 v47, v149, v47
	v_mul_f32_e32 v40, v44, v45
	v_mul_f32_e32 v44, v147, v32
	v_mul_f32_e32 v33, v146, v33
	v_mfma_f32_32x32x16_bf16 v[16:31], v[88:91], v[34:37], v[16:31]
	v_mul_f32_e32 v32, v41, v42
	v_mul_f32_e32 v34, v144, v43
	v_cvt_pk_bf16_f32 v32, v34, v32
	v_cvt_pk_bf16_f32 v33, v33, v44
	v_cvt_pk_bf16_f32 v34, v40, v46
	v_cvt_pk_bf16_f32 v35, v47, v135
	v_mul_f32_e32 v36, v39, v130
	v_mul_f32_e32 v36, v38, v36
	v_mfma_f32_32x32x16_bf16 v[0:15], v[84:87], v[32:35], v[0:15]
	v_log_f32_e32 v36, v36
	s_nop 0
	v_add_f32_e32 v126, v126, v36
	v_mfma_f32_32x32x16_bf16 v[16:31], v[80:83], v[32:35], v[16:31]

.Lsbq0_masked_1:
	ds_read_b128 v[32:35], v129
	ds_read_b128 v[214:217], v129 offset:32
	ds_read_b128 v[210:213], v129 offset:64
	ds_read_b128 v[130:133], v129 offset:96
	ds_read_b64_tr_b16 v[92:93], v128 offset:36864
	ds_read_b64_tr_b16 v[94:95], v128 offset:38400
	ds_read_b64_tr_b16 v[90:91], v128 offset:38464
	ds_read_b64_tr_b16 v[88:89], v128 offset:36928
	ds_read_b64_tr_b16 v[84:85], v128 offset:39936
	ds_read_b64_tr_b16 v[86:87], v128 offset:41472
	ds_read_b64_tr_b16 v[82:83], v128 offset:41536
	ds_read_b64_tr_b16 v[80:81], v128 offset:40000
	v_cndmask_b32_e64 v129, v114, 16, s[18:19]
	v_sub_u32_e32 v127, v129, v127
	v_cmp_lt_i32_e32 vcc, 0, v127
	v_cmp_lt_i32_e64 s[0:1], 27, v127
	v_exp_f32_e32 v128, v126
	s_waitcnt lgkmcnt(11)
	v_mfma_f32_32x32x16_bf16 v[32:47], v[32:35], v[48:51], 0
	s_waitcnt lgkmcnt(10)
	v_mfma_f32_32x32x16_bf16 v[32:47], v[214:217], v[52:55], v[32:47]
	s_waitcnt lgkmcnt(9)
	v_mfma_f32_32x32x16_bf16 v[32:47], v[210:213], v[56:59], v[32:47]
	s_waitcnt lgkmcnt(8)
	v_mfma_f32_32x32x16_bf16 v[32:47], v[130:133], v[60:63], v[32:47]
	s_nop 11
	v_min_f32_e64 v32, -v32, s60
	v_min_f32_e64 v33, -v33, s60
	v_exp_f32_e32 v32, v32
	v_min_f32_e64 v34, -v34, s60
	v_exp_f32_e32 v33, v33
	v_exp_f32_e32 v34, v34
	v_min_f32_e64 v35, -v35, s60
	v_exp_f32_e32 v130, v35
	v_add_f32_e32 v35, 1.0, v32
	v_add_f32_e32 v129, 1.0, v33
	v_rcp_f32_e32 v35, v35
	v_add_f32_e32 v131, 1.0, v34
	v_rcp_f32_e32 v129, v129
	v_rcp_f32_e32 v131, v131
	v_add_f32_e32 v132, 1.0, v130
	v_rcp_f32_e32 v132, v132
	v_mul_f32_e32 v32, v32, v35
	v_mul_f32_e32 v133, v128, v35
	v_min_f32_e64 v36, -v36, s60
	v_mul_f32_e32 v33, v33, v129
	v_mul_f32_e32 v134, v128, v129
	v_cndmask_b32_e32 v35, 1.0, v32, vcc
	v_cndmask_b32_e32 v133, 0, v133, vcc
	v_cmp_lt_i32_e32 vcc, 1, v127
	v_mul_f32_e32 v34, v34, v131
	v_exp_f32_e32 v32, v36
	v_cndmask_b32_e32 v129, 1.0, v33, vcc
	v_cndmask_b32_e32 v134, 0, v134, vcc
	v_cmp_lt_i32_e32 vcc, 2, v127
	v_add_f32_e32 v36, 1.0, v32
	v_rcp_f32_e32 v36, v36
	v_cndmask_b32_e32 v33, 1.0, v34, vcc
	v_mul_f32_e32 v34, v128, v131
	v_cndmask_b32_e32 v135, 0, v34, vcc
	v_mul_f32_e32 v34, v130, v132
	v_cmp_lt_i32_e32 vcc, 3, v127
	v_mul_f32_e32 v32, v32, v36
	v_mul_f32_e32 v36, v128, v36
	v_cndmask_b32_e32 v131, 1.0, v34, vcc
	v_mul_f32_e32 v34, v128, v132
	v_cndmask_b32_e32 v132, 0, v34, vcc
	v_min_f32_e64 v34, -v37, s60
	v_exp_f32_e32 v34, v34
	v_cmp_lt_i32_e32 vcc, 8, v127
	v_min_f32_e64 v37, -v38, s60
	v_cndmask_b32_e32 v136, 0, v36, vcc
	v_add_f32_e32 v36, 1.0, v34
	v_rcp_f32_e32 v36, v36
	v_exp_f32_e32 v37, v37
	v_cndmask_b32_e32 v32, 1.0, v32, vcc
	v_cmp_lt_i32_e32 vcc, 9, v127
	v_mul_f32_e32 v34, v34, v36
	v_cndmask_b32_e32 v38, 1.0, v34, vcc
	v_add_f32_e32 v34, 1.0, v37
	v_min_f32_e64 v39, -v39, s60
	v_rcp_f32_e32 v34, v34
	v_exp_f32_e32 v39, v39
	v_mul_f32_e32 v36, v128, v36
	v_cndmask_b32_e32 v137, 0, v36, vcc
	v_mul_f32_e32 v36, v37, v34
	v_add_f32_e32 v37, 1.0, v39
	v_rcp_f32_e32 v37, v37
	v_cmp_lt_i32_e32 vcc, 10, v127
	v_mul_f32_e32 v34, v128, v34
	v_cndmask_b32_e32 v138, 1.0, v36, vcc
	v_cndmask_b32_e32 v139, 0, v34, vcc
	v_mul_f32_e32 v34, v39, v37
	v_cmp_lt_i32_e32 vcc, 11, v127
	v_min_f32_e64 v36, -v40, s60
	v_exp_f32_e32 v36, v36
	v_cndmask_b32_e32 v39, 1.0, v34, vcc
	v_mul_f32_e32 v34, v128, v37
	v_min_f32_e64 v37, -v41, s60
	v_exp_f32_e32 v37, v37
	v_cndmask_b32_e32 v40, 0, v34, vcc
	v_add_f32_e32 v34, 1.0, v36
	v_rcp_f32_e32 v34, v34
	v_add_f32_e32 v41, 1.0, v37
	v_min_f32_e64 v42, -v42, s60
	v_rcp_f32_e32 v41, v41
	v_exp_f32_e32 v42, v42
	v_mul_f32_e32 v36, v36, v34
	v_cmp_lt_i32_e32 vcc, 16, v127
	v_mul_f32_e32 v34, v128, v34
	v_cndmask_b32_e32 v140, 0, v34, vcc
	v_mul_f32_e32 v34, v37, v41
	v_add_f32_e32 v37, 1.0, v42
	v_rcp_f32_e32 v37, v37
	v_cndmask_b32_e32 v36, 1.0, v36, vcc
	v_cmp_lt_i32_e32 vcc, 17, v127
	v_min_f32_e64 v45, -v45, s60
	v_cndmask_b32_e32 v141, 1.0, v34, vcc
	v_mul_f32_e32 v34, v128, v41
	v_cndmask_b32_e32 v41, 0, v34, vcc
	v_mul_f32_e32 v34, v42, v37
	v_cmp_lt_i32_e32 vcc, 18, v127
	v_min_f32_e64 v42, -v43, s60
	v_exp_f32_e32 v42, v42
	v_cndmask_b32_e32 v43, 1.0, v34, vcc
	v_mul_f32_e32 v34, v128, v37
	v_min_f32_e64 v37, -v44, s60
	v_exp_f32_e32 v37, v37
	v_cndmask_b32_e32 v142, 0, v34, vcc
	v_add_f32_e32 v34, 1.0, v42
	v_rcp_f32_e32 v34, v34
	v_add_f32_e32 v44, 1.0, v37
	v_rcp_f32_e32 v44, v44
	v_exp_f32_e32 v45, v45
	v_min_f32_e64 v46, -v46, s60
	v_min_f32_e64 v47, -v47, s60
	v_exp_f32_e32 v46, v46
	v_exp_f32_e32 v47, v47
	v_mul_f32_e32 v42, v42, v34
	v_cmp_lt_i32_e32 vcc, 19, v127
	v_mul_f32_e32 v34, v128, v34
	v_add_f32_e32 v130, 1.0, v46
	v_cndmask_b32_e32 v143, 0, v34, vcc
	v_mul_f32_e32 v34, v37, v44
	v_add_f32_e32 v37, 1.0, v45
	v_rcp_f32_e32 v37, v37
	v_add_f32_e32 v144, 1.0, v47
	v_rcp_f32_e32 v130, v130
	v_rcp_f32_e32 v144, v144
	v_cndmask_b32_e32 v42, 1.0, v42, vcc
	v_cmp_lt_i32_e32 vcc, 24, v127
	v_mul_f32_e32 v44, v128, v44
	v_mul_f32_e32 v45, v45, v37
	v_cndmask_b32_e32 v34, 1.0, v34, vcc
	v_cndmask_b32_e32 v44, 0, v44, vcc
	v_cmp_lt_i32_e32 vcc, 25, v127
	v_mul_f32_e32 v37, v128, v37
	v_mul_f32_e32 v46, v46, v130
	v_cndmask_b32_e32 v45, 1.0, v45, vcc
	v_cndmask_b32_e32 v37, 0, v37, vcc
	v_cmp_lt_i32_e32 vcc, 26, v127
	v_mul_f32_e32 v47, v47, v144
	v_cndmask_b32_e64 v47, 1.0, v47, s[0:1]
	v_cndmask_b32_e32 v46, 1.0, v46, vcc
	v_mul_f32_e32 v34, v34, v45
	v_mul_f32_e32 v127, v46, v47
	v_mul_f32_e32 v127, v34, v127
	v_mov_b32_e32 v145, v127
	s_nop 1
	v_permlane32_swap_b32_e32 v127, v145
	v_mul_f32_e32 v34, v128, v130
	v_cndmask_b32_e32 v130, 0, v34, vcc
	v_mul_f32_e32 v34, v128, v144
	v_cndmask_b32_e64 v34, 0, v34, s[0:1]
	s_waitcnt lgkmcnt(0)
	v_cndmask_b32_e64 v128, 1.0, v145, s[2:3]
	v_mul_f32_e32 v144, v34, v128
	v_mul_f32_e32 v34, v36, v141
	v_mul_f32_e32 v36, v43, v42
	v_mul_f32_e32 v36, v34, v36
	v_mul_f32_e32 v32, v32, v38
	v_mul_f32_e32 v34, v138, v39
	v_mov_b32_e32 v146, v36
	s_nop 1
	v_permlane32_swap_b32_e32 v36, v146
	v_mul_f32_e32 v34, v32, v34
	v_mul_f32_e32 v47, v47, v128
	v_mov_b32_e32 v128, v34
	s_nop 1
	v_permlane32_swap_b32_e32 v34, v128
	v_mul_f32_e32 v46, v46, v47
	v_mul_f32_e32 v47, v130, v47
	v_mul_f32_e32 v32, v127, v145
	s_waitcnt lgkmcnt(1)
	v_mul_f32_e32 v130, v36, v146
	v_mul_f32_e32 v45, v45, v46
	v_mul_f32_e32 v46, v37, v46
	s_waitcnt lgkmcnt(0)
	v_cndmask_b32_e64 v127, 1.0, v128, s[2:3]
	v_pk_mul_f32 v[36:37], v[32:33], v[130:131]
	v_pk_mul_f32 v[34:35], v[34:35], v[128:129]
	v_mul_f32_e32 v127, v36, v127
	v_mul_f32_e32 v130, v39, v127
	v_mul_f32_e32 v138, v138, v130
	v_mul_f32_e32 v145, v38, v138
	v_pk_mul_f32 v[38:39], v[34:35], v[36:37]
	v_mov_b32_e32 v128, v39
	s_nop 1
	v_permlane32_swap_b32_e32 v39, v128
	v_mul_f32_e32 v37, v40, v127
	v_mul_f32_e32 v40, v139, v130
	v_mul_f32_e32 v36, v137, v138
	v_mul_f32_e32 v127, v136, v145
	s_waitcnt lgkmcnt(0)
	v_cndmask_b32_e64 v34, 1.0, v128, s[2:3]
	v_mul_f32_e32 v34, v38, v34
	v_mul_f32_e32 v35, v131, v34
	v_mul_f32_e32 v33, v33, v35
	v_mul_f32_e32 v129, v129, v33
	v_mul_f32_e32 v130, v132, v34
	v_mul_f32_e32 v35, v135, v35
	v_mul_f32_e32 v33, v134, v33
	v_mul_f32_e32 v34, v133, v129
	v_cvt_pk_bf16_f32 v34, v34, v33
	v_cvt_pk_bf16_f32 v35, v35, v130
	v_cvt_pk_bf16_f32 v36, v127, v36
	v_cvt_pk_bf16_f32 v37, v40, v37
	v_cndmask_b32_e64 v33, 1.0, v146, s[2:3]
	v_mul_f32_e32 v32, v32, v33
	v_mfma_f32_32x32x16_bf16 v[0:15], v[92:95], v[34:37], v[0:15]
	v_mul_f32_e32 v33, v42, v32
	v_mul_f32_e32 v42, v43, v33
	v_mul_f32_e32 v43, v141, v42
	v_mul_f32_e32 v40, v44, v45
	v_mul_f32_e32 v44, v143, v32
	v_mul_f32_e32 v33, v142, v33
	v_mul_f32_e32 v32, v41, v42
	v_mfma_f32_32x32x16_bf16 v[16:31], v[88:91], v[34:37], v[16:31]
	v_mul_f32_e32 v34, v140, v43
	v_cvt_pk_bf16_f32 v32, v34, v32
	v_cvt_pk_bf16_f32 v33, v33, v44
	v_cvt_pk_bf16_f32 v34, v40, v46
	v_cvt_pk_bf16_f32 v35, v47, v144
	v_mul_f32_e32 v36, v39, v128
	v_mul_f32_e32 v36, v38, v36
	v_mfma_f32_32x32x16_bf16 v[0:15], v[84:87], v[32:35], v[0:15]
	v_log_f32_e32 v36, v36
	s_nop 0
	v_add_f32_e32 v126, v126, v36
	v_mfma_f32_32x32x16_bf16 v[16:31], v[80:83], v[32:35], v[16:31]
	s_branch .LBB0_372
.Lsbq0_nomask_1:
	ds_read_b128 v[32:35], v129
	ds_read_b128 v[214:217], v129 offset:32
	ds_read_b128 v[210:213], v129 offset:64
	ds_read_b128 v[130:133], v129 offset:96
	ds_read_b64_tr_b16 v[92:93], v128 offset:36864
	ds_read_b64_tr_b16 v[94:95], v128 offset:38400
	ds_read_b64_tr_b16 v[90:91], v128 offset:38464
	ds_read_b64_tr_b16 v[88:89], v128 offset:36928
	ds_read_b64_tr_b16 v[84:85], v128 offset:39936
	ds_read_b64_tr_b16 v[86:87], v128 offset:41472
	ds_read_b64_tr_b16 v[82:83], v128 offset:41536
	ds_read_b64_tr_b16 v[80:81], v128 offset:40000
	v_exp_f32_e32 v128, v126
	s_waitcnt lgkmcnt(11)
	v_mfma_f32_32x32x16_bf16 v[32:47], v[32:35], v[48:51], 0
	s_waitcnt lgkmcnt(10)
	v_mfma_f32_32x32x16_bf16 v[32:47], v[214:217], v[52:55], v[32:47]
	s_waitcnt lgkmcnt(9)
	v_mfma_f32_32x32x16_bf16 v[32:47], v[210:213], v[56:59], v[32:47]
	s_waitcnt lgkmcnt(8)
	v_mfma_f32_32x32x16_bf16 v[32:47], v[130:133], v[60:63], v[32:47]
	s_nop 11
	v_min_f32_e64 v32, -v32, s60
	v_min_f32_e64 v33, -v33, s60
	v_exp_f32_e32 v32, v32
	v_min_f32_e64 v34, -v34, s60
	v_exp_f32_e32 v33, v33
	v_exp_f32_e32 v34, v34
	v_min_f32_e64 v35, -v35, s60
	v_exp_f32_e32 v130, v35
	v_add_f32_e32 v35, 1.0, v32
	v_add_f32_e32 v129, 1.0, v33
	v_rcp_f32_e32 v35, v35
	v_add_f32_e32 v131, 1.0, v34
	v_rcp_f32_e32 v129, v129
	v_rcp_f32_e32 v131, v131
	v_add_f32_e32 v132, 1.0, v130
	v_rcp_f32_e32 v132, v132
	v_mul_f32_e32 v32, v32, v35
	v_mul_f32_e32 v133, v128, v35
	v_min_f32_e64 v36, -v36, s60
	v_mul_f32_e32 v33, v33, v129
	v_mul_f32_e32 v134, v128, v129
	v_mov_b32_e32 v35, v32
	v_mul_f32_e32 v34, v34, v131
	v_exp_f32_e32 v32, v36
	v_mov_b32_e32 v129, v33
	v_add_f32_e32 v36, 1.0, v32
	v_rcp_f32_e32 v36, v36
	v_mov_b32_e32 v33, v34
	v_mul_f32_e32 v135, v128, v131
	v_mul_f32_e32 v131, v130, v132
	v_mul_f32_e32 v32, v32, v36
	v_mul_f32_e32 v136, v128, v36
	v_mul_f32_e32 v132, v128, v132
	v_min_f32_e64 v34, -v37, s60
	v_exp_f32_e32 v34, v34
	v_min_f32_e64 v37, -v38, s60
	v_add_f32_e32 v36, 1.0, v34
	v_rcp_f32_e32 v36, v36
	v_exp_f32_e32 v37, v37
	v_mul_f32_e32 v38, v34, v36
	v_add_f32_e32 v34, 1.0, v37
	v_min_f32_e64 v39, -v39, s60
	v_rcp_f32_e32 v34, v34
	v_exp_f32_e32 v39, v39
	v_mul_f32_e32 v137, v128, v36
	v_mul_f32_e32 v138, v37, v34
	v_add_f32_e32 v37, 1.0, v39
	v_rcp_f32_e32 v37, v37
	v_mul_f32_e32 v139, v128, v34
	v_mul_f32_e32 v39, v39, v37
	v_min_f32_e64 v36, -v40, s60
	v_exp_f32_e32 v36, v36
	v_mul_f32_e32 v40, v128, v37
	v_min_f32_e64 v37, -v41, s60
	v_exp_f32_e32 v37, v37
	v_add_f32_e32 v34, 1.0, v36
	v_rcp_f32_e32 v34, v34
	v_add_f32_e32 v41, 1.0, v37
	v_min_f32_e64 v42, -v42, s60
	v_rcp_f32_e32 v41, v41
	v_exp_f32_e32 v42, v42
	v_mul_f32_e32 v36, v36, v34
	v_mul_f32_e32 v140, v128, v34
	v_mul_f32_e32 v141, v37, v41
	v_add_f32_e32 v37, 1.0, v42
	v_rcp_f32_e32 v37, v37
	v_min_f32_e64 v45, -v45, s60
	v_mul_f32_e32 v41, v128, v41
	v_mul_f32_e32 v34, v42, v37
	v_min_f32_e64 v42, -v43, s60
	v_exp_f32_e32 v42, v42
	v_mov_b32_e32 v43, v34
	v_mul_f32_e32 v142, v128, v37
	v_min_f32_e64 v37, -v44, s60
	v_exp_f32_e32 v37, v37
	v_add_f32_e32 v34, 1.0, v42
	v_rcp_f32_e32 v34, v34
	v_add_f32_e32 v44, 1.0, v37
	v_rcp_f32_e32 v44, v44
	v_exp_f32_e32 v45, v45
	v_min_f32_e64 v46, -v46, s60
	v_min_f32_e64 v47, -v47, s60
	v_exp_f32_e32 v46, v46
	v_exp_f32_e32 v47, v47
	v_mul_f32_e32 v42, v42, v34
	v_mul_f32_e32 v143, v128, v34
	v_add_f32_e32 v130, 1.0, v46
	v_mul_f32_e32 v34, v37, v44
	v_add_f32_e32 v37, 1.0, v45
	v_rcp_f32_e32 v37, v37
	v_add_f32_e32 v144, 1.0, v47
	v_rcp_f32_e32 v130, v130
	v_rcp_f32_e32 v144, v144
	v_mul_f32_e32 v44, v128, v44
	v_mul_f32_e32 v45, v45, v37
	v_mul_f32_e32 v37, v128, v37
	v_mul_f32_e32 v46, v46, v130
	v_mul_f32_e32 v47, v47, v144
	v_mul_f32_e32 v34, v34, v45
	v_mul_f32_e32 v127, v46, v47
	v_mul_f32_e32 v127, v34, v127
	v_mov_b32_e32 v145, v127
	s_nop 1
	v_permlane32_swap_b32_e32 v127, v145
	v_mul_f32_e32 v130, v128, v130
	v_mul_f32_e32 v34, v128, v144
	s_waitcnt lgkmcnt(0)
	v_cndmask_b32_e64 v128, 1.0, v145, s[2:3]
	v_mul_f32_e32 v144, v34, v128
	v_mul_f32_e32 v34, v36, v141
	v_mul_f32_e32 v36, v43, v42
	v_mul_f32_e32 v36, v34, v36
	v_mul_f32_e32 v32, v32, v38
	v_mul_f32_e32 v34, v138, v39
	v_mov_b32_e32 v146, v36
	s_nop 1
	v_permlane32_swap_b32_e32 v36, v146
	v_mul_f32_e32 v34, v32, v34
	v_mul_f32_e32 v47, v47, v128
	v_mov_b32_e32 v128, v34
	s_nop 1
	v_permlane32_swap_b32_e32 v34, v128
	v_mul_f32_e32 v46, v46, v47
	v_mul_f32_e32 v47, v130, v47
	v_mul_f32_e32 v32, v127, v145
	s_waitcnt lgkmcnt(1)
	v_mul_f32_e32 v130, v36, v146
	v_mul_f32_e32 v45, v45, v46
	v_mul_f32_e32 v46, v37, v46
	s_waitcnt lgkmcnt(0)
	v_cndmask_b32_e64 v127, 1.0, v128, s[2:3]
	v_pk_mul_f32 v[36:37], v[32:33], v[130:131]
	v_pk_mul_f32 v[34:35], v[34:35], v[128:129]
	v_mul_f32_e32 v127, v36, v127
	v_mul_f32_e32 v130, v39, v127
	v_mul_f32_e32 v138, v138, v130
	v_mul_f32_e32 v145, v38, v138
	v_pk_mul_f32 v[38:39], v[34:35], v[36:37]
	v_mov_b32_e32 v128, v39
	s_nop 1
	v_permlane32_swap_b32_e32 v39, v128
	v_mul_f32_e32 v37, v40, v127
	v_mul_f32_e32 v40, v139, v130
	v_mul_f32_e32 v36, v137, v138
	v_mul_f32_e32 v127, v136, v145
	s_waitcnt lgkmcnt(0)
	v_cndmask_b32_e64 v34, 1.0, v128, s[2:3]
	v_mul_f32_e32 v34, v38, v34
	v_mul_f32_e32 v35, v131, v34
	v_mul_f32_e32 v33, v33, v35
	v_mul_f32_e32 v129, v129, v33
	v_mul_f32_e32 v130, v132, v34
	v_mul_f32_e32 v35, v135, v35
	v_mul_f32_e32 v33, v134, v33
	v_mul_f32_e32 v34, v133, v129
	v_cvt_pk_bf16_f32 v34, v34, v33
	v_cvt_pk_bf16_f32 v35, v35, v130
	v_cvt_pk_bf16_f32 v36, v127, v36
	v_cvt_pk_bf16_f32 v37, v40, v37
	v_cndmask_b32_e64 v33, 1.0, v146, s[2:3]
	v_mul_f32_e32 v32, v32, v33
	v_mfma_f32_32x32x16_bf16 v[0:15], v[92:95], v[34:37], v[0:15]
	v_mul_f32_e32 v33, v42, v32
	v_mul_f32_e32 v42, v43, v33
	v_mul_f32_e32 v43, v141, v42
	v_mul_f32_e32 v40, v44, v45
	v_mul_f32_e32 v44, v143, v32
	v_mul_f32_e32 v33, v142, v33
	v_mul_f32_e32 v32, v41, v42
	v_mfma_f32_32x32x16_bf16 v[16:31], v[88:91], v[34:37], v[16:31]
	v_mul_f32_e32 v34, v140, v43
	v_cvt_pk_bf16_f32 v32, v34, v32
	v_cvt_pk_bf16_f32 v33, v33, v44
	v_cvt_pk_bf16_f32 v34, v40, v46
	v_cvt_pk_bf16_f32 v35, v47, v144
	v_mul_f32_e32 v36, v39, v128
	v_mul_f32_e32 v36, v38, v36
	v_mfma_f32_32x32x16_bf16 v[0:15], v[84:87], v[32:35], v[0:15]
	v_log_f32_e32 v36, v36
	s_nop 0
	v_add_f32_e32 v126, v126, v36
	v_mfma_f32_32x32x16_bf16 v[16:31], v[80:83], v[32:35], v[16:31]
